# one static priority raise for waves 4-7 at kernel entry replaces the per-block s_setprio toggling in all K-loops (224 s_setprio removed)
# baseline (speedup 1.0000x reference)
_Z3fwd4Args:
	v_writelane_b32 v249, s0, 0
	v_writelane_b32 v249, s1, 1
	v_writelane_b32 v249, s2, 2
	v_mov_b32_e32 v250, v0
	v_readfirstlane_b32 s98, v0
	s_and_b32 s98, s98, 0x3ff
	s_cmp_ge_u32 s98, 0x100
	s_cbranch_scc0 .Lprio_skip
	s_setprio 1
.Lprio_skip:
	s_and_b32 s101, s2, 3
	s_cmp_lg_u32 s101, 0
	s_cselect_b32 s101, 0x100, 0

.LBB0_243:
	s_lshl_b32 s24, s12, 20
	s_and_b32 s24, s24, 0xff00000
	v_readlane_b32 s36, v248, 22
	v_readlane_b32 s37, v248, 23
	s_add_u32 s24, s36, s24
	s_addc_u32 s35, s37, 0
	s_lshr_b32 s36, s12, 13
	s_and_b32 s36, s36, 0x7ff80
	s_add_u32 s54, s24, s36
	s_addc_u32 s55, s35, 0
	s_lshl_b32 s24, s12, 12
	s_and_b32 s24, s24, 0xff00000
	v_readlane_b32 s38, v248, 24
	v_readlane_b32 s39, v248, 25
	s_add_u32 s24, s38, s24
	s_addc_u32 s35, s39, 0
	s_add_u32 s70, s24, s36
	s_addc_u32 s71, s35, 0
	s_cmp_lt_i32 s1, 1
	v_cmp_gt_i64_e64 s[72:73], s[12:13], -1
	s_cbranch_scc1 .LBB0_253
	s_and_b64 s[12:13], s[72:73], exec
	s_cselect_b32 s24, s55, s5
	s_cselect_b32 s35, s54, s4
	s_cselect_b32 s36, s71, s3
	s_cselect_b32 s37, s70, s2
	s_add_i32 s38, s1, -2
	s_add_u32 s4, s4, 0x80080
	s_addc_u32 s5, s5, 0
	s_add_u32 s39, s2, 0x100
	s_addc_u32 s40, s3, 0
	s_mov_b32 s2, 0
	v_add_u32_e32 v138, s29, v183
	ds_read_b128 v[144:147], v138
	ds_read_b128 v[148:151], v138 offset:1024
	ds_read_b128 v[152:155], v138 offset:2048
	ds_read_b128 v[156:159], v138 offset:3072
	v_add_u32_e32 v138, s34, v183
	ds_read_b128 v[160:163], v138
	ds_read_b128 v[164:167], v138 offset:1024
	ds_read_b128 v[186:189], v138 offset:2048
	ds_read_b128 v[190:193], v138 offset:3072
	s_add_i32 s41, s2, 2
	s_add_u32 s3, s4, 0xfff80080
	s_addc_u32 s12, s5, -1
	s_cmp_eq_u32 s38, s2
	s_cselect_b32 s2, s37, s39
	s_cselect_b32 s13, s24, s12
	s_cselect_b32 s12, s35, s3
	s_cselect_b32 s3, s36, s40
	s_add_i32 m0, s17, 0xc000
	ds_read_b128 v[194:197], v185
	ds_read_b128 v[198:201], v185 offset:1024
	ds_read_b128 v[202:205], v185 offset:2048
	ds_read_b128 v[208:211], v185 offset:3072
	ds_read_b128 v[212:215], v185 offset:4096
	ds_read_b128 v[216:219], v185 offset:5120
	ds_read_b128 v[220:223], v185 offset:6144
	ds_read_b128 v[224:227], v185 offset:7168
	global_load_lds_dwordx4 v140, s[4:5]
	s_add_i32 m0, s17, 0xe000
	s_nop 0
	global_load_lds_dwordx4 v142, s[4:5]
	s_waitcnt vmcnt(8)
	s_waitcnt lgkmcnt(0)
	s_barrier
	s_waitcnt lgkmcnt(0)
	v_mfma_i32_16x16x64_i8 v[126:129], v[144:147], v[194:197], 0
	v_mfma_i32_16x16x64_i8 v[126:129], v[148:151], v[198:201], v[126:129]
	v_mfma_i32_16x16x64_i8 v[122:125], v[152:155], v[194:197], 0
	v_mfma_i32_16x16x64_i8 v[122:125], v[156:159], v[198:201], v[122:125]
	v_mfma_i32_16x16x64_i8 v[118:121], v[144:147], v[202:205], 0
	v_mfma_i32_16x16x64_i8 v[118:121], v[148:151], v[208:211], v[118:121]
	v_mfma_i32_16x16x64_i8 v[114:117], v[152:155], v[202:205], 0
	v_mfma_i32_16x16x64_i8 v[114:117], v[156:159], v[208:211], v[114:117]
	v_mfma_i32_16x16x64_i8 v[110:113], v[144:147], v[212:215], 0
	v_mfma_i32_16x16x64_i8 v[110:113], v[148:151], v[216:219], v[110:113]
	v_mfma_i32_16x16x64_i8 v[106:109], v[152:155], v[212:215], 0
	v_mfma_i32_16x16x64_i8 v[106:109], v[156:159], v[216:219], v[106:109]
	v_mfma_i32_16x16x64_i8 v[102:105], v[144:147], v[220:223], 0
	v_mfma_i32_16x16x64_i8 v[102:105], v[148:151], v[224:227], v[102:105]
	v_mfma_i32_16x16x64_i8 v[98:101], v[152:155], v[220:223], 0
	v_mfma_i32_16x16x64_i8 v[98:101], v[156:159], v[224:227], v[98:101]
	v_mfma_i32_16x16x64_i8 v[94:97], v[160:163], v[194:197], 0
	v_mfma_i32_16x16x64_i8 v[94:97], v[164:167], v[198:201], v[94:97]
	v_mfma_i32_16x16x64_i8 v[90:93], v[186:189], v[194:197], 0
	v_mfma_i32_16x16x64_i8 v[90:93], v[190:193], v[198:201], v[90:93]
	v_mfma_i32_16x16x64_i8 v[86:89], v[160:163], v[202:205], 0
	v_mfma_i32_16x16x64_i8 v[86:89], v[164:167], v[208:211], v[86:89]
	v_mfma_i32_16x16x64_i8 v[82:85], v[186:189], v[202:205], 0
	v_mfma_i32_16x16x64_i8 v[82:85], v[190:193], v[208:211], v[82:85]
	v_mfma_i32_16x16x64_i8 v[78:81], v[160:163], v[212:215], 0
	v_mfma_i32_16x16x64_i8 v[78:81], v[164:167], v[216:219], v[78:81]
	v_mfma_i32_16x16x64_i8 v[74:77], v[186:189], v[212:215], 0
	v_mfma_i32_16x16x64_i8 v[74:77], v[190:193], v[216:219], v[74:77]
	v_mfma_i32_16x16x64_i8 v[70:73], v[160:163], v[220:223], 0
	v_mfma_i32_16x16x64_i8 v[70:73], v[164:167], v[224:227], v[70:73]
	v_mfma_i32_16x16x64_i8 v[66:69], v[186:189], v[220:223], 0
	v_mfma_i32_16x16x64_i8 v[66:69], v[190:193], v[224:227], v[66:69]
	s_barrier
	s_add_i32 s42, s29, s16
	s_mov_b32 m0, s42
	ds_read_b128 v[194:197], v185 offset:16384
	ds_read_b128 v[198:201], v185 offset:17408
	ds_read_b128 v[202:205], v185 offset:18432
	ds_read_b128 v[208:211], v185 offset:19456
	ds_read_b128 v[212:215], v185 offset:20480
	ds_read_b128 v[216:219], v185 offset:21504
	ds_read_b128 v[220:223], v185 offset:22528
	ds_read_b128 v[224:227], v185 offset:23552
	global_load_lds_dwordx4 v132, s[2:3]
	s_add_i32 m0, s42, 0x2000
	s_add_u32 s42, s2, 0x80000
	s_addc_u32 s43, s3, 0
	s_add_i32 s44, s34, s16
	global_load_lds_dwordx4 v136, s[2:3]
	s_mov_b32 m0, s44
	v_lshl_add_u64 v[234:235], s[12:13], 0, v[134:135]
	global_load_lds_dwordx4 v132, s[42:43]
	s_add_i32 m0, s44, 0x2000
	s_nop 0
	global_load_lds_dwordx4 v136, s[42:43]
	v_lshl_add_u64 v[232:233], s[12:13], 0, v[130:131]
	s_mov_b32 m0, s17
	s_nop 0
	global_load_lds_dwordx4 v130, s[12:13]
	s_mov_b32 m0, s18
	s_nop 0
	global_load_lds_dwordx4 v134, s[12:13]
	s_waitcnt vmcnt(8)
	s_waitcnt lgkmcnt(0)
	s_barrier
	s_waitcnt lgkmcnt(0)
	v_mfma_i32_16x16x64_i8 v[62:65], v[144:147], v[194:197], 0
	v_mfma_i32_16x16x64_i8 v[62:65], v[148:151], v[198:201], v[62:65]
	v_mfma_i32_16x16x64_i8 v[58:61], v[152:155], v[194:197], 0
	v_mfma_i32_16x16x64_i8 v[58:61], v[156:159], v[198:201], v[58:61]
	v_mfma_i32_16x16x64_i8 v[54:57], v[144:147], v[202:205], 0
	v_mfma_i32_16x16x64_i8 v[54:57], v[148:151], v[208:211], v[54:57]
	v_mfma_i32_16x16x64_i8 v[50:53], v[152:155], v[202:205], 0
	v_mfma_i32_16x16x64_i8 v[50:53], v[156:159], v[208:211], v[50:53]
	v_mfma_i32_16x16x64_i8 v[46:49], v[144:147], v[212:215], 0
	v_mfma_i32_16x16x64_i8 v[46:49], v[148:151], v[216:219], v[46:49]
	v_mfma_i32_16x16x64_i8 v[42:45], v[152:155], v[212:215], 0
	v_mfma_i32_16x16x64_i8 v[42:45], v[156:159], v[216:219], v[42:45]
	v_mfma_i32_16x16x64_i8 v[38:41], v[144:147], v[220:223], 0
	v_mfma_i32_16x16x64_i8 v[38:41], v[148:151], v[224:227], v[38:41]
	v_mfma_i32_16x16x64_i8 v[34:37], v[152:155], v[220:223], 0
	v_mfma_i32_16x16x64_i8 v[34:37], v[156:159], v[224:227], v[34:37]
	v_mfma_i32_16x16x64_i8 v[30:33], v[160:163], v[194:197], 0
	v_mfma_i32_16x16x64_i8 v[30:33], v[164:167], v[198:201], v[30:33]
	v_mfma_i32_16x16x64_i8 v[26:29], v[186:189], v[194:197], 0
	v_mfma_i32_16x16x64_i8 v[26:29], v[190:193], v[198:201], v[26:29]
	v_mfma_i32_16x16x64_i8 v[22:25], v[160:163], v[202:205], 0
	v_mfma_i32_16x16x64_i8 v[22:25], v[164:167], v[208:211], v[22:25]
	v_mfma_i32_16x16x64_i8 v[18:21], v[186:189], v[202:205], 0
	v_mfma_i32_16x16x64_i8 v[18:21], v[190:193], v[208:211], v[18:21]
	v_mfma_i32_16x16x64_i8 v[14:17], v[160:163], v[212:215], 0
	v_mfma_i32_16x16x64_i8 v[14:17], v[164:167], v[216:219], v[14:17]
	v_mfma_i32_16x16x64_i8 v[10:13], v[186:189], v[212:215], 0
	v_mfma_i32_16x16x64_i8 v[10:13], v[190:193], v[216:219], v[10:13]
	v_mfma_i32_16x16x64_i8 v[6:9], v[160:163], v[220:223], 0
	v_mfma_i32_16x16x64_i8 v[6:9], v[164:167], v[224:227], v[6:9]
	v_mfma_i32_16x16x64_i8 v[2:5], v[186:189], v[220:223], 0
	v_mfma_i32_16x16x64_i8 v[2:5], v[190:193], v[224:227], v[2:5]
	s_barrier
	s_add_i32 s42, 0, 0x18000
	v_add_u32_e32 v138, s42, v183
	s_add_i32 s43, 0, 0x1c000
	ds_read_b128 v[144:147], v138
	ds_read_b128 v[148:151], v138 offset:1024
	ds_read_b128 v[152:155], v138 offset:2048
	ds_read_b128 v[156:159], v138 offset:3072
	v_add_u32_e32 v138, s43, v183
	ds_read_b128 v[160:163], v138
	ds_read_b128 v[164:167], v138 offset:1024
	ds_read_b128 v[186:189], v138 offset:2048
	ds_read_b128 v[190:193], v138 offset:3072
	s_add_u32 s12, s12, 0x80000
	s_addc_u32 s13, s13, 0
	s_mov_b32 m0, s19
	ds_read_b128 v[194:197], v185 offset:32768
	ds_read_b128 v[198:201], v185 offset:33792
	ds_read_b128 v[202:205], v185 offset:34816
	ds_read_b128 v[208:211], v185 offset:35840
	ds_read_b128 v[212:215], v185 offset:36864
	ds_read_b128 v[216:219], v185 offset:37888
	ds_read_b128 v[220:223], v185 offset:38912
	ds_read_b128 v[224:227], v185 offset:39936
	global_load_lds_dwordx4 v130, s[12:13]
	s_mov_b32 m0, s20
	s_nop 0
	global_load_lds_dwordx4 v134, s[12:13]
	s_waitcnt vmcnt(8)
	s_waitcnt lgkmcnt(0)
	s_barrier
	s_waitcnt lgkmcnt(0)
	v_mfma_i32_16x16x64_i8 v[126:129], v[144:147], v[194:197], v[126:129]
	v_mfma_i32_16x16x64_i8 v[126:129], v[148:151], v[198:201], v[126:129]
	v_mfma_i32_16x16x64_i8 v[122:125], v[152:155], v[194:197], v[122:125]
	v_mfma_i32_16x16x64_i8 v[122:125], v[156:159], v[198:201], v[122:125]
	v_mfma_i32_16x16x64_i8 v[118:121], v[144:147], v[202:205], v[118:121]
	v_mfma_i32_16x16x64_i8 v[118:121], v[148:151], v[208:211], v[118:121]
	v_mfma_i32_16x16x64_i8 v[114:117], v[152:155], v[202:205], v[114:117]
	v_mfma_i32_16x16x64_i8 v[114:117], v[156:159], v[208:211], v[114:117]
	v_mfma_i32_16x16x64_i8 v[110:113], v[144:147], v[212:215], v[110:113]
	v_mfma_i32_16x16x64_i8 v[110:113], v[148:151], v[216:219], v[110:113]
	v_mfma_i32_16x16x64_i8 v[106:109], v[152:155], v[212:215], v[106:109]
	v_mfma_i32_16x16x64_i8 v[106:109], v[156:159], v[216:219], v[106:109]
	v_mfma_i32_16x16x64_i8 v[102:105], v[144:147], v[220:223], v[102:105]
	v_mfma_i32_16x16x64_i8 v[102:105], v[148:151], v[224:227], v[102:105]
	v_mfma_i32_16x16x64_i8 v[98:101], v[152:155], v[220:223], v[98:101]
	v_mfma_i32_16x16x64_i8 v[98:101], v[156:159], v[224:227], v[98:101]
	v_mfma_i32_16x16x64_i8 v[94:97], v[160:163], v[194:197], v[94:97]
	v_mfma_i32_16x16x64_i8 v[94:97], v[164:167], v[198:201], v[94:97]
	v_mfma_i32_16x16x64_i8 v[90:93], v[186:189], v[194:197], v[90:93]
	v_mfma_i32_16x16x64_i8 v[90:93], v[190:193], v[198:201], v[90:93]
	v_mfma_i32_16x16x64_i8 v[86:89], v[160:163], v[202:205], v[86:89]
	v_mfma_i32_16x16x64_i8 v[86:89], v[164:167], v[208:211], v[86:89]
	v_mfma_i32_16x16x64_i8 v[82:85], v[186:189], v[202:205], v[82:85]
	v_mfma_i32_16x16x64_i8 v[82:85], v[190:193], v[208:211], v[82:85]
	v_mfma_i32_16x16x64_i8 v[78:81], v[160:163], v[212:215], v[78:81]
	v_mfma_i32_16x16x64_i8 v[78:81], v[164:167], v[216:219], v[78:81]
	v_mfma_i32_16x16x64_i8 v[74:77], v[186:189], v[212:215], v[74:77]
	v_mfma_i32_16x16x64_i8 v[74:77], v[190:193], v[216:219], v[74:77]
	v_mfma_i32_16x16x64_i8 v[70:73], v[160:163], v[220:223], v[70:73]
	v_mfma_i32_16x16x64_i8 v[70:73], v[164:167], v[224:227], v[70:73]
	v_mfma_i32_16x16x64_i8 v[66:69], v[186:189], v[220:223], v[66:69]
	v_mfma_i32_16x16x64_i8 v[66:69], v[190:193], v[224:227], v[66:69]
	s_barrier
	s_add_i32 s12, s42, s16
	s_add_u32 s98, s2, s10
	s_addc_u32 s99, s3, s11
	s_mov_b32 m0, s12
	ds_read_b128 v[194:197], v185 offset:49152
	ds_read_b128 v[198:201], v185 offset:50176
	ds_read_b128 v[202:205], v185 offset:51200
	ds_read_b128 v[208:211], v185 offset:52224
	ds_read_b128 v[212:215], v185 offset:53248
	ds_read_b128 v[216:219], v185 offset:54272
	ds_read_b128 v[220:223], v185 offset:55296
	ds_read_b128 v[224:227], v185 offset:56320
	global_load_lds_dwordx4 v132, s[98:99]
	s_add_i32 m0, s12, 0x2000
	s_add_u32 s2, s2, 0x80080
	s_addc_u32 s3, s3, 0
	s_add_i32 s12, s43, s16
	global_load_lds_dwordx4 v136, s[98:99]
	s_mov_b32 m0, s12
	s_nop 0
	global_load_lds_dwordx4 v132, s[2:3]
	s_add_i32 m0, s12, 0x2000
	s_nop 0
	global_load_lds_dwordx4 v136, s[2:3]
	v_lshl_add_u64 v[228:229], v[232:233], 0, s[10:11]
	s_mov_b32 m0, s22
	s_nop 0
	global_load_lds_dwordx4 v[228:229], off
	v_lshl_add_u64 v[228:229], v[234:235], 0, s[10:11]
	s_mov_b32 m0, s23
	s_nop 0
	global_load_lds_dwordx4 v[228:229], off
	s_waitcnt vmcnt(8)
	s_waitcnt lgkmcnt(0)
	s_barrier
	s_waitcnt lgkmcnt(0)
	v_mfma_i32_16x16x64_i8 v[62:65], v[144:147], v[194:197], v[62:65]
	v_mfma_i32_16x16x64_i8 v[62:65], v[148:151], v[198:201], v[62:65]
	v_mfma_i32_16x16x64_i8 v[58:61], v[152:155], v[194:197], v[58:61]
	v_mfma_i32_16x16x64_i8 v[58:61], v[156:159], v[198:201], v[58:61]
	v_mfma_i32_16x16x64_i8 v[54:57], v[144:147], v[202:205], v[54:57]
	v_mfma_i32_16x16x64_i8 v[54:57], v[148:151], v[208:211], v[54:57]
	v_mfma_i32_16x16x64_i8 v[50:53], v[152:155], v[202:205], v[50:53]
	v_mfma_i32_16x16x64_i8 v[50:53], v[156:159], v[208:211], v[50:53]
	v_mfma_i32_16x16x64_i8 v[46:49], v[144:147], v[212:215], v[46:49]
	v_mfma_i32_16x16x64_i8 v[46:49], v[148:151], v[216:219], v[46:49]
	v_mfma_i32_16x16x64_i8 v[42:45], v[152:155], v[212:215], v[42:45]
	v_mfma_i32_16x16x64_i8 v[42:45], v[156:159], v[216:219], v[42:45]
	v_mfma_i32_16x16x64_i8 v[38:41], v[144:147], v[220:223], v[38:41]
	v_mfma_i32_16x16x64_i8 v[38:41], v[148:151], v[224:227], v[38:41]
	v_mfma_i32_16x16x64_i8 v[34:37], v[152:155], v[220:223], v[34:37]
	v_mfma_i32_16x16x64_i8 v[34:37], v[156:159], v[224:227], v[34:37]
	v_mfma_i32_16x16x64_i8 v[30:33], v[160:163], v[194:197], v[30:33]
	v_mfma_i32_16x16x64_i8 v[30:33], v[164:167], v[198:201], v[30:33]
	v_mfma_i32_16x16x64_i8 v[26:29], v[186:189], v[194:197], v[26:29]
	v_mfma_i32_16x16x64_i8 v[26:29], v[190:193], v[198:201], v[26:29]
	v_mfma_i32_16x16x64_i8 v[22:25], v[160:163], v[202:205], v[22:25]
	v_mfma_i32_16x16x64_i8 v[22:25], v[164:167], v[208:211], v[22:25]
	v_mfma_i32_16x16x64_i8 v[18:21], v[186:189], v[202:205], v[18:21]
	v_mfma_i32_16x16x64_i8 v[18:21], v[190:193], v[208:211], v[18:21]
	v_mfma_i32_16x16x64_i8 v[14:17], v[160:163], v[212:215], v[14:17]
	v_mfma_i32_16x16x64_i8 v[14:17], v[164:167], v[216:219], v[14:17]
	v_mfma_i32_16x16x64_i8 v[10:13], v[186:189], v[212:215], v[10:13]
	v_mfma_i32_16x16x64_i8 v[10:13], v[190:193], v[216:219], v[10:13]
	v_mfma_i32_16x16x64_i8 v[6:9], v[160:163], v[220:223], v[6:9]
	v_mfma_i32_16x16x64_i8 v[6:9], v[164:167], v[224:227], v[6:9]
	v_mfma_i32_16x16x64_i8 v[2:5], v[186:189], v[220:223], v[2:5]
	v_mfma_i32_16x16x64_i8 v[2:5], v[190:193], v[224:227], v[2:5]
	s_barrier
	s_add_u32 s4, s4, 0x100
	s_addc_u32 s5, s5, 0
	s_add_u32 s39, s39, 0x100
	s_addc_u32 s40, s40, 0
	s_cmp_ge_i32 s41, s1
	s_mov_b32 s2, s41
	s_cbranch_scc1 .Lkpeel_exit_0
.LBB0_245:
	v_add_u32_e32 v138, s29, v183
	ds_read_b128 v[144:147], v138
	ds_read_b128 v[148:151], v138 offset:1024
	ds_read_b128 v[152:155], v138 offset:2048
	ds_read_b128 v[156:159], v138 offset:3072
	v_add_u32_e32 v138, s34, v183
	ds_read_b128 v[160:163], v138
	ds_read_b128 v[164:167], v138 offset:1024
	ds_read_b128 v[186:189], v138 offset:2048
	ds_read_b128 v[190:193], v138 offset:3072
	s_add_i32 s41, s2, 2
	s_add_u32 s3, s4, 0xfff80080
	s_addc_u32 s12, s5, -1
	s_cmp_eq_u32 s38, s2
	s_cselect_b32 s2, s37, s39
	s_cselect_b32 s13, s24, s12
	s_cselect_b32 s12, s35, s3
	s_cselect_b32 s3, s36, s40
	s_add_i32 m0, s17, 0xc000
	ds_read_b128 v[194:197], v185
	ds_read_b128 v[198:201], v185 offset:1024
	ds_read_b128 v[202:205], v185 offset:2048
	ds_read_b128 v[208:211], v185 offset:3072
	ds_read_b128 v[212:215], v185 offset:4096
	ds_read_b128 v[216:219], v185 offset:5120
	ds_read_b128 v[220:223], v185 offset:6144
	ds_read_b128 v[224:227], v185 offset:7168
	global_load_lds_dwordx4 v140, s[4:5]
	s_add_i32 m0, s17, 0xe000
	s_nop 0
	global_load_lds_dwordx4 v142, s[4:5]
	s_waitcnt vmcnt(8)
	s_waitcnt lgkmcnt(0)
	s_barrier
	s_waitcnt lgkmcnt(0)
	v_mfma_i32_16x16x64_i8 v[126:129], v[144:147], v[194:197], v[126:129]
	v_mfma_i32_16x16x64_i8 v[126:129], v[148:151], v[198:201], v[126:129]
	v_mfma_i32_16x16x64_i8 v[122:125], v[152:155], v[194:197], v[122:125]
	v_mfma_i32_16x16x64_i8 v[122:125], v[156:159], v[198:201], v[122:125]
	v_mfma_i32_16x16x64_i8 v[118:121], v[144:147], v[202:205], v[118:121]
	v_mfma_i32_16x16x64_i8 v[118:121], v[148:151], v[208:211], v[118:121]
	v_mfma_i32_16x16x64_i8 v[114:117], v[152:155], v[202:205], v[114:117]
	v_mfma_i32_16x16x64_i8 v[114:117], v[156:159], v[208:211], v[114:117]
	v_mfma_i32_16x16x64_i8 v[110:113], v[144:147], v[212:215], v[110:113]
	v_mfma_i32_16x16x64_i8 v[110:113], v[148:151], v[216:219], v[110:113]
	v_mfma_i32_16x16x64_i8 v[106:109], v[152:155], v[212:215], v[106:109]
	v_mfma_i32_16x16x64_i8 v[106:109], v[156:159], v[216:219], v[106:109]
	v_mfma_i32_16x16x64_i8 v[102:105], v[144:147], v[220:223], v[102:105]
	v_mfma_i32_16x16x64_i8 v[102:105], v[148:151], v[224:227], v[102:105]
	v_mfma_i32_16x16x64_i8 v[98:101], v[152:155], v[220:223], v[98:101]
	v_mfma_i32_16x16x64_i8 v[98:101], v[156:159], v[224:227], v[98:101]
	v_mfma_i32_16x16x64_i8 v[94:97], v[160:163], v[194:197], v[94:97]
	v_mfma_i32_16x16x64_i8 v[94:97], v[164:167], v[198:201], v[94:97]
	v_mfma_i32_16x16x64_i8 v[90:93], v[186:189], v[194:197], v[90:93]
	v_mfma_i32_16x16x64_i8 v[90:93], v[190:193], v[198:201], v[90:93]
	v_mfma_i32_16x16x64_i8 v[86:89], v[160:163], v[202:205], v[86:89]
	v_mfma_i32_16x16x64_i8 v[86:89], v[164:167], v[208:211], v[86:89]
	v_mfma_i32_16x16x64_i8 v[82:85], v[186:189], v[202:205], v[82:85]
	v_mfma_i32_16x16x64_i8 v[82:85], v[190:193], v[208:211], v[82:85]
	v_mfma_i32_16x16x64_i8 v[78:81], v[160:163], v[212:215], v[78:81]
	v_mfma_i32_16x16x64_i8 v[78:81], v[164:167], v[216:219], v[78:81]
	v_mfma_i32_16x16x64_i8 v[74:77], v[186:189], v[212:215], v[74:77]
	v_mfma_i32_16x16x64_i8 v[74:77], v[190:193], v[216:219], v[74:77]
	v_mfma_i32_16x16x64_i8 v[70:73], v[160:163], v[220:223], v[70:73]
	v_mfma_i32_16x16x64_i8 v[70:73], v[164:167], v[224:227], v[70:73]
	v_mfma_i32_16x16x64_i8 v[66:69], v[186:189], v[220:223], v[66:69]
	v_mfma_i32_16x16x64_i8 v[66:69], v[190:193], v[224:227], v[66:69]
	s_barrier
	s_add_i32 s42, s29, s16
	s_mov_b32 m0, s42
	ds_read_b128 v[194:197], v185 offset:16384
	ds_read_b128 v[198:201], v185 offset:17408
	ds_read_b128 v[202:205], v185 offset:18432
	ds_read_b128 v[208:211], v185 offset:19456
	ds_read_b128 v[212:215], v185 offset:20480
	ds_read_b128 v[216:219], v185 offset:21504
	ds_read_b128 v[220:223], v185 offset:22528
	ds_read_b128 v[224:227], v185 offset:23552
	global_load_lds_dwordx4 v132, s[2:3]
	s_add_i32 m0, s42, 0x2000
	s_add_u32 s42, s2, 0x80000
	s_addc_u32 s43, s3, 0
	s_add_i32 s44, s34, s16
	global_load_lds_dwordx4 v136, s[2:3]
	s_mov_b32 m0, s44
	v_lshl_add_u64 v[234:235], s[12:13], 0, v[134:135]
	global_load_lds_dwordx4 v132, s[42:43]
	s_add_i32 m0, s44, 0x2000
	s_nop 0
	global_load_lds_dwordx4 v136, s[42:43]
	v_lshl_add_u64 v[232:233], s[12:13], 0, v[130:131]
	s_mov_b32 m0, s17
	s_nop 0
	global_load_lds_dwordx4 v130, s[12:13]
	s_mov_b32 m0, s18
	s_nop 0
	global_load_lds_dwordx4 v134, s[12:13]
	s_waitcnt vmcnt(8)
	s_waitcnt lgkmcnt(0)
	s_barrier
	s_waitcnt lgkmcnt(0)
	v_mfma_i32_16x16x64_i8 v[62:65], v[144:147], v[194:197], v[62:65]
	v_mfma_i32_16x16x64_i8 v[62:65], v[148:151], v[198:201], v[62:65]
	v_mfma_i32_16x16x64_i8 v[58:61], v[152:155], v[194:197], v[58:61]
	v_mfma_i32_16x16x64_i8 v[58:61], v[156:159], v[198:201], v[58:61]
	v_mfma_i32_16x16x64_i8 v[54:57], v[144:147], v[202:205], v[54:57]
	v_mfma_i32_16x16x64_i8 v[54:57], v[148:151], v[208:211], v[54:57]
	v_mfma_i32_16x16x64_i8 v[50:53], v[152:155], v[202:205], v[50:53]
	v_mfma_i32_16x16x64_i8 v[50:53], v[156:159], v[208:211], v[50:53]
	v_mfma_i32_16x16x64_i8 v[46:49], v[144:147], v[212:215], v[46:49]
	v_mfma_i32_16x16x64_i8 v[46:49], v[148:151], v[216:219], v[46:49]
	v_mfma_i32_16x16x64_i8 v[42:45], v[152:155], v[212:215], v[42:45]
	v_mfma_i32_16x16x64_i8 v[42:45], v[156:159], v[216:219], v[42:45]
	v_mfma_i32_16x16x64_i8 v[38:41], v[144:147], v[220:223], v[38:41]
	v_mfma_i32_16x16x64_i8 v[38:41], v[148:151], v[224:227], v[38:41]
	v_mfma_i32_16x16x64_i8 v[34:37], v[152:155], v[220:223], v[34:37]
	v_mfma_i32_16x16x64_i8 v[34:37], v[156:159], v[224:227], v[34:37]
	v_mfma_i32_16x16x64_i8 v[30:33], v[160:163], v[194:197], v[30:33]
	v_mfma_i32_16x16x64_i8 v[30:33], v[164:167], v[198:201], v[30:33]
	v_mfma_i32_16x16x64_i8 v[26:29], v[186:189], v[194:197], v[26:29]
	v_mfma_i32_16x16x64_i8 v[26:29], v[190:193], v[198:201], v[26:29]
	v_mfma_i32_16x16x64_i8 v[22:25], v[160:163], v[202:205], v[22:25]
	v_mfma_i32_16x16x64_i8 v[22:25], v[164:167], v[208:211], v[22:25]
	v_mfma_i32_16x16x64_i8 v[18:21], v[186:189], v[202:205], v[18:21]
	v_mfma_i32_16x16x64_i8 v[18:21], v[190:193], v[208:211], v[18:21]
	v_mfma_i32_16x16x64_i8 v[14:17], v[160:163], v[212:215], v[14:17]
	v_mfma_i32_16x16x64_i8 v[14:17], v[164:167], v[216:219], v[14:17]
	v_mfma_i32_16x16x64_i8 v[10:13], v[186:189], v[212:215], v[10:13]
	v_mfma_i32_16x16x64_i8 v[10:13], v[190:193], v[216:219], v[10:13]
	v_mfma_i32_16x16x64_i8 v[6:9], v[160:163], v[220:223], v[6:9]
	v_mfma_i32_16x16x64_i8 v[6:9], v[164:167], v[224:227], v[6:9]
	v_mfma_i32_16x16x64_i8 v[2:5], v[186:189], v[220:223], v[2:5]
	v_mfma_i32_16x16x64_i8 v[2:5], v[190:193], v[224:227], v[2:5]
	s_barrier
	s_add_i32 s42, 0, 0x18000
	v_add_u32_e32 v138, s42, v183
	s_add_i32 s43, 0, 0x1c000
	ds_read_b128 v[144:147], v138
	ds_read_b128 v[148:151], v138 offset:1024
	ds_read_b128 v[152:155], v138 offset:2048
	ds_read_b128 v[156:159], v138 offset:3072
	v_add_u32_e32 v138, s43, v183
	ds_read_b128 v[160:163], v138
	ds_read_b128 v[164:167], v138 offset:1024
	ds_read_b128 v[186:189], v138 offset:2048
	ds_read_b128 v[190:193], v138 offset:3072
	s_add_u32 s12, s12, 0x80000
	s_addc_u32 s13, s13, 0
	s_mov_b32 m0, s19
	ds_read_b128 v[194:197], v185 offset:32768
	ds_read_b128 v[198:201], v185 offset:33792
	ds_read_b128 v[202:205], v185 offset:34816
	ds_read_b128 v[208:211], v185 offset:35840
	ds_read_b128 v[212:215], v185 offset:36864
	ds_read_b128 v[216:219], v185 offset:37888
	ds_read_b128 v[220:223], v185 offset:38912
	ds_read_b128 v[224:227], v185 offset:39936
	global_load_lds_dwordx4 v130, s[12:13]
	s_mov_b32 m0, s20
	s_nop 0
	global_load_lds_dwordx4 v134, s[12:13]
	s_waitcnt vmcnt(8)
	s_waitcnt lgkmcnt(0)
	s_barrier
	s_waitcnt lgkmcnt(0)
	v_mfma_i32_16x16x64_i8 v[126:129], v[144:147], v[194:197], v[126:129]
	v_mfma_i32_16x16x64_i8 v[126:129], v[148:151], v[198:201], v[126:129]
	v_mfma_i32_16x16x64_i8 v[122:125], v[152:155], v[194:197], v[122:125]
	v_mfma_i32_16x16x64_i8 v[122:125], v[156:159], v[198:201], v[122:125]
	v_mfma_i32_16x16x64_i8 v[118:121], v[144:147], v[202:205], v[118:121]
	v_mfma_i32_16x16x64_i8 v[118:121], v[148:151], v[208:211], v[118:121]
	v_mfma_i32_16x16x64_i8 v[114:117], v[152:155], v[202:205], v[114:117]
	v_mfma_i32_16x16x64_i8 v[114:117], v[156:159], v[208:211], v[114:117]
	v_mfma_i32_16x16x64_i8 v[110:113], v[144:147], v[212:215], v[110:113]
	v_mfma_i32_16x16x64_i8 v[110:113], v[148:151], v[216:219], v[110:113]
	v_mfma_i32_16x16x64_i8 v[106:109], v[152:155], v[212:215], v[106:109]
	v_mfma_i32_16x16x64_i8 v[106:109], v[156:159], v[216:219], v[106:109]
	v_mfma_i32_16x16x64_i8 v[102:105], v[144:147], v[220:223], v[102:105]
	v_mfma_i32_16x16x64_i8 v[102:105], v[148:151], v[224:227], v[102:105]
	v_mfma_i32_16x16x64_i8 v[98:101], v[152:155], v[220:223], v[98:101]
	v_mfma_i32_16x16x64_i8 v[98:101], v[156:159], v[224:227], v[98:101]
	v_mfma_i32_16x16x64_i8 v[94:97], v[160:163], v[194:197], v[94:97]
	v_mfma_i32_16x16x64_i8 v[94:97], v[164:167], v[198:201], v[94:97]
	v_mfma_i32_16x16x64_i8 v[90:93], v[186:189], v[194:197], v[90:93]
	v_mfma_i32_16x16x64_i8 v[90:93], v[190:193], v[198:201], v[90:93]
	v_mfma_i32_16x16x64_i8 v[86:89], v[160:163], v[202:205], v[86:89]
	v_mfma_i32_16x16x64_i8 v[86:89], v[164:167], v[208:211], v[86:89]
	v_mfma_i32_16x16x64_i8 v[82:85], v[186:189], v[202:205], v[82:85]
	v_mfma_i32_16x16x64_i8 v[82:85], v[190:193], v[208:211], v[82:85]
	v_mfma_i32_16x16x64_i8 v[78:81], v[160:163], v[212:215], v[78:81]
	v_mfma_i32_16x16x64_i8 v[78:81], v[164:167], v[216:219], v[78:81]
	v_mfma_i32_16x16x64_i8 v[74:77], v[186:189], v[212:215], v[74:77]
	v_mfma_i32_16x16x64_i8 v[74:77], v[190:193], v[216:219], v[74:77]
	v_mfma_i32_16x16x64_i8 v[70:73], v[160:163], v[220:223], v[70:73]
	v_mfma_i32_16x16x64_i8 v[70:73], v[164:167], v[224:227], v[70:73]
	v_mfma_i32_16x16x64_i8 v[66:69], v[186:189], v[220:223], v[66:69]
	v_mfma_i32_16x16x64_i8 v[66:69], v[190:193], v[224:227], v[66:69]
	s_barrier
	s_add_i32 s12, s42, s16
	s_add_u32 s98, s2, s10
	s_addc_u32 s99, s3, s11
	s_mov_b32 m0, s12
	ds_read_b128 v[194:197], v185 offset:49152
	ds_read_b128 v[198:201], v185 offset:50176
	ds_read_b128 v[202:205], v185 offset:51200
	ds_read_b128 v[208:211], v185 offset:52224
	ds_read_b128 v[212:215], v185 offset:53248
	ds_read_b128 v[216:219], v185 offset:54272
	ds_read_b128 v[220:223], v185 offset:55296
	ds_read_b128 v[224:227], v185 offset:56320
	global_load_lds_dwordx4 v132, s[98:99]
	s_add_i32 m0, s12, 0x2000
	s_add_u32 s2, s2, 0x80080
	s_addc_u32 s3, s3, 0
	s_add_i32 s12, s43, s16
	global_load_lds_dwordx4 v136, s[98:99]
	s_mov_b32 m0, s12
	s_nop 0
	global_load_lds_dwordx4 v132, s[2:3]
	s_add_i32 m0, s12, 0x2000
	s_nop 0
	global_load_lds_dwordx4 v136, s[2:3]
	v_lshl_add_u64 v[228:229], v[232:233], 0, s[10:11]
	s_mov_b32 m0, s22
	s_nop 0
	global_load_lds_dwordx4 v[228:229], off
	v_lshl_add_u64 v[228:229], v[234:235], 0, s[10:11]
	s_mov_b32 m0, s23
	s_nop 0
	global_load_lds_dwordx4 v[228:229], off
	s_waitcnt vmcnt(8)
	s_waitcnt lgkmcnt(0)
	s_barrier
	s_waitcnt lgkmcnt(0)
	v_mfma_i32_16x16x64_i8 v[62:65], v[144:147], v[194:197], v[62:65]
	v_mfma_i32_16x16x64_i8 v[62:65], v[148:151], v[198:201], v[62:65]
	v_mfma_i32_16x16x64_i8 v[58:61], v[152:155], v[194:197], v[58:61]
	v_mfma_i32_16x16x64_i8 v[58:61], v[156:159], v[198:201], v[58:61]
	v_mfma_i32_16x16x64_i8 v[54:57], v[144:147], v[202:205], v[54:57]
	v_mfma_i32_16x16x64_i8 v[54:57], v[148:151], v[208:211], v[54:57]
	v_mfma_i32_16x16x64_i8 v[50:53], v[152:155], v[202:205], v[50:53]
	v_mfma_i32_16x16x64_i8 v[50:53], v[156:159], v[208:211], v[50:53]
	v_mfma_i32_16x16x64_i8 v[46:49], v[144:147], v[212:215], v[46:49]
	v_mfma_i32_16x16x64_i8 v[46:49], v[148:151], v[216:219], v[46:49]
	v_mfma_i32_16x16x64_i8 v[42:45], v[152:155], v[212:215], v[42:45]
	v_mfma_i32_16x16x64_i8 v[42:45], v[156:159], v[216:219], v[42:45]
	v_mfma_i32_16x16x64_i8 v[38:41], v[144:147], v[220:223], v[38:41]
	v_mfma_i32_16x16x64_i8 v[38:41], v[148:151], v[224:227], v[38:41]
	v_mfma_i32_16x16x64_i8 v[34:37], v[152:155], v[220:223], v[34:37]
	v_mfma_i32_16x16x64_i8 v[34:37], v[156:159], v[224:227], v[34:37]
	v_mfma_i32_16x16x64_i8 v[30:33], v[160:163], v[194:197], v[30:33]
	v_mfma_i32_16x16x64_i8 v[30:33], v[164:167], v[198:201], v[30:33]
	v_mfma_i32_16x16x64_i8 v[26:29], v[186:189], v[194:197], v[26:29]
	v_mfma_i32_16x16x64_i8 v[26:29], v[190:193], v[198:201], v[26:29]
	v_mfma_i32_16x16x64_i8 v[22:25], v[160:163], v[202:205], v[22:25]
	v_mfma_i32_16x16x64_i8 v[22:25], v[164:167], v[208:211], v[22:25]
	v_mfma_i32_16x16x64_i8 v[18:21], v[186:189], v[202:205], v[18:21]
	v_mfma_i32_16x16x64_i8 v[18:21], v[190:193], v[208:211], v[18:21]
	v_mfma_i32_16x16x64_i8 v[14:17], v[160:163], v[212:215], v[14:17]
	v_mfma_i32_16x16x64_i8 v[14:17], v[164:167], v[216:219], v[14:17]
	v_mfma_i32_16x16x64_i8 v[10:13], v[186:189], v[212:215], v[10:13]
	v_mfma_i32_16x16x64_i8 v[10:13], v[190:193], v[216:219], v[10:13]
	v_mfma_i32_16x16x64_i8 v[6:9], v[160:163], v[220:223], v[6:9]
	v_mfma_i32_16x16x64_i8 v[6:9], v[164:167], v[224:227], v[6:9]
	v_mfma_i32_16x16x64_i8 v[2:5], v[186:189], v[220:223], v[2:5]
	v_mfma_i32_16x16x64_i8 v[2:5], v[190:193], v[224:227], v[2:5]
	s_barrier
	s_add_u32 s4, s4, 0x100
	s_addc_u32 s5, s5, 0
	s_add_u32 s39, s39, 0x100
	s_addc_u32 s40, s40, 0
	s_cmp_ge_i32 s41, s1
	s_mov_b32 s2, s41
	s_cbranch_scc0 .LBB0_245

.LBB0_265:
	s_lshl_b32 s10, s8, 21
	s_and_b32 s10, s10, 0x1fe00000
	v_readlane_b32 s40, v248, 20
	v_readlane_b32 s41, v248, 21
	s_add_u32 s10, s40, s10
	s_addc_u32 s33, s41, 0
	s_lshr_b32 s39, s8, 13
	s_and_b32 s39, s39, 0x7ff80
	s_add_u32 s70, s10, s39
	s_addc_u32 s71, s33, 0
	s_lshl_b32 s10, s8, 13
	s_and_b32 s10, s10, 0x1fe00000
	v_readlane_b32 s40, v248, 18
	v_readlane_b32 s41, v248, 19
	s_add_u32 s10, s40, s10
	s_addc_u32 s33, s41, 0
	s_add_u32 s72, s10, s39
	s_addc_u32 s73, s33, 0
	s_cmp_lt_i32 s1, 1
	v_cmp_gt_i64_e64 s[74:75], s[8:9], -1
	s_cbranch_scc1 .LBB0_324
	s_and_b64 s[8:9], s[74:75], exec
	s_cselect_b32 s10, s71, s5
	s_cselect_b32 s33, s70, s4
	s_cselect_b32 s39, s73, s3
	s_cselect_b32 s40, s72, s2
	s_add_i32 s41, s1, -2
	s_add_u32 s4, s4, 0x100080
	s_addc_u32 s5, s5, 0
	s_add_u32 s42, s2, 0x100
	s_addc_u32 s43, s3, 0
	s_mov_b32 s2, 0
	ds_read_b128 v[148:151], v145
	ds_read_b128 v[152:155], v145 offset:1024
	ds_read_b128 v[156:159], v145 offset:2048
	ds_read_b128 v[160:163], v145 offset:3072
	ds_read_b128 v[164:167], v146
	ds_read_b128 v[168:171], v146 offset:1024
	ds_read_b128 v[172:175], v146 offset:2048
	ds_read_b128 v[176:179], v146 offset:3072
	s_add_i32 s44, s2, 2
	s_add_u32 s3, s4, 0xfff00080
	s_addc_u32 s8, s5, -1
	s_cmp_eq_u32 s41, s2
	s_cselect_b32 s2, s40, s42
	s_cselect_b32 s9, s10, s8
	s_cselect_b32 s8, s33, s3
	s_cselect_b32 s3, s39, s43
	s_add_i32 m0, s16, 0xc000
	ds_read_b128 v[180:183], v147
	ds_read_b128 v[184:187], v147 offset:1024
	ds_read_b128 v[188:191], v147 offset:2048
	ds_read_b128 v[192:195], v147 offset:3072
	ds_read_b128 v[196:199], v147 offset:4096
	ds_read_b128 v[200:203], v147 offset:5120
	ds_read_b128 v[208:211], v147 offset:6144
	ds_read_b128 v[212:215], v147 offset:7168
	global_load_lds_dwordx4 v138, s[4:5]
	s_add_i32 m0, s16, 0xe000
	s_nop 0
	global_load_lds_dwordx4 v140, s[4:5]
	s_waitcnt vmcnt(8)
	s_waitcnt lgkmcnt(0)
	s_barrier
	s_waitcnt lgkmcnt(0)
	v_mfma_f32_16x16x32_bf16 v[122:125], v[148:151], v[180:183], 0
	v_mfma_f32_16x16x32_bf16 v[122:125], v[152:155], v[184:187], v[122:125]
	v_mfma_f32_16x16x32_bf16 v[118:121], v[156:159], v[180:183], 0
	v_mfma_f32_16x16x32_bf16 v[118:121], v[160:163], v[184:187], v[118:121]
	v_mfma_f32_16x16x32_bf16 v[110:113], v[148:151], v[188:191], 0
	v_mfma_f32_16x16x32_bf16 v[110:113], v[152:155], v[192:195], v[110:113]
	v_mfma_f32_16x16x32_bf16 v[102:105], v[156:159], v[188:191], 0
	v_mfma_f32_16x16x32_bf16 v[102:105], v[160:163], v[192:195], v[102:105]
	v_mfma_f32_16x16x32_bf16 v[94:97], v[148:151], v[196:199], 0
	v_mfma_f32_16x16x32_bf16 v[94:97], v[152:155], v[200:203], v[94:97]
	v_mfma_f32_16x16x32_bf16 v[86:89], v[156:159], v[196:199], 0
	v_mfma_f32_16x16x32_bf16 v[86:89], v[160:163], v[200:203], v[86:89]
	v_mfma_f32_16x16x32_bf16 v[78:81], v[148:151], v[208:211], 0
	v_mfma_f32_16x16x32_bf16 v[78:81], v[152:155], v[212:215], v[78:81]
	v_mfma_f32_16x16x32_bf16 v[70:73], v[156:159], v[208:211], 0
	v_mfma_f32_16x16x32_bf16 v[70:73], v[160:163], v[212:215], v[70:73]
	v_mfma_f32_16x16x32_bf16 v[126:129], v[164:167], v[180:183], 0
	v_mfma_f32_16x16x32_bf16 v[126:129], v[168:171], v[184:187], v[126:129]
	v_mfma_f32_16x16x32_bf16 v[114:117], v[172:175], v[180:183], 0
	v_mfma_f32_16x16x32_bf16 v[114:117], v[176:179], v[184:187], v[114:117]
	v_mfma_f32_16x16x32_bf16 v[106:109], v[164:167], v[188:191], 0
	v_mfma_f32_16x16x32_bf16 v[106:109], v[168:171], v[192:195], v[106:109]
	v_mfma_f32_16x16x32_bf16 v[98:101], v[172:175], v[188:191], 0
	v_mfma_f32_16x16x32_bf16 v[98:101], v[176:179], v[192:195], v[98:101]
	v_mfma_f32_16x16x32_bf16 v[90:93], v[164:167], v[196:199], 0
	v_mfma_f32_16x16x32_bf16 v[90:93], v[168:171], v[200:203], v[90:93]
	v_mfma_f32_16x16x32_bf16 v[82:85], v[172:175], v[196:199], 0
	v_mfma_f32_16x16x32_bf16 v[82:85], v[176:179], v[200:203], v[82:85]
	v_mfma_f32_16x16x32_bf16 v[74:77], v[164:167], v[208:211], 0
	v_mfma_f32_16x16x32_bf16 v[74:77], v[168:171], v[212:215], v[74:77]
	v_mfma_f32_16x16x32_bf16 v[66:69], v[172:175], v[208:211], 0
	v_mfma_f32_16x16x32_bf16 v[66:69], v[176:179], v[212:215], v[66:69]
	s_barrier
	s_add_i32 s45, s36, s13
	s_mov_b32 m0, s45
	ds_read_b128 v[180:183], v147 offset:16384
	ds_read_b128 v[184:187], v147 offset:17408
	ds_read_b128 v[188:191], v147 offset:18432
	ds_read_b128 v[192:195], v147 offset:19456
	ds_read_b128 v[196:199], v147 offset:20480
	ds_read_b128 v[200:203], v147 offset:21504
	ds_read_b128 v[208:211], v147 offset:22528
	ds_read_b128 v[212:215], v147 offset:23552
	global_load_lds_dwordx4 v132, s[2:3]
	s_add_i32 m0, s45, 0x2000
	s_add_u32 s46, s2, 0x100000
	s_addc_u32 s47, s3, 0
	s_add_i32 s45, s37, s13
	global_load_lds_dwordx4 v136, s[2:3]
	s_mov_b32 m0, s45
	v_lshl_add_u64 v[220:221], s[8:9], 0, v[134:135]
	global_load_lds_dwordx4 v132, s[46:47]
	s_add_i32 m0, s45, 0x2000
	s_nop 0
	global_load_lds_dwordx4 v136, s[46:47]
	v_lshl_add_u64 v[218:219], s[8:9], 0, v[130:131]
	s_mov_b32 m0, s16
	s_nop 0
	global_load_lds_dwordx4 v130, s[8:9]
	s_mov_b32 m0, s17
	s_nop 0
	global_load_lds_dwordx4 v134, s[8:9]
	s_waitcnt vmcnt(8)
	s_waitcnt lgkmcnt(0)
	s_barrier
	s_waitcnt lgkmcnt(0)
	v_mfma_f32_16x16x32_bf16 v[62:65], v[148:151], v[180:183], 0
	v_mfma_f32_16x16x32_bf16 v[62:65], v[152:155], v[184:187], v[62:65]
	v_mfma_f32_16x16x32_bf16 v[54:57], v[156:159], v[180:183], 0
	v_mfma_f32_16x16x32_bf16 v[54:57], v[160:163], v[184:187], v[54:57]
	v_mfma_f32_16x16x32_bf16 v[46:49], v[148:151], v[188:191], 0
	v_mfma_f32_16x16x32_bf16 v[46:49], v[152:155], v[192:195], v[46:49]
	v_mfma_f32_16x16x32_bf16 v[38:41], v[156:159], v[188:191], 0
	v_mfma_f32_16x16x32_bf16 v[38:41], v[160:163], v[192:195], v[38:41]
	v_mfma_f32_16x16x32_bf16 v[30:33], v[148:151], v[196:199], 0
	v_mfma_f32_16x16x32_bf16 v[30:33], v[152:155], v[200:203], v[30:33]
	v_mfma_f32_16x16x32_bf16 v[22:25], v[156:159], v[196:199], 0
	v_mfma_f32_16x16x32_bf16 v[22:25], v[160:163], v[200:203], v[22:25]
	v_mfma_f32_16x16x32_bf16 v[14:17], v[148:151], v[208:211], 0
	v_mfma_f32_16x16x32_bf16 v[14:17], v[152:155], v[212:215], v[14:17]
	v_mfma_f32_16x16x32_bf16 v[6:9], v[156:159], v[208:211], 0
	v_mfma_f32_16x16x32_bf16 v[6:9], v[160:163], v[212:215], v[6:9]
	v_mfma_f32_16x16x32_bf16 v[58:61], v[164:167], v[180:183], 0
	v_mfma_f32_16x16x32_bf16 v[58:61], v[168:171], v[184:187], v[58:61]
	v_mfma_f32_16x16x32_bf16 v[50:53], v[172:175], v[180:183], 0
	v_mfma_f32_16x16x32_bf16 v[50:53], v[176:179], v[184:187], v[50:53]
	v_mfma_f32_16x16x32_bf16 v[42:45], v[164:167], v[188:191], 0
	v_mfma_f32_16x16x32_bf16 v[42:45], v[168:171], v[192:195], v[42:45]
	v_mfma_f32_16x16x32_bf16 v[34:37], v[172:175], v[188:191], 0
	v_mfma_f32_16x16x32_bf16 v[34:37], v[176:179], v[192:195], v[34:37]
	v_mfma_f32_16x16x32_bf16 v[26:29], v[164:167], v[196:199], 0
	v_mfma_f32_16x16x32_bf16 v[26:29], v[168:171], v[200:203], v[26:29]
	v_mfma_f32_16x16x32_bf16 v[18:21], v[172:175], v[196:199], 0
	v_mfma_f32_16x16x32_bf16 v[18:21], v[176:179], v[200:203], v[18:21]
	v_mfma_f32_16x16x32_bf16 v[10:13], v[164:167], v[208:211], 0
	v_mfma_f32_16x16x32_bf16 v[10:13], v[168:171], v[212:215], v[10:13]
	v_mfma_f32_16x16x32_bf16 v[2:5], v[172:175], v[208:211], 0
	v_mfma_f32_16x16x32_bf16 v[2:5], v[176:179], v[212:215], v[2:5]
	s_barrier
	s_add_i32 s45, 0, 0x18000
	s_add_i32 s46, 0, 0x1c000
	v_add_u32_e32 v160, s45, v1
	v_add_u32_e32 v176, s46, v1
	ds_read_b128 v[148:151], v160
	ds_read_b128 v[152:155], v160 offset:1024
	ds_read_b128 v[156:159], v160 offset:2048
	ds_read_b128 v[160:163], v160 offset:3072
	ds_read_b128 v[164:167], v176
	ds_read_b128 v[168:171], v176 offset:1024
	ds_read_b128 v[172:175], v176 offset:2048
	ds_read_b128 v[176:179], v176 offset:3072
	s_add_u32 s8, s8, 0x100000
	s_addc_u32 s9, s9, 0
	s_mov_b32 m0, s18
	ds_read_b128 v[180:183], v147 offset:32768
	ds_read_b128 v[184:187], v147 offset:33792
	ds_read_b128 v[188:191], v147 offset:34816
	ds_read_b128 v[192:195], v147 offset:35840
	ds_read_b128 v[196:199], v147 offset:36864
	ds_read_b128 v[200:203], v147 offset:37888
	ds_read_b128 v[208:211], v147 offset:38912
	ds_read_b128 v[212:215], v147 offset:39936
	global_load_lds_dwordx4 v130, s[8:9]
	s_mov_b32 m0, s19
	s_nop 0
	global_load_lds_dwordx4 v134, s[8:9]
	s_waitcnt vmcnt(8)
	s_waitcnt lgkmcnt(0)
	s_barrier
	s_waitcnt lgkmcnt(0)
	v_mfma_f32_16x16x32_bf16 v[122:125], v[148:151], v[180:183], v[122:125]
	v_mfma_f32_16x16x32_bf16 v[122:125], v[152:155], v[184:187], v[122:125]
	v_mfma_f32_16x16x32_bf16 v[118:121], v[156:159], v[180:183], v[118:121]
	v_mfma_f32_16x16x32_bf16 v[118:121], v[160:163], v[184:187], v[118:121]
	v_mfma_f32_16x16x32_bf16 v[110:113], v[148:151], v[188:191], v[110:113]
	v_mfma_f32_16x16x32_bf16 v[110:113], v[152:155], v[192:195], v[110:113]
	v_mfma_f32_16x16x32_bf16 v[102:105], v[156:159], v[188:191], v[102:105]
	v_mfma_f32_16x16x32_bf16 v[102:105], v[160:163], v[192:195], v[102:105]
	v_mfma_f32_16x16x32_bf16 v[94:97], v[148:151], v[196:199], v[94:97]
	v_mfma_f32_16x16x32_bf16 v[94:97], v[152:155], v[200:203], v[94:97]
	v_mfma_f32_16x16x32_bf16 v[86:89], v[156:159], v[196:199], v[86:89]
	v_mfma_f32_16x16x32_bf16 v[86:89], v[160:163], v[200:203], v[86:89]
	v_mfma_f32_16x16x32_bf16 v[78:81], v[148:151], v[208:211], v[78:81]
	v_mfma_f32_16x16x32_bf16 v[78:81], v[152:155], v[212:215], v[78:81]
	v_mfma_f32_16x16x32_bf16 v[70:73], v[156:159], v[208:211], v[70:73]
	v_mfma_f32_16x16x32_bf16 v[70:73], v[160:163], v[212:215], v[70:73]
	v_mfma_f32_16x16x32_bf16 v[126:129], v[164:167], v[180:183], v[126:129]
	v_mfma_f32_16x16x32_bf16 v[126:129], v[168:171], v[184:187], v[126:129]
	v_mfma_f32_16x16x32_bf16 v[114:117], v[172:175], v[180:183], v[114:117]
	v_mfma_f32_16x16x32_bf16 v[114:117], v[176:179], v[184:187], v[114:117]
	v_mfma_f32_16x16x32_bf16 v[106:109], v[164:167], v[188:191], v[106:109]
	v_mfma_f32_16x16x32_bf16 v[106:109], v[168:171], v[192:195], v[106:109]
	v_mfma_f32_16x16x32_bf16 v[98:101], v[172:175], v[188:191], v[98:101]
	v_mfma_f32_16x16x32_bf16 v[98:101], v[176:179], v[192:195], v[98:101]
	v_mfma_f32_16x16x32_bf16 v[90:93], v[164:167], v[196:199], v[90:93]
	v_mfma_f32_16x16x32_bf16 v[90:93], v[168:171], v[200:203], v[90:93]
	v_mfma_f32_16x16x32_bf16 v[82:85], v[172:175], v[196:199], v[82:85]
	v_mfma_f32_16x16x32_bf16 v[82:85], v[176:179], v[200:203], v[82:85]
	v_mfma_f32_16x16x32_bf16 v[74:77], v[164:167], v[208:211], v[74:77]
	v_mfma_f32_16x16x32_bf16 v[74:77], v[168:171], v[212:215], v[74:77]
	v_mfma_f32_16x16x32_bf16 v[66:69], v[172:175], v[208:211], v[66:69]
	v_mfma_f32_16x16x32_bf16 v[66:69], v[176:179], v[212:215], v[66:69]
	s_barrier
	s_add_i32 s8, s45, s13
	s_add_u32 s98, s2, s24
	s_addc_u32 s99, s3, s25
	s_mov_b32 m0, s8
	ds_read_b128 v[180:183], v147 offset:49152
	ds_read_b128 v[184:187], v147 offset:50176
	ds_read_b128 v[188:191], v147 offset:51200
	ds_read_b128 v[192:195], v147 offset:52224
	ds_read_b128 v[196:199], v147 offset:53248
	ds_read_b128 v[200:203], v147 offset:54272
	ds_read_b128 v[208:211], v147 offset:55296
	ds_read_b128 v[212:215], v147 offset:56320
	global_load_lds_dwordx4 v132, s[98:99]
	s_add_i32 m0, s8, 0x2000
	s_add_u32 s2, s2, 0x100080
	s_addc_u32 s3, s3, 0
	s_add_i32 s8, s46, s13
	global_load_lds_dwordx4 v136, s[98:99]
	s_mov_b32 m0, s8
	s_nop 0
	global_load_lds_dwordx4 v132, s[2:3]
	s_add_i32 m0, s8, 0x2000
	s_nop 0
	global_load_lds_dwordx4 v136, s[2:3]
	v_lshl_add_u64 v[204:205], v[218:219], 0, s[24:25]
	s_mov_b32 m0, s29
	s_nop 0
	global_load_lds_dwordx4 v[204:205], off
	v_lshl_add_u64 v[204:205], v[220:221], 0, s[24:25]
	s_mov_b32 m0, s34
	s_nop 0
	global_load_lds_dwordx4 v[204:205], off
	s_waitcnt vmcnt(8)
	s_waitcnt lgkmcnt(0)
	s_barrier
	s_waitcnt lgkmcnt(0)
	v_mfma_f32_16x16x32_bf16 v[62:65], v[148:151], v[180:183], v[62:65]
	v_mfma_f32_16x16x32_bf16 v[62:65], v[152:155], v[184:187], v[62:65]
	v_mfma_f32_16x16x32_bf16 v[54:57], v[156:159], v[180:183], v[54:57]
	v_mfma_f32_16x16x32_bf16 v[54:57], v[160:163], v[184:187], v[54:57]
	v_mfma_f32_16x16x32_bf16 v[46:49], v[148:151], v[188:191], v[46:49]
	v_mfma_f32_16x16x32_bf16 v[46:49], v[152:155], v[192:195], v[46:49]
	v_mfma_f32_16x16x32_bf16 v[38:41], v[156:159], v[188:191], v[38:41]
	v_mfma_f32_16x16x32_bf16 v[38:41], v[160:163], v[192:195], v[38:41]
	v_mfma_f32_16x16x32_bf16 v[30:33], v[148:151], v[196:199], v[30:33]
	v_mfma_f32_16x16x32_bf16 v[30:33], v[152:155], v[200:203], v[30:33]
	v_mfma_f32_16x16x32_bf16 v[22:25], v[156:159], v[196:199], v[22:25]
	v_mfma_f32_16x16x32_bf16 v[22:25], v[160:163], v[200:203], v[22:25]
	v_mfma_f32_16x16x32_bf16 v[14:17], v[148:151], v[208:211], v[14:17]
	v_mfma_f32_16x16x32_bf16 v[14:17], v[152:155], v[212:215], v[14:17]
	v_mfma_f32_16x16x32_bf16 v[6:9], v[156:159], v[208:211], v[6:9]
	v_mfma_f32_16x16x32_bf16 v[6:9], v[160:163], v[212:215], v[6:9]
	v_mfma_f32_16x16x32_bf16 v[58:61], v[164:167], v[180:183], v[58:61]
	v_mfma_f32_16x16x32_bf16 v[58:61], v[168:171], v[184:187], v[58:61]
	v_mfma_f32_16x16x32_bf16 v[50:53], v[172:175], v[180:183], v[50:53]
	v_mfma_f32_16x16x32_bf16 v[50:53], v[176:179], v[184:187], v[50:53]
	v_mfma_f32_16x16x32_bf16 v[42:45], v[164:167], v[188:191], v[42:45]
	v_mfma_f32_16x16x32_bf16 v[42:45], v[168:171], v[192:195], v[42:45]
	v_mfma_f32_16x16x32_bf16 v[34:37], v[172:175], v[188:191], v[34:37]
	v_mfma_f32_16x16x32_bf16 v[34:37], v[176:179], v[192:195], v[34:37]
	v_mfma_f32_16x16x32_bf16 v[26:29], v[164:167], v[196:199], v[26:29]
	v_mfma_f32_16x16x32_bf16 v[26:29], v[168:171], v[200:203], v[26:29]
	v_mfma_f32_16x16x32_bf16 v[18:21], v[172:175], v[196:199], v[18:21]
	v_mfma_f32_16x16x32_bf16 v[18:21], v[176:179], v[200:203], v[18:21]
	v_mfma_f32_16x16x32_bf16 v[10:13], v[164:167], v[208:211], v[10:13]
	v_mfma_f32_16x16x32_bf16 v[10:13], v[168:171], v[212:215], v[10:13]
	v_mfma_f32_16x16x32_bf16 v[2:5], v[172:175], v[208:211], v[2:5]
	v_mfma_f32_16x16x32_bf16 v[2:5], v[176:179], v[212:215], v[2:5]
	s_barrier
	s_add_u32 s4, s4, 0x100
	s_addc_u32 s5, s5, 0
	s_add_u32 s42, s42, 0x100
	s_addc_u32 s43, s43, 0
	s_cmp_ge_i32 s44, s1
	s_mov_b32 s2, s44
	s_cbranch_scc1 .Lkpeel_exit_1
.LBB0_267:
	ds_read_b128 v[148:151], v145
	ds_read_b128 v[152:155], v145 offset:1024
	ds_read_b128 v[156:159], v145 offset:2048
	ds_read_b128 v[160:163], v145 offset:3072
	ds_read_b128 v[164:167], v146
	ds_read_b128 v[168:171], v146 offset:1024
	ds_read_b128 v[172:175], v146 offset:2048
	ds_read_b128 v[176:179], v146 offset:3072
	s_add_i32 s44, s2, 2
	s_add_u32 s3, s4, 0xfff00080
	s_addc_u32 s8, s5, -1
	s_cmp_eq_u32 s41, s2
	s_cselect_b32 s2, s40, s42
	s_cselect_b32 s9, s10, s8
	s_cselect_b32 s8, s33, s3
	s_cselect_b32 s3, s39, s43
	s_add_i32 m0, s16, 0xc000
	ds_read_b128 v[180:183], v147
	ds_read_b128 v[184:187], v147 offset:1024
	ds_read_b128 v[188:191], v147 offset:2048
	ds_read_b128 v[192:195], v147 offset:3072
	ds_read_b128 v[196:199], v147 offset:4096
	ds_read_b128 v[200:203], v147 offset:5120
	ds_read_b128 v[208:211], v147 offset:6144
	ds_read_b128 v[212:215], v147 offset:7168
	global_load_lds_dwordx4 v138, s[4:5]
	s_add_i32 m0, s16, 0xe000
	s_nop 0
	global_load_lds_dwordx4 v140, s[4:5]
	s_waitcnt vmcnt(8)
	s_waitcnt lgkmcnt(0)
	s_barrier
	s_waitcnt lgkmcnt(0)
	v_mfma_f32_16x16x32_bf16 v[122:125], v[148:151], v[180:183], v[122:125]
	v_mfma_f32_16x16x32_bf16 v[122:125], v[152:155], v[184:187], v[122:125]
	v_mfma_f32_16x16x32_bf16 v[118:121], v[156:159], v[180:183], v[118:121]
	v_mfma_f32_16x16x32_bf16 v[118:121], v[160:163], v[184:187], v[118:121]
	v_mfma_f32_16x16x32_bf16 v[110:113], v[148:151], v[188:191], v[110:113]
	v_mfma_f32_16x16x32_bf16 v[110:113], v[152:155], v[192:195], v[110:113]
	v_mfma_f32_16x16x32_bf16 v[102:105], v[156:159], v[188:191], v[102:105]
	v_mfma_f32_16x16x32_bf16 v[102:105], v[160:163], v[192:195], v[102:105]
	v_mfma_f32_16x16x32_bf16 v[94:97], v[148:151], v[196:199], v[94:97]
	v_mfma_f32_16x16x32_bf16 v[94:97], v[152:155], v[200:203], v[94:97]
	v_mfma_f32_16x16x32_bf16 v[86:89], v[156:159], v[196:199], v[86:89]
	v_mfma_f32_16x16x32_bf16 v[86:89], v[160:163], v[200:203], v[86:89]
	v_mfma_f32_16x16x32_bf16 v[78:81], v[148:151], v[208:211], v[78:81]
	v_mfma_f32_16x16x32_bf16 v[78:81], v[152:155], v[212:215], v[78:81]
	v_mfma_f32_16x16x32_bf16 v[70:73], v[156:159], v[208:211], v[70:73]
	v_mfma_f32_16x16x32_bf16 v[70:73], v[160:163], v[212:215], v[70:73]
	v_mfma_f32_16x16x32_bf16 v[126:129], v[164:167], v[180:183], v[126:129]
	v_mfma_f32_16x16x32_bf16 v[126:129], v[168:171], v[184:187], v[126:129]
	v_mfma_f32_16x16x32_bf16 v[114:117], v[172:175], v[180:183], v[114:117]
	v_mfma_f32_16x16x32_bf16 v[114:117], v[176:179], v[184:187], v[114:117]
	v_mfma_f32_16x16x32_bf16 v[106:109], v[164:167], v[188:191], v[106:109]
	v_mfma_f32_16x16x32_bf16 v[106:109], v[168:171], v[192:195], v[106:109]
	v_mfma_f32_16x16x32_bf16 v[98:101], v[172:175], v[188:191], v[98:101]
	v_mfma_f32_16x16x32_bf16 v[98:101], v[176:179], v[192:195], v[98:101]
	v_mfma_f32_16x16x32_bf16 v[90:93], v[164:167], v[196:199], v[90:93]
	v_mfma_f32_16x16x32_bf16 v[90:93], v[168:171], v[200:203], v[90:93]
	v_mfma_f32_16x16x32_bf16 v[82:85], v[172:175], v[196:199], v[82:85]
	v_mfma_f32_16x16x32_bf16 v[82:85], v[176:179], v[200:203], v[82:85]
	v_mfma_f32_16x16x32_bf16 v[74:77], v[164:167], v[208:211], v[74:77]
	v_mfma_f32_16x16x32_bf16 v[74:77], v[168:171], v[212:215], v[74:77]
	v_mfma_f32_16x16x32_bf16 v[66:69], v[172:175], v[208:211], v[66:69]
	v_mfma_f32_16x16x32_bf16 v[66:69], v[176:179], v[212:215], v[66:69]
	s_barrier
	s_add_i32 s45, s36, s13
	s_mov_b32 m0, s45
	ds_read_b128 v[180:183], v147 offset:16384
	ds_read_b128 v[184:187], v147 offset:17408
	ds_read_b128 v[188:191], v147 offset:18432
	ds_read_b128 v[192:195], v147 offset:19456
	ds_read_b128 v[196:199], v147 offset:20480
	ds_read_b128 v[200:203], v147 offset:21504
	ds_read_b128 v[208:211], v147 offset:22528
	ds_read_b128 v[212:215], v147 offset:23552
	global_load_lds_dwordx4 v132, s[2:3]
	s_add_i32 m0, s45, 0x2000
	s_add_u32 s46, s2, 0x100000
	s_addc_u32 s47, s3, 0
	s_add_i32 s45, s37, s13
	global_load_lds_dwordx4 v136, s[2:3]
	s_mov_b32 m0, s45
	v_lshl_add_u64 v[220:221], s[8:9], 0, v[134:135]
	global_load_lds_dwordx4 v132, s[46:47]
	s_add_i32 m0, s45, 0x2000
	s_nop 0
	global_load_lds_dwordx4 v136, s[46:47]
	v_lshl_add_u64 v[218:219], s[8:9], 0, v[130:131]
	s_mov_b32 m0, s16
	s_nop 0
	global_load_lds_dwordx4 v130, s[8:9]
	s_mov_b32 m0, s17
	s_nop 0
	global_load_lds_dwordx4 v134, s[8:9]
	s_waitcnt vmcnt(8)
	s_waitcnt lgkmcnt(0)
	s_barrier
	s_waitcnt lgkmcnt(0)
	v_mfma_f32_16x16x32_bf16 v[62:65], v[148:151], v[180:183], v[62:65]
	v_mfma_f32_16x16x32_bf16 v[62:65], v[152:155], v[184:187], v[62:65]
	v_mfma_f32_16x16x32_bf16 v[54:57], v[156:159], v[180:183], v[54:57]
	v_mfma_f32_16x16x32_bf16 v[54:57], v[160:163], v[184:187], v[54:57]
	v_mfma_f32_16x16x32_bf16 v[46:49], v[148:151], v[188:191], v[46:49]
	v_mfma_f32_16x16x32_bf16 v[46:49], v[152:155], v[192:195], v[46:49]
	v_mfma_f32_16x16x32_bf16 v[38:41], v[156:159], v[188:191], v[38:41]
	v_mfma_f32_16x16x32_bf16 v[38:41], v[160:163], v[192:195], v[38:41]
	v_mfma_f32_16x16x32_bf16 v[30:33], v[148:151], v[196:199], v[30:33]
	v_mfma_f32_16x16x32_bf16 v[30:33], v[152:155], v[200:203], v[30:33]
	v_mfma_f32_16x16x32_bf16 v[22:25], v[156:159], v[196:199], v[22:25]
	v_mfma_f32_16x16x32_bf16 v[22:25], v[160:163], v[200:203], v[22:25]
	v_mfma_f32_16x16x32_bf16 v[14:17], v[148:151], v[208:211], v[14:17]
	v_mfma_f32_16x16x32_bf16 v[14:17], v[152:155], v[212:215], v[14:17]
	v_mfma_f32_16x16x32_bf16 v[6:9], v[156:159], v[208:211], v[6:9]
	v_mfma_f32_16x16x32_bf16 v[6:9], v[160:163], v[212:215], v[6:9]
	v_mfma_f32_16x16x32_bf16 v[58:61], v[164:167], v[180:183], v[58:61]
	v_mfma_f32_16x16x32_bf16 v[58:61], v[168:171], v[184:187], v[58:61]
	v_mfma_f32_16x16x32_bf16 v[50:53], v[172:175], v[180:183], v[50:53]
	v_mfma_f32_16x16x32_bf16 v[50:53], v[176:179], v[184:187], v[50:53]
	v_mfma_f32_16x16x32_bf16 v[42:45], v[164:167], v[188:191], v[42:45]
	v_mfma_f32_16x16x32_bf16 v[42:45], v[168:171], v[192:195], v[42:45]
	v_mfma_f32_16x16x32_bf16 v[34:37], v[172:175], v[188:191], v[34:37]
	v_mfma_f32_16x16x32_bf16 v[34:37], v[176:179], v[192:195], v[34:37]
	v_mfma_f32_16x16x32_bf16 v[26:29], v[164:167], v[196:199], v[26:29]
	v_mfma_f32_16x16x32_bf16 v[26:29], v[168:171], v[200:203], v[26:29]
	v_mfma_f32_16x16x32_bf16 v[18:21], v[172:175], v[196:199], v[18:21]
	v_mfma_f32_16x16x32_bf16 v[18:21], v[176:179], v[200:203], v[18:21]
	v_mfma_f32_16x16x32_bf16 v[10:13], v[164:167], v[208:211], v[10:13]
	v_mfma_f32_16x16x32_bf16 v[10:13], v[168:171], v[212:215], v[10:13]
	v_mfma_f32_16x16x32_bf16 v[2:5], v[172:175], v[208:211], v[2:5]
	v_mfma_f32_16x16x32_bf16 v[2:5], v[176:179], v[212:215], v[2:5]
	s_barrier
	s_add_i32 s45, 0, 0x18000
	s_add_i32 s46, 0, 0x1c000
	v_add_u32_e32 v160, s45, v1
	v_add_u32_e32 v176, s46, v1
	ds_read_b128 v[148:151], v160
	ds_read_b128 v[152:155], v160 offset:1024
	ds_read_b128 v[156:159], v160 offset:2048
	ds_read_b128 v[160:163], v160 offset:3072
	ds_read_b128 v[164:167], v176
	ds_read_b128 v[168:171], v176 offset:1024
	ds_read_b128 v[172:175], v176 offset:2048
	ds_read_b128 v[176:179], v176 offset:3072
	s_add_u32 s8, s8, 0x100000
	s_addc_u32 s9, s9, 0
	s_mov_b32 m0, s18
	ds_read_b128 v[180:183], v147 offset:32768
	ds_read_b128 v[184:187], v147 offset:33792
	ds_read_b128 v[188:191], v147 offset:34816
	ds_read_b128 v[192:195], v147 offset:35840
	ds_read_b128 v[196:199], v147 offset:36864
	ds_read_b128 v[200:203], v147 offset:37888
	ds_read_b128 v[208:211], v147 offset:38912
	ds_read_b128 v[212:215], v147 offset:39936
	global_load_lds_dwordx4 v130, s[8:9]
	s_mov_b32 m0, s19
	s_nop 0
	global_load_lds_dwordx4 v134, s[8:9]
	s_waitcnt vmcnt(8)
	s_waitcnt lgkmcnt(0)
	s_barrier
	s_waitcnt lgkmcnt(0)
	v_mfma_f32_16x16x32_bf16 v[122:125], v[148:151], v[180:183], v[122:125]
	v_mfma_f32_16x16x32_bf16 v[122:125], v[152:155], v[184:187], v[122:125]
	v_mfma_f32_16x16x32_bf16 v[118:121], v[156:159], v[180:183], v[118:121]
	v_mfma_f32_16x16x32_bf16 v[118:121], v[160:163], v[184:187], v[118:121]
	v_mfma_f32_16x16x32_bf16 v[110:113], v[148:151], v[188:191], v[110:113]
	v_mfma_f32_16x16x32_bf16 v[110:113], v[152:155], v[192:195], v[110:113]
	v_mfma_f32_16x16x32_bf16 v[102:105], v[156:159], v[188:191], v[102:105]
	v_mfma_f32_16x16x32_bf16 v[102:105], v[160:163], v[192:195], v[102:105]
	v_mfma_f32_16x16x32_bf16 v[94:97], v[148:151], v[196:199], v[94:97]
	v_mfma_f32_16x16x32_bf16 v[94:97], v[152:155], v[200:203], v[94:97]
	v_mfma_f32_16x16x32_bf16 v[86:89], v[156:159], v[196:199], v[86:89]
	v_mfma_f32_16x16x32_bf16 v[86:89], v[160:163], v[200:203], v[86:89]
	v_mfma_f32_16x16x32_bf16 v[78:81], v[148:151], v[208:211], v[78:81]
	v_mfma_f32_16x16x32_bf16 v[78:81], v[152:155], v[212:215], v[78:81]
	v_mfma_f32_16x16x32_bf16 v[70:73], v[156:159], v[208:211], v[70:73]
	v_mfma_f32_16x16x32_bf16 v[70:73], v[160:163], v[212:215], v[70:73]
	v_mfma_f32_16x16x32_bf16 v[126:129], v[164:167], v[180:183], v[126:129]
	v_mfma_f32_16x16x32_bf16 v[126:129], v[168:171], v[184:187], v[126:129]
	v_mfma_f32_16x16x32_bf16 v[114:117], v[172:175], v[180:183], v[114:117]
	v_mfma_f32_16x16x32_bf16 v[114:117], v[176:179], v[184:187], v[114:117]
	v_mfma_f32_16x16x32_bf16 v[106:109], v[164:167], v[188:191], v[106:109]
	v_mfma_f32_16x16x32_bf16 v[106:109], v[168:171], v[192:195], v[106:109]
	v_mfma_f32_16x16x32_bf16 v[98:101], v[172:175], v[188:191], v[98:101]
	v_mfma_f32_16x16x32_bf16 v[98:101], v[176:179], v[192:195], v[98:101]
	v_mfma_f32_16x16x32_bf16 v[90:93], v[164:167], v[196:199], v[90:93]
	v_mfma_f32_16x16x32_bf16 v[90:93], v[168:171], v[200:203], v[90:93]
	v_mfma_f32_16x16x32_bf16 v[82:85], v[172:175], v[196:199], v[82:85]
	v_mfma_f32_16x16x32_bf16 v[82:85], v[176:179], v[200:203], v[82:85]
	v_mfma_f32_16x16x32_bf16 v[74:77], v[164:167], v[208:211], v[74:77]
	v_mfma_f32_16x16x32_bf16 v[74:77], v[168:171], v[212:215], v[74:77]
	v_mfma_f32_16x16x32_bf16 v[66:69], v[172:175], v[208:211], v[66:69]
	v_mfma_f32_16x16x32_bf16 v[66:69], v[176:179], v[212:215], v[66:69]
	s_barrier
	s_add_i32 s8, s45, s13
	s_add_u32 s98, s2, s24
	s_addc_u32 s99, s3, s25
	s_mov_b32 m0, s8
	ds_read_b128 v[180:183], v147 offset:49152
	ds_read_b128 v[184:187], v147 offset:50176
	ds_read_b128 v[188:191], v147 offset:51200
	ds_read_b128 v[192:195], v147 offset:52224
	ds_read_b128 v[196:199], v147 offset:53248
	ds_read_b128 v[200:203], v147 offset:54272
	ds_read_b128 v[208:211], v147 offset:55296
	ds_read_b128 v[212:215], v147 offset:56320
	global_load_lds_dwordx4 v132, s[98:99]
	s_add_i32 m0, s8, 0x2000
	s_add_u32 s2, s2, 0x100080
	s_addc_u32 s3, s3, 0
	s_add_i32 s8, s46, s13
	global_load_lds_dwordx4 v136, s[98:99]
	s_mov_b32 m0, s8
	s_nop 0
	global_load_lds_dwordx4 v132, s[2:3]
	s_add_i32 m0, s8, 0x2000
	s_nop 0
	global_load_lds_dwordx4 v136, s[2:3]
	v_lshl_add_u64 v[204:205], v[218:219], 0, s[24:25]
	s_mov_b32 m0, s29
	s_nop 0
	global_load_lds_dwordx4 v[204:205], off
	v_lshl_add_u64 v[204:205], v[220:221], 0, s[24:25]
	s_mov_b32 m0, s34
	s_nop 0
	global_load_lds_dwordx4 v[204:205], off
	s_waitcnt vmcnt(8)
	s_waitcnt lgkmcnt(0)
	s_barrier
	s_waitcnt lgkmcnt(0)
	v_mfma_f32_16x16x32_bf16 v[62:65], v[148:151], v[180:183], v[62:65]
	v_mfma_f32_16x16x32_bf16 v[62:65], v[152:155], v[184:187], v[62:65]
	v_mfma_f32_16x16x32_bf16 v[54:57], v[156:159], v[180:183], v[54:57]
	v_mfma_f32_16x16x32_bf16 v[54:57], v[160:163], v[184:187], v[54:57]
	v_mfma_f32_16x16x32_bf16 v[46:49], v[148:151], v[188:191], v[46:49]
	v_mfma_f32_16x16x32_bf16 v[46:49], v[152:155], v[192:195], v[46:49]
	v_mfma_f32_16x16x32_bf16 v[38:41], v[156:159], v[188:191], v[38:41]
	v_mfma_f32_16x16x32_bf16 v[38:41], v[160:163], v[192:195], v[38:41]
	v_mfma_f32_16x16x32_bf16 v[30:33], v[148:151], v[196:199], v[30:33]
	v_mfma_f32_16x16x32_bf16 v[30:33], v[152:155], v[200:203], v[30:33]
	v_mfma_f32_16x16x32_bf16 v[22:25], v[156:159], v[196:199], v[22:25]
	v_mfma_f32_16x16x32_bf16 v[22:25], v[160:163], v[200:203], v[22:25]
	v_mfma_f32_16x16x32_bf16 v[14:17], v[148:151], v[208:211], v[14:17]
	v_mfma_f32_16x16x32_bf16 v[14:17], v[152:155], v[212:215], v[14:17]
	v_mfma_f32_16x16x32_bf16 v[6:9], v[156:159], v[208:211], v[6:9]
	v_mfma_f32_16x16x32_bf16 v[6:9], v[160:163], v[212:215], v[6:9]
	v_mfma_f32_16x16x32_bf16 v[58:61], v[164:167], v[180:183], v[58:61]
	v_mfma_f32_16x16x32_bf16 v[58:61], v[168:171], v[184:187], v[58:61]
	v_mfma_f32_16x16x32_bf16 v[50:53], v[172:175], v[180:183], v[50:53]
	v_mfma_f32_16x16x32_bf16 v[50:53], v[176:179], v[184:187], v[50:53]
	v_mfma_f32_16x16x32_bf16 v[42:45], v[164:167], v[188:191], v[42:45]
	v_mfma_f32_16x16x32_bf16 v[42:45], v[168:171], v[192:195], v[42:45]
	v_mfma_f32_16x16x32_bf16 v[34:37], v[172:175], v[188:191], v[34:37]
	v_mfma_f32_16x16x32_bf16 v[34:37], v[176:179], v[192:195], v[34:37]
	v_mfma_f32_16x16x32_bf16 v[26:29], v[164:167], v[196:199], v[26:29]
	v_mfma_f32_16x16x32_bf16 v[26:29], v[168:171], v[200:203], v[26:29]
	v_mfma_f32_16x16x32_bf16 v[18:21], v[172:175], v[196:199], v[18:21]
	v_mfma_f32_16x16x32_bf16 v[18:21], v[176:179], v[200:203], v[18:21]
	v_mfma_f32_16x16x32_bf16 v[10:13], v[164:167], v[208:211], v[10:13]
	v_mfma_f32_16x16x32_bf16 v[10:13], v[168:171], v[212:215], v[10:13]
	v_mfma_f32_16x16x32_bf16 v[2:5], v[172:175], v[208:211], v[2:5]
	v_mfma_f32_16x16x32_bf16 v[2:5], v[176:179], v[212:215], v[2:5]
	s_barrier
	s_add_u32 s4, s4, 0x100
	s_addc_u32 s5, s5, 0
	s_add_u32 s42, s42, 0x100
	s_addc_u32 s43, s43, 0
	s_cmp_ge_i32 s44, s1
	s_mov_b32 s2, s44
	s_cbranch_scc0 .LBB0_267

.LBB0_524:
	s_lshl_b32 s0, s26, 20
	s_and_b32 s0, s0, 0xff00000
	s_add_u32 s0, s70, s0
	s_addc_u32 s23, s71, 0
	s_lshr_b32 s22, s26, 13
	s_and_b32 s24, s22, 0x7ff80
	s_add_u32 s22, s0, s24
	s_addc_u32 s23, s23, 0
	s_lshl_b32 s0, s26, 12
	s_and_b32 s0, s0, 0xff00000
	s_add_u32 s0, s30, s0
	s_addc_u32 s25, s31, 0
	s_add_u32 s24, s0, s24
	s_addc_u32 s25, s25, 0
	s_cmp_lt_i32 s37, 1
	v_cmp_gt_i64_e64 s[26:27], s[26:27], -1
	s_cbranch_scc1 .LBB0_546
	s_and_b64 s[40:41], s[26:27], exec
	s_cselect_b32 s0, s23, s39
	s_cselect_b32 s36, s22, s38
	s_cselect_b32 s65, s25, s3
	s_cselect_b32 s66, s24, s2
	s_add_i32 s67, s37, -2
	s_add_u32 s38, s38, 0x80080
	s_addc_u32 s39, s39, 0
	s_add_u32 s68, s2, 0x100
	s_addc_u32 s69, s3, 0
	s_mov_b32 s2, 0
	ds_read_b128 v[148:151], v144
	ds_read_b128 v[152:155], v144 offset:1024
	ds_read_b128 v[156:159], v144 offset:2048
	ds_read_b128 v[160:163], v144 offset:3072
	ds_read_b128 v[164:167], v145
	ds_read_b128 v[168:171], v145 offset:1024
	ds_read_b128 v[172:175], v145 offset:2048
	ds_read_b128 v[176:179], v145 offset:3072
	s_waitcnt lgkmcnt(0)
	s_add_i32 s72, s2, 2
	s_add_u32 s3, s38, 0xfff80080
	s_addc_u32 s40, s39, -1
	s_cmp_eq_u32 s67, s2
	s_cselect_b32 s2, s66, s68
	s_cselect_b32 s41, s0, s40
	s_cselect_b32 s40, s36, s3
	s_cselect_b32 s3, s65, s69
	s_add_i32 m0, s29, 0xc000
	ds_read_b128 v[180:183], v146
	ds_read_b128 v[184:187], v146 offset:1024
	ds_read_b128 v[188:191], v146 offset:2048
	ds_read_b128 v[192:195], v146 offset:3072
	ds_read_b128 v[196:199], v146 offset:4096
	ds_read_b128 v[200:203], v146 offset:5120
	ds_read_b128 v[208:211], v146 offset:6144
	ds_read_b128 v[212:215], v146 offset:7168
	global_load_lds_dwordx4 v138, s[38:39]
	s_add_i32 m0, s29, 0xe000
	s_nop 0
	global_load_lds_dwordx4 v140, s[38:39]
	s_waitcnt vmcnt(8)
	s_waitcnt lgkmcnt(0)
	s_barrier
	s_waitcnt lgkmcnt(0)
	v_mfma_f32_16x16x32_bf16 v[126:129], v[148:151], v[180:183], 0
	v_mfma_f32_16x16x32_bf16 v[126:129], v[152:155], v[184:187], v[126:129]
	v_mfma_f32_16x16x32_bf16 v[122:125], v[156:159], v[180:183], 0
	v_mfma_f32_16x16x32_bf16 v[122:125], v[160:163], v[184:187], v[122:125]
	v_mfma_f32_16x16x32_bf16 v[110:113], v[148:151], v[188:191], 0
	v_mfma_f32_16x16x32_bf16 v[110:113], v[152:155], v[192:195], v[110:113]
	v_mfma_f32_16x16x32_bf16 v[102:105], v[156:159], v[188:191], 0
	v_mfma_f32_16x16x32_bf16 v[102:105], v[160:163], v[192:195], v[102:105]
	v_mfma_f32_16x16x32_bf16 v[94:97], v[148:151], v[196:199], 0
	v_mfma_f32_16x16x32_bf16 v[94:97], v[152:155], v[200:203], v[94:97]
	v_mfma_f32_16x16x32_bf16 v[86:89], v[156:159], v[196:199], 0
	v_mfma_f32_16x16x32_bf16 v[86:89], v[160:163], v[200:203], v[86:89]
	v_mfma_f32_16x16x32_bf16 v[78:81], v[148:151], v[208:211], 0
	v_mfma_f32_16x16x32_bf16 v[78:81], v[152:155], v[212:215], v[78:81]
	v_mfma_f32_16x16x32_bf16 v[70:73], v[156:159], v[208:211], 0
	v_mfma_f32_16x16x32_bf16 v[70:73], v[160:163], v[212:215], v[70:73]
	v_mfma_f32_16x16x32_bf16 v[118:121], v[164:167], v[180:183], 0
	v_mfma_f32_16x16x32_bf16 v[118:121], v[168:171], v[184:187], v[118:121]
	v_mfma_f32_16x16x32_bf16 v[114:117], v[172:175], v[180:183], 0
	v_mfma_f32_16x16x32_bf16 v[114:117], v[176:179], v[184:187], v[114:117]
	v_mfma_f32_16x16x32_bf16 v[106:109], v[164:167], v[188:191], 0
	v_mfma_f32_16x16x32_bf16 v[106:109], v[168:171], v[192:195], v[106:109]
	v_mfma_f32_16x16x32_bf16 v[98:101], v[172:175], v[188:191], 0
	v_mfma_f32_16x16x32_bf16 v[98:101], v[176:179], v[192:195], v[98:101]
	v_mfma_f32_16x16x32_bf16 v[90:93], v[164:167], v[196:199], 0
	v_mfma_f32_16x16x32_bf16 v[90:93], v[168:171], v[200:203], v[90:93]
	v_mfma_f32_16x16x32_bf16 v[82:85], v[172:175], v[196:199], 0
	v_mfma_f32_16x16x32_bf16 v[82:85], v[176:179], v[200:203], v[82:85]
	v_mfma_f32_16x16x32_bf16 v[74:77], v[164:167], v[208:211], 0
	v_mfma_f32_16x16x32_bf16 v[74:77], v[168:171], v[212:215], v[74:77]
	v_mfma_f32_16x16x32_bf16 v[66:69], v[172:175], v[208:211], 0
	v_mfma_f32_16x16x32_bf16 v[66:69], v[176:179], v[212:215], v[66:69]
	s_barrier
	s_add_i32 s73, s52, s33
	s_mov_b32 m0, s73
	ds_read_b128 v[180:183], v146 offset:16384
	ds_read_b128 v[184:187], v146 offset:17408
	ds_read_b128 v[188:191], v146 offset:18432
	ds_read_b128 v[192:195], v146 offset:19456
	ds_read_b128 v[196:199], v146 offset:20480
	ds_read_b128 v[200:203], v146 offset:21504
	ds_read_b128 v[208:211], v146 offset:22528
	ds_read_b128 v[212:215], v146 offset:23552
	global_load_lds_dwordx4 v132, s[2:3]
	s_add_i32 m0, s73, 0x2000
	s_add_u32 s74, s2, 0x80000
	s_addc_u32 s75, s3, 0
	s_add_i32 s73, s53, s33
	global_load_lds_dwordx4 v136, s[2:3]
	s_mov_b32 m0, s73
	v_lshl_add_u64 v[220:221], s[40:41], 0, v[134:135]
	global_load_lds_dwordx4 v132, s[74:75]
	s_add_i32 m0, s73, 0x2000
	s_nop 0
	global_load_lds_dwordx4 v136, s[74:75]
	v_lshl_add_u64 v[218:219], s[40:41], 0, v[130:131]
	s_mov_b32 m0, s29
	s_nop 0
	global_load_lds_dwordx4 v130, s[40:41]
	s_mov_b32 m0, s35
	s_nop 0
	global_load_lds_dwordx4 v134, s[40:41]
	s_waitcnt vmcnt(8)
	s_waitcnt lgkmcnt(0)
	s_barrier
	s_waitcnt lgkmcnt(0)
	v_mfma_f32_16x16x32_bf16 v[62:65], v[148:151], v[180:183], 0
	v_mfma_f32_16x16x32_bf16 v[62:65], v[152:155], v[184:187], v[62:65]
	v_mfma_f32_16x16x32_bf16 v[54:57], v[156:159], v[180:183], 0
	v_mfma_f32_16x16x32_bf16 v[54:57], v[160:163], v[184:187], v[54:57]
	v_mfma_f32_16x16x32_bf16 v[46:49], v[148:151], v[188:191], 0
	v_mfma_f32_16x16x32_bf16 v[46:49], v[152:155], v[192:195], v[46:49]
	v_mfma_f32_16x16x32_bf16 v[38:41], v[156:159], v[188:191], 0
	v_mfma_f32_16x16x32_bf16 v[38:41], v[160:163], v[192:195], v[38:41]
	v_mfma_f32_16x16x32_bf16 v[30:33], v[148:151], v[196:199], 0
	v_mfma_f32_16x16x32_bf16 v[30:33], v[152:155], v[200:203], v[30:33]
	v_mfma_f32_16x16x32_bf16 v[22:25], v[156:159], v[196:199], 0
	v_mfma_f32_16x16x32_bf16 v[22:25], v[160:163], v[200:203], v[22:25]
	v_mfma_f32_16x16x32_bf16 v[14:17], v[148:151], v[208:211], 0
	v_mfma_f32_16x16x32_bf16 v[14:17], v[152:155], v[212:215], v[14:17]
	v_mfma_f32_16x16x32_bf16 v[6:9], v[156:159], v[208:211], 0
	v_mfma_f32_16x16x32_bf16 v[6:9], v[160:163], v[212:215], v[6:9]
	v_mfma_f32_16x16x32_bf16 v[58:61], v[164:167], v[180:183], 0
	v_mfma_f32_16x16x32_bf16 v[58:61], v[168:171], v[184:187], v[58:61]
	v_mfma_f32_16x16x32_bf16 v[50:53], v[172:175], v[180:183], 0
	v_mfma_f32_16x16x32_bf16 v[50:53], v[176:179], v[184:187], v[50:53]
	v_mfma_f32_16x16x32_bf16 v[42:45], v[164:167], v[188:191], 0
	v_mfma_f32_16x16x32_bf16 v[42:45], v[168:171], v[192:195], v[42:45]
	v_mfma_f32_16x16x32_bf16 v[34:37], v[172:175], v[188:191], 0
	v_mfma_f32_16x16x32_bf16 v[34:37], v[176:179], v[192:195], v[34:37]
	v_mfma_f32_16x16x32_bf16 v[26:29], v[164:167], v[196:199], 0
	v_mfma_f32_16x16x32_bf16 v[26:29], v[168:171], v[200:203], v[26:29]
	v_mfma_f32_16x16x32_bf16 v[18:21], v[172:175], v[196:199], 0
	v_mfma_f32_16x16x32_bf16 v[18:21], v[176:179], v[200:203], v[18:21]
	v_mfma_f32_16x16x32_bf16 v[10:13], v[164:167], v[208:211], 0
	v_mfma_f32_16x16x32_bf16 v[10:13], v[168:171], v[212:215], v[10:13]
	v_mfma_f32_16x16x32_bf16 v[2:5], v[172:175], v[208:211], 0
	v_mfma_f32_16x16x32_bf16 v[2:5], v[176:179], v[212:215], v[2:5]
	s_barrier
	s_add_i32 s73, 0, 0x18000
	v_add_u32_e32 v147, s73, v142
	s_add_i32 s74, 0, 0x1c000
	ds_read_b128 v[148:151], v147
	ds_read_b128 v[152:155], v147 offset:1024
	ds_read_b128 v[156:159], v147 offset:2048
	ds_read_b128 v[160:163], v147 offset:3072
	v_add_u32_e32 v147, s74, v142
	ds_read_b128 v[164:167], v147
	ds_read_b128 v[168:171], v147 offset:1024
	ds_read_b128 v[172:175], v147 offset:2048
	ds_read_b128 v[176:179], v147 offset:3072
	s_add_u32 s40, s40, 0x80000
	s_addc_u32 s41, s41, 0
	s_mov_b32 m0, s43
	ds_read_b128 v[180:183], v146 offset:32768
	ds_read_b128 v[184:187], v146 offset:33792
	ds_read_b128 v[188:191], v146 offset:34816
	ds_read_b128 v[192:195], v146 offset:35840
	ds_read_b128 v[196:199], v146 offset:36864
	ds_read_b128 v[200:203], v146 offset:37888
	ds_read_b128 v[208:211], v146 offset:38912
	ds_read_b128 v[212:215], v146 offset:39936
	global_load_lds_dwordx4 v130, s[40:41]
	s_mov_b32 m0, s44
	s_nop 0
	global_load_lds_dwordx4 v134, s[40:41]
	s_waitcnt vmcnt(8)
	s_waitcnt lgkmcnt(0)
	s_barrier
	s_waitcnt lgkmcnt(0)
	v_mfma_f32_16x16x32_bf16 v[126:129], v[148:151], v[180:183], v[126:129]
	v_mfma_f32_16x16x32_bf16 v[126:129], v[152:155], v[184:187], v[126:129]
	v_mfma_f32_16x16x32_bf16 v[122:125], v[156:159], v[180:183], v[122:125]
	v_mfma_f32_16x16x32_bf16 v[122:125], v[160:163], v[184:187], v[122:125]
	v_mfma_f32_16x16x32_bf16 v[110:113], v[148:151], v[188:191], v[110:113]
	v_mfma_f32_16x16x32_bf16 v[110:113], v[152:155], v[192:195], v[110:113]
	v_mfma_f32_16x16x32_bf16 v[102:105], v[156:159], v[188:191], v[102:105]
	v_mfma_f32_16x16x32_bf16 v[102:105], v[160:163], v[192:195], v[102:105]
	v_mfma_f32_16x16x32_bf16 v[94:97], v[148:151], v[196:199], v[94:97]
	v_mfma_f32_16x16x32_bf16 v[94:97], v[152:155], v[200:203], v[94:97]
	v_mfma_f32_16x16x32_bf16 v[86:89], v[156:159], v[196:199], v[86:89]
	v_mfma_f32_16x16x32_bf16 v[86:89], v[160:163], v[200:203], v[86:89]
	v_mfma_f32_16x16x32_bf16 v[78:81], v[148:151], v[208:211], v[78:81]
	v_mfma_f32_16x16x32_bf16 v[78:81], v[152:155], v[212:215], v[78:81]
	v_mfma_f32_16x16x32_bf16 v[70:73], v[156:159], v[208:211], v[70:73]
	v_mfma_f32_16x16x32_bf16 v[70:73], v[160:163], v[212:215], v[70:73]
	v_mfma_f32_16x16x32_bf16 v[118:121], v[164:167], v[180:183], v[118:121]
	v_mfma_f32_16x16x32_bf16 v[118:121], v[168:171], v[184:187], v[118:121]
	v_mfma_f32_16x16x32_bf16 v[114:117], v[172:175], v[180:183], v[114:117]
	v_mfma_f32_16x16x32_bf16 v[114:117], v[176:179], v[184:187], v[114:117]
	v_mfma_f32_16x16x32_bf16 v[106:109], v[164:167], v[188:191], v[106:109]
	v_mfma_f32_16x16x32_bf16 v[106:109], v[168:171], v[192:195], v[106:109]
	v_mfma_f32_16x16x32_bf16 v[98:101], v[172:175], v[188:191], v[98:101]
	v_mfma_f32_16x16x32_bf16 v[98:101], v[176:179], v[192:195], v[98:101]
	v_mfma_f32_16x16x32_bf16 v[90:93], v[164:167], v[196:199], v[90:93]
	v_mfma_f32_16x16x32_bf16 v[90:93], v[168:171], v[200:203], v[90:93]
	v_mfma_f32_16x16x32_bf16 v[82:85], v[172:175], v[196:199], v[82:85]
	v_mfma_f32_16x16x32_bf16 v[82:85], v[176:179], v[200:203], v[82:85]
	v_mfma_f32_16x16x32_bf16 v[74:77], v[164:167], v[208:211], v[74:77]
	v_mfma_f32_16x16x32_bf16 v[74:77], v[168:171], v[212:215], v[74:77]
	v_mfma_f32_16x16x32_bf16 v[66:69], v[172:175], v[208:211], v[66:69]
	v_mfma_f32_16x16x32_bf16 v[66:69], v[176:179], v[212:215], v[66:69]
	s_barrier
	s_add_i32 s40, s73, s33
	s_add_u32 s98, s2, s16
	s_addc_u32 s99, s3, s17
	s_mov_b32 m0, s40
	ds_read_b128 v[180:183], v146 offset:49152
	ds_read_b128 v[184:187], v146 offset:50176
	ds_read_b128 v[188:191], v146 offset:51200
	ds_read_b128 v[192:195], v146 offset:52224
	ds_read_b128 v[196:199], v146 offset:53248
	ds_read_b128 v[200:203], v146 offset:54272
	ds_read_b128 v[208:211], v146 offset:55296
	ds_read_b128 v[212:215], v146 offset:56320
	global_load_lds_dwordx4 v132, s[98:99]
	s_add_i32 m0, s40, 0x2000
	s_add_u32 s2, s2, 0x80080
	s_addc_u32 s3, s3, 0
	s_add_i32 s40, s74, s33
	global_load_lds_dwordx4 v136, s[98:99]
	s_mov_b32 m0, s40
	s_nop 0
	global_load_lds_dwordx4 v132, s[2:3]
	s_add_i32 m0, s40, 0x2000
	s_nop 0
	global_load_lds_dwordx4 v136, s[2:3]
	v_lshl_add_u64 v[204:205], v[218:219], 0, s[16:17]
	s_mov_b32 m0, s46
	s_nop 0
	global_load_lds_dwordx4 v[204:205], off
	v_lshl_add_u64 v[204:205], v[220:221], 0, s[16:17]
	s_mov_b32 m0, s47
	s_nop 0
	global_load_lds_dwordx4 v[204:205], off
	s_waitcnt vmcnt(8)
	s_waitcnt lgkmcnt(0)
	s_barrier
	s_waitcnt lgkmcnt(0)
	v_mfma_f32_16x16x32_bf16 v[62:65], v[148:151], v[180:183], v[62:65]
	v_mfma_f32_16x16x32_bf16 v[62:65], v[152:155], v[184:187], v[62:65]
	v_mfma_f32_16x16x32_bf16 v[54:57], v[156:159], v[180:183], v[54:57]
	v_mfma_f32_16x16x32_bf16 v[54:57], v[160:163], v[184:187], v[54:57]
	v_mfma_f32_16x16x32_bf16 v[46:49], v[148:151], v[188:191], v[46:49]
	v_mfma_f32_16x16x32_bf16 v[46:49], v[152:155], v[192:195], v[46:49]
	v_mfma_f32_16x16x32_bf16 v[38:41], v[156:159], v[188:191], v[38:41]
	v_mfma_f32_16x16x32_bf16 v[38:41], v[160:163], v[192:195], v[38:41]
	v_mfma_f32_16x16x32_bf16 v[30:33], v[148:151], v[196:199], v[30:33]
	v_mfma_f32_16x16x32_bf16 v[30:33], v[152:155], v[200:203], v[30:33]
	v_mfma_f32_16x16x32_bf16 v[22:25], v[156:159], v[196:199], v[22:25]
	v_mfma_f32_16x16x32_bf16 v[22:25], v[160:163], v[200:203], v[22:25]
	v_mfma_f32_16x16x32_bf16 v[14:17], v[148:151], v[208:211], v[14:17]
	v_mfma_f32_16x16x32_bf16 v[14:17], v[152:155], v[212:215], v[14:17]
	v_mfma_f32_16x16x32_bf16 v[6:9], v[156:159], v[208:211], v[6:9]
	v_mfma_f32_16x16x32_bf16 v[6:9], v[160:163], v[212:215], v[6:9]
	v_mfma_f32_16x16x32_bf16 v[58:61], v[164:167], v[180:183], v[58:61]
	v_mfma_f32_16x16x32_bf16 v[58:61], v[168:171], v[184:187], v[58:61]
	v_mfma_f32_16x16x32_bf16 v[50:53], v[172:175], v[180:183], v[50:53]
	v_mfma_f32_16x16x32_bf16 v[50:53], v[176:179], v[184:187], v[50:53]
	v_mfma_f32_16x16x32_bf16 v[42:45], v[164:167], v[188:191], v[42:45]
	v_mfma_f32_16x16x32_bf16 v[42:45], v[168:171], v[192:195], v[42:45]
	v_mfma_f32_16x16x32_bf16 v[34:37], v[172:175], v[188:191], v[34:37]
	v_mfma_f32_16x16x32_bf16 v[34:37], v[176:179], v[192:195], v[34:37]
	v_mfma_f32_16x16x32_bf16 v[26:29], v[164:167], v[196:199], v[26:29]
	v_mfma_f32_16x16x32_bf16 v[26:29], v[168:171], v[200:203], v[26:29]
	v_mfma_f32_16x16x32_bf16 v[18:21], v[172:175], v[196:199], v[18:21]
	v_mfma_f32_16x16x32_bf16 v[18:21], v[176:179], v[200:203], v[18:21]
	v_mfma_f32_16x16x32_bf16 v[10:13], v[164:167], v[208:211], v[10:13]
	v_mfma_f32_16x16x32_bf16 v[10:13], v[168:171], v[212:215], v[10:13]
	v_mfma_f32_16x16x32_bf16 v[2:5], v[172:175], v[208:211], v[2:5]
	v_mfma_f32_16x16x32_bf16 v[2:5], v[176:179], v[212:215], v[2:5]
	s_barrier
	s_add_u32 s38, s38, 0x100
	s_addc_u32 s39, s39, 0
	s_add_u32 s68, s68, 0x100
	s_addc_u32 s69, s69, 0
	s_cmp_ge_i32 s72, s37
	s_mov_b32 s2, s72
	s_cbranch_scc1 .Lkpeel_exit_2
.LBB0_526:
	ds_read_b128 v[148:151], v144
	ds_read_b128 v[152:155], v144 offset:1024
	ds_read_b128 v[156:159], v144 offset:2048
	ds_read_b128 v[160:163], v144 offset:3072
	ds_read_b128 v[164:167], v145
	ds_read_b128 v[168:171], v145 offset:1024
	ds_read_b128 v[172:175], v145 offset:2048
	ds_read_b128 v[176:179], v145 offset:3072
	s_waitcnt lgkmcnt(0)
	s_add_i32 s72, s2, 2
	s_add_u32 s3, s38, 0xfff80080
	s_addc_u32 s40, s39, -1
	s_cmp_eq_u32 s67, s2
	s_cselect_b32 s2, s66, s68
	s_cselect_b32 s41, s0, s40
	s_cselect_b32 s40, s36, s3
	s_cselect_b32 s3, s65, s69
	s_add_i32 m0, s29, 0xc000
	ds_read_b128 v[180:183], v146
	ds_read_b128 v[184:187], v146 offset:1024
	ds_read_b128 v[188:191], v146 offset:2048
	ds_read_b128 v[192:195], v146 offset:3072
	ds_read_b128 v[196:199], v146 offset:4096
	ds_read_b128 v[200:203], v146 offset:5120
	ds_read_b128 v[208:211], v146 offset:6144
	ds_read_b128 v[212:215], v146 offset:7168
	global_load_lds_dwordx4 v138, s[38:39]
	s_add_i32 m0, s29, 0xe000
	s_nop 0
	global_load_lds_dwordx4 v140, s[38:39]
	s_waitcnt vmcnt(8)
	s_waitcnt lgkmcnt(0)
	s_barrier
	s_waitcnt lgkmcnt(0)
	v_mfma_f32_16x16x32_bf16 v[126:129], v[148:151], v[180:183], v[126:129]
	v_mfma_f32_16x16x32_bf16 v[126:129], v[152:155], v[184:187], v[126:129]
	v_mfma_f32_16x16x32_bf16 v[122:125], v[156:159], v[180:183], v[122:125]
	v_mfma_f32_16x16x32_bf16 v[122:125], v[160:163], v[184:187], v[122:125]
	v_mfma_f32_16x16x32_bf16 v[110:113], v[148:151], v[188:191], v[110:113]
	v_mfma_f32_16x16x32_bf16 v[110:113], v[152:155], v[192:195], v[110:113]
	v_mfma_f32_16x16x32_bf16 v[102:105], v[156:159], v[188:191], v[102:105]
	v_mfma_f32_16x16x32_bf16 v[102:105], v[160:163], v[192:195], v[102:105]
	v_mfma_f32_16x16x32_bf16 v[94:97], v[148:151], v[196:199], v[94:97]
	v_mfma_f32_16x16x32_bf16 v[94:97], v[152:155], v[200:203], v[94:97]
	v_mfma_f32_16x16x32_bf16 v[86:89], v[156:159], v[196:199], v[86:89]
	v_mfma_f32_16x16x32_bf16 v[86:89], v[160:163], v[200:203], v[86:89]
	v_mfma_f32_16x16x32_bf16 v[78:81], v[148:151], v[208:211], v[78:81]
	v_mfma_f32_16x16x32_bf16 v[78:81], v[152:155], v[212:215], v[78:81]
	v_mfma_f32_16x16x32_bf16 v[70:73], v[156:159], v[208:211], v[70:73]
	v_mfma_f32_16x16x32_bf16 v[70:73], v[160:163], v[212:215], v[70:73]
	v_mfma_f32_16x16x32_bf16 v[118:121], v[164:167], v[180:183], v[118:121]
	v_mfma_f32_16x16x32_bf16 v[118:121], v[168:171], v[184:187], v[118:121]
	v_mfma_f32_16x16x32_bf16 v[114:117], v[172:175], v[180:183], v[114:117]
	v_mfma_f32_16x16x32_bf16 v[114:117], v[176:179], v[184:187], v[114:117]
	v_mfma_f32_16x16x32_bf16 v[106:109], v[164:167], v[188:191], v[106:109]
	v_mfma_f32_16x16x32_bf16 v[106:109], v[168:171], v[192:195], v[106:109]
	v_mfma_f32_16x16x32_bf16 v[98:101], v[172:175], v[188:191], v[98:101]
	v_mfma_f32_16x16x32_bf16 v[98:101], v[176:179], v[192:195], v[98:101]
	v_mfma_f32_16x16x32_bf16 v[90:93], v[164:167], v[196:199], v[90:93]
	v_mfma_f32_16x16x32_bf16 v[90:93], v[168:171], v[200:203], v[90:93]
	v_mfma_f32_16x16x32_bf16 v[82:85], v[172:175], v[196:199], v[82:85]
	v_mfma_f32_16x16x32_bf16 v[82:85], v[176:179], v[200:203], v[82:85]
	v_mfma_f32_16x16x32_bf16 v[74:77], v[164:167], v[208:211], v[74:77]
	v_mfma_f32_16x16x32_bf16 v[74:77], v[168:171], v[212:215], v[74:77]
	v_mfma_f32_16x16x32_bf16 v[66:69], v[172:175], v[208:211], v[66:69]
	v_mfma_f32_16x16x32_bf16 v[66:69], v[176:179], v[212:215], v[66:69]
	s_barrier
	s_add_i32 s73, s52, s33
	s_mov_b32 m0, s73
	ds_read_b128 v[180:183], v146 offset:16384
	ds_read_b128 v[184:187], v146 offset:17408
	ds_read_b128 v[188:191], v146 offset:18432
	ds_read_b128 v[192:195], v146 offset:19456
	ds_read_b128 v[196:199], v146 offset:20480
	ds_read_b128 v[200:203], v146 offset:21504
	ds_read_b128 v[208:211], v146 offset:22528
	ds_read_b128 v[212:215], v146 offset:23552
	global_load_lds_dwordx4 v132, s[2:3]
	s_add_i32 m0, s73, 0x2000
	s_add_u32 s74, s2, 0x80000
	s_addc_u32 s75, s3, 0
	s_add_i32 s73, s53, s33
	global_load_lds_dwordx4 v136, s[2:3]
	s_mov_b32 m0, s73
	v_lshl_add_u64 v[220:221], s[40:41], 0, v[134:135]
	global_load_lds_dwordx4 v132, s[74:75]
	s_add_i32 m0, s73, 0x2000
	s_nop 0
	global_load_lds_dwordx4 v136, s[74:75]
	v_lshl_add_u64 v[218:219], s[40:41], 0, v[130:131]
	s_mov_b32 m0, s29
	s_nop 0
	global_load_lds_dwordx4 v130, s[40:41]
	s_mov_b32 m0, s35
	s_nop 0
	global_load_lds_dwordx4 v134, s[40:41]
	s_waitcnt vmcnt(8)
	s_waitcnt lgkmcnt(0)
	s_barrier
	s_waitcnt lgkmcnt(0)
	v_mfma_f32_16x16x32_bf16 v[62:65], v[148:151], v[180:183], v[62:65]
	v_mfma_f32_16x16x32_bf16 v[62:65], v[152:155], v[184:187], v[62:65]
	v_mfma_f32_16x16x32_bf16 v[54:57], v[156:159], v[180:183], v[54:57]
	v_mfma_f32_16x16x32_bf16 v[54:57], v[160:163], v[184:187], v[54:57]
	v_mfma_f32_16x16x32_bf16 v[46:49], v[148:151], v[188:191], v[46:49]
	v_mfma_f32_16x16x32_bf16 v[46:49], v[152:155], v[192:195], v[46:49]
	v_mfma_f32_16x16x32_bf16 v[38:41], v[156:159], v[188:191], v[38:41]
	v_mfma_f32_16x16x32_bf16 v[38:41], v[160:163], v[192:195], v[38:41]
	v_mfma_f32_16x16x32_bf16 v[30:33], v[148:151], v[196:199], v[30:33]
	v_mfma_f32_16x16x32_bf16 v[30:33], v[152:155], v[200:203], v[30:33]
	v_mfma_f32_16x16x32_bf16 v[22:25], v[156:159], v[196:199], v[22:25]
	v_mfma_f32_16x16x32_bf16 v[22:25], v[160:163], v[200:203], v[22:25]
	v_mfma_f32_16x16x32_bf16 v[14:17], v[148:151], v[208:211], v[14:17]
	v_mfma_f32_16x16x32_bf16 v[14:17], v[152:155], v[212:215], v[14:17]
	v_mfma_f32_16x16x32_bf16 v[6:9], v[156:159], v[208:211], v[6:9]
	v_mfma_f32_16x16x32_bf16 v[6:9], v[160:163], v[212:215], v[6:9]
	v_mfma_f32_16x16x32_bf16 v[58:61], v[164:167], v[180:183], v[58:61]
	v_mfma_f32_16x16x32_bf16 v[58:61], v[168:171], v[184:187], v[58:61]
	v_mfma_f32_16x16x32_bf16 v[50:53], v[172:175], v[180:183], v[50:53]
	v_mfma_f32_16x16x32_bf16 v[50:53], v[176:179], v[184:187], v[50:53]
	v_mfma_f32_16x16x32_bf16 v[42:45], v[164:167], v[188:191], v[42:45]
	v_mfma_f32_16x16x32_bf16 v[42:45], v[168:171], v[192:195], v[42:45]
	v_mfma_f32_16x16x32_bf16 v[34:37], v[172:175], v[188:191], v[34:37]
	v_mfma_f32_16x16x32_bf16 v[34:37], v[176:179], v[192:195], v[34:37]
	v_mfma_f32_16x16x32_bf16 v[26:29], v[164:167], v[196:199], v[26:29]
	v_mfma_f32_16x16x32_bf16 v[26:29], v[168:171], v[200:203], v[26:29]
	v_mfma_f32_16x16x32_bf16 v[18:21], v[172:175], v[196:199], v[18:21]
	v_mfma_f32_16x16x32_bf16 v[18:21], v[176:179], v[200:203], v[18:21]
	v_mfma_f32_16x16x32_bf16 v[10:13], v[164:167], v[208:211], v[10:13]
	v_mfma_f32_16x16x32_bf16 v[10:13], v[168:171], v[212:215], v[10:13]
	v_mfma_f32_16x16x32_bf16 v[2:5], v[172:175], v[208:211], v[2:5]
	v_mfma_f32_16x16x32_bf16 v[2:5], v[176:179], v[212:215], v[2:5]
	s_barrier
	s_add_i32 s73, 0, 0x18000
	v_add_u32_e32 v147, s73, v142
	s_add_i32 s74, 0, 0x1c000
	ds_read_b128 v[148:151], v147
	ds_read_b128 v[152:155], v147 offset:1024
	ds_read_b128 v[156:159], v147 offset:2048
	ds_read_b128 v[160:163], v147 offset:3072
	v_add_u32_e32 v147, s74, v142
	ds_read_b128 v[164:167], v147
	ds_read_b128 v[168:171], v147 offset:1024
	ds_read_b128 v[172:175], v147 offset:2048
	ds_read_b128 v[176:179], v147 offset:3072
	s_add_u32 s40, s40, 0x80000
	s_addc_u32 s41, s41, 0
	s_mov_b32 m0, s43
	ds_read_b128 v[180:183], v146 offset:32768
	ds_read_b128 v[184:187], v146 offset:33792
	ds_read_b128 v[188:191], v146 offset:34816
	ds_read_b128 v[192:195], v146 offset:35840
	ds_read_b128 v[196:199], v146 offset:36864
	ds_read_b128 v[200:203], v146 offset:37888
	ds_read_b128 v[208:211], v146 offset:38912
	ds_read_b128 v[212:215], v146 offset:39936
	global_load_lds_dwordx4 v130, s[40:41]
	s_mov_b32 m0, s44
	s_nop 0
	global_load_lds_dwordx4 v134, s[40:41]
	s_waitcnt vmcnt(8)
	s_waitcnt lgkmcnt(0)
	s_barrier
	s_waitcnt lgkmcnt(0)
	v_mfma_f32_16x16x32_bf16 v[126:129], v[148:151], v[180:183], v[126:129]
	v_mfma_f32_16x16x32_bf16 v[126:129], v[152:155], v[184:187], v[126:129]
	v_mfma_f32_16x16x32_bf16 v[122:125], v[156:159], v[180:183], v[122:125]
	v_mfma_f32_16x16x32_bf16 v[122:125], v[160:163], v[184:187], v[122:125]
	v_mfma_f32_16x16x32_bf16 v[110:113], v[148:151], v[188:191], v[110:113]
	v_mfma_f32_16x16x32_bf16 v[110:113], v[152:155], v[192:195], v[110:113]
	v_mfma_f32_16x16x32_bf16 v[102:105], v[156:159], v[188:191], v[102:105]
	v_mfma_f32_16x16x32_bf16 v[102:105], v[160:163], v[192:195], v[102:105]
	v_mfma_f32_16x16x32_bf16 v[94:97], v[148:151], v[196:199], v[94:97]
	v_mfma_f32_16x16x32_bf16 v[94:97], v[152:155], v[200:203], v[94:97]
	v_mfma_f32_16x16x32_bf16 v[86:89], v[156:159], v[196:199], v[86:89]
	v_mfma_f32_16x16x32_bf16 v[86:89], v[160:163], v[200:203], v[86:89]
	v_mfma_f32_16x16x32_bf16 v[78:81], v[148:151], v[208:211], v[78:81]
	v_mfma_f32_16x16x32_bf16 v[78:81], v[152:155], v[212:215], v[78:81]
	v_mfma_f32_16x16x32_bf16 v[70:73], v[156:159], v[208:211], v[70:73]
	v_mfma_f32_16x16x32_bf16 v[70:73], v[160:163], v[212:215], v[70:73]
	v_mfma_f32_16x16x32_bf16 v[118:121], v[164:167], v[180:183], v[118:121]
	v_mfma_f32_16x16x32_bf16 v[118:121], v[168:171], v[184:187], v[118:121]
	v_mfma_f32_16x16x32_bf16 v[114:117], v[172:175], v[180:183], v[114:117]
	v_mfma_f32_16x16x32_bf16 v[114:117], v[176:179], v[184:187], v[114:117]
	v_mfma_f32_16x16x32_bf16 v[106:109], v[164:167], v[188:191], v[106:109]
	v_mfma_f32_16x16x32_bf16 v[106:109], v[168:171], v[192:195], v[106:109]
	v_mfma_f32_16x16x32_bf16 v[98:101], v[172:175], v[188:191], v[98:101]
	v_mfma_f32_16x16x32_bf16 v[98:101], v[176:179], v[192:195], v[98:101]
	v_mfma_f32_16x16x32_bf16 v[90:93], v[164:167], v[196:199], v[90:93]
	v_mfma_f32_16x16x32_bf16 v[90:93], v[168:171], v[200:203], v[90:93]
	v_mfma_f32_16x16x32_bf16 v[82:85], v[172:175], v[196:199], v[82:85]
	v_mfma_f32_16x16x32_bf16 v[82:85], v[176:179], v[200:203], v[82:85]
	v_mfma_f32_16x16x32_bf16 v[74:77], v[164:167], v[208:211], v[74:77]
	v_mfma_f32_16x16x32_bf16 v[74:77], v[168:171], v[212:215], v[74:77]
	v_mfma_f32_16x16x32_bf16 v[66:69], v[172:175], v[208:211], v[66:69]
	v_mfma_f32_16x16x32_bf16 v[66:69], v[176:179], v[212:215], v[66:69]
	s_barrier
	s_add_i32 s40, s73, s33
	s_add_u32 s98, s2, s16
	s_addc_u32 s99, s3, s17
	s_mov_b32 m0, s40
	ds_read_b128 v[180:183], v146 offset:49152
	ds_read_b128 v[184:187], v146 offset:50176
	ds_read_b128 v[188:191], v146 offset:51200
	ds_read_b128 v[192:195], v146 offset:52224
	ds_read_b128 v[196:199], v146 offset:53248
	ds_read_b128 v[200:203], v146 offset:54272
	ds_read_b128 v[208:211], v146 offset:55296
	ds_read_b128 v[212:215], v146 offset:56320
	global_load_lds_dwordx4 v132, s[98:99]
	s_add_i32 m0, s40, 0x2000
	s_add_u32 s2, s2, 0x80080
	s_addc_u32 s3, s3, 0
	s_add_i32 s40, s74, s33
	global_load_lds_dwordx4 v136, s[98:99]
	s_mov_b32 m0, s40
	s_nop 0
	global_load_lds_dwordx4 v132, s[2:3]
	s_add_i32 m0, s40, 0x2000
	s_nop 0
	global_load_lds_dwordx4 v136, s[2:3]
	v_lshl_add_u64 v[204:205], v[218:219], 0, s[16:17]
	s_mov_b32 m0, s46
	s_nop 0
	global_load_lds_dwordx4 v[204:205], off
	v_lshl_add_u64 v[204:205], v[220:221], 0, s[16:17]
	s_mov_b32 m0, s47
	s_nop 0
	global_load_lds_dwordx4 v[204:205], off
	s_waitcnt vmcnt(8)
	s_waitcnt lgkmcnt(0)
	s_barrier
	s_waitcnt lgkmcnt(0)
	v_mfma_f32_16x16x32_bf16 v[62:65], v[148:151], v[180:183], v[62:65]
	v_mfma_f32_16x16x32_bf16 v[62:65], v[152:155], v[184:187], v[62:65]
	v_mfma_f32_16x16x32_bf16 v[54:57], v[156:159], v[180:183], v[54:57]
	v_mfma_f32_16x16x32_bf16 v[54:57], v[160:163], v[184:187], v[54:57]
	v_mfma_f32_16x16x32_bf16 v[46:49], v[148:151], v[188:191], v[46:49]
	v_mfma_f32_16x16x32_bf16 v[46:49], v[152:155], v[192:195], v[46:49]
	v_mfma_f32_16x16x32_bf16 v[38:41], v[156:159], v[188:191], v[38:41]
	v_mfma_f32_16x16x32_bf16 v[38:41], v[160:163], v[192:195], v[38:41]
	v_mfma_f32_16x16x32_bf16 v[30:33], v[148:151], v[196:199], v[30:33]
	v_mfma_f32_16x16x32_bf16 v[30:33], v[152:155], v[200:203], v[30:33]
	v_mfma_f32_16x16x32_bf16 v[22:25], v[156:159], v[196:199], v[22:25]
	v_mfma_f32_16x16x32_bf16 v[22:25], v[160:163], v[200:203], v[22:25]
	v_mfma_f32_16x16x32_bf16 v[14:17], v[148:151], v[208:211], v[14:17]
	v_mfma_f32_16x16x32_bf16 v[14:17], v[152:155], v[212:215], v[14:17]
	v_mfma_f32_16x16x32_bf16 v[6:9], v[156:159], v[208:211], v[6:9]
	v_mfma_f32_16x16x32_bf16 v[6:9], v[160:163], v[212:215], v[6:9]
	v_mfma_f32_16x16x32_bf16 v[58:61], v[164:167], v[180:183], v[58:61]
	v_mfma_f32_16x16x32_bf16 v[58:61], v[168:171], v[184:187], v[58:61]
	v_mfma_f32_16x16x32_bf16 v[50:53], v[172:175], v[180:183], v[50:53]
	v_mfma_f32_16x16x32_bf16 v[50:53], v[176:179], v[184:187], v[50:53]
	v_mfma_f32_16x16x32_bf16 v[42:45], v[164:167], v[188:191], v[42:45]
	v_mfma_f32_16x16x32_bf16 v[42:45], v[168:171], v[192:195], v[42:45]
	v_mfma_f32_16x16x32_bf16 v[34:37], v[172:175], v[188:191], v[34:37]
	v_mfma_f32_16x16x32_bf16 v[34:37], v[176:179], v[192:195], v[34:37]
	v_mfma_f32_16x16x32_bf16 v[26:29], v[164:167], v[196:199], v[26:29]
	v_mfma_f32_16x16x32_bf16 v[26:29], v[168:171], v[200:203], v[26:29]
	v_mfma_f32_16x16x32_bf16 v[18:21], v[172:175], v[196:199], v[18:21]
	v_mfma_f32_16x16x32_bf16 v[18:21], v[176:179], v[200:203], v[18:21]
	v_mfma_f32_16x16x32_bf16 v[10:13], v[164:167], v[208:211], v[10:13]
	v_mfma_f32_16x16x32_bf16 v[10:13], v[168:171], v[212:215], v[10:13]
	v_mfma_f32_16x16x32_bf16 v[2:5], v[172:175], v[208:211], v[2:5]
	v_mfma_f32_16x16x32_bf16 v[2:5], v[176:179], v[212:215], v[2:5]
	s_barrier
	s_add_u32 s38, s38, 0x100
	s_addc_u32 s39, s39, 0
	s_add_u32 s68, s68, 0x100
	s_addc_u32 s69, s69, 0
	s_cmp_ge_i32 s72, s37
	s_mov_b32 s2, s72
	s_cbranch_scc0 .LBB0_526

.LBB0_632:
	s_lshl_b32 s11, s26, 20
	s_and_b32 s11, s11, 0xff00000
	v_readlane_b32 s46, v248, 20
	v_readlane_b32 s47, v248, 21
	s_add_u32 s11, s46, s11
	v_cmp_gt_i64_e64 s[0:1], s[26:27], -1
	s_addc_u32 s16, s47, 0
	s_lshr_b32 s27, s26, 13
	s_and_b32 s27, s27, 0x7ff80
	s_add_u32 s76, s11, s27
	s_addc_u32 s77, s16, 0
	s_lshl_b32 s11, s26, 12
	s_and_b32 s11, s11, 0xff00000
	s_add_u32 s11, s60, s11
	s_addc_u32 s16, s61, 0
	s_add_u32 s78, s11, s27
	s_addc_u32 s79, s16, 0
	s_cmp_lt_i32 s17, 1
	s_cbranch_scc1 .LBB0_640
	s_and_b64 s[26:27], s[0:1], exec
	s_cselect_b32 s11, s77, s19
	s_cselect_b32 s16, s76, s18
	s_cselect_b32 s46, s79, s3
	s_cselect_b32 s47, s78, s2
	s_add_i32 s50, s17, -2
	s_add_u32 s18, s18, 0x80080
	s_addc_u32 s19, s19, 0
	s_add_u32 s51, s2, 0x100
	s_addc_u32 s52, s3, 0
	s_mov_b32 s2, 0
	ds_read_b128 v[130:133], v197
	ds_read_b128 v[134:137], v197 offset:1024
	ds_read_b128 v[138:141], v197 offset:2048
	ds_read_b128 v[142:145], v197 offset:3072
	ds_read_b128 v[146:149], v198
	ds_read_b128 v[150:153], v198 offset:1024
	ds_read_b128 v[154:157], v198 offset:2048
	ds_read_b128 v[170:173], v198 offset:3072
	s_add_i32 s53, s2, 2
	s_add_u32 s3, s18, 0xfff80080
	s_addc_u32 s26, s19, -1
	s_cmp_eq_u32 s50, s2
	s_cselect_b32 s2, s47, s51
	s_cselect_b32 s27, s11, s26
	s_cselect_b32 s26, s16, s3
	s_cselect_b32 s3, s46, s52
	s_add_i32 m0, s13, 0xc000
	ds_read_b128 v[174:177], v199
	ds_read_b128 v[178:181], v199 offset:1024
	ds_read_b128 v[182:185], v199 offset:2048
	ds_read_b128 v[186:189], v199 offset:3072
	ds_read_b128 v[190:193], v199 offset:4096
	ds_read_b128 v[200:203], v199 offset:5120
	ds_read_b128 v[208:211], v199 offset:6144
	ds_read_b128 v[212:215], v199 offset:7168
	global_load_lds_dwordx4 v166, s[18:19]
	s_add_i32 m0, s13, 0xe000
	s_nop 0
	global_load_lds_dwordx4 v168, s[18:19]
	s_waitcnt vmcnt(8)
	s_waitcnt lgkmcnt(0)
	s_barrier
	s_waitcnt lgkmcnt(0)
	v_mfma_f32_16x16x32_bf16 v[122:125], v[130:133], v[174:177], 0
	v_mfma_f32_16x16x32_bf16 v[122:125], v[134:137], v[178:181], v[122:125]
	v_mfma_f32_16x16x32_bf16 v[114:117], v[138:141], v[174:177], 0
	v_mfma_f32_16x16x32_bf16 v[114:117], v[142:145], v[178:181], v[114:117]
	v_mfma_f32_16x16x32_bf16 v[106:109], v[130:133], v[182:185], 0
	v_mfma_f32_16x16x32_bf16 v[106:109], v[134:137], v[186:189], v[106:109]
	v_mfma_f32_16x16x32_bf16 v[98:101], v[138:141], v[182:185], 0
	v_mfma_f32_16x16x32_bf16 v[98:101], v[142:145], v[186:189], v[98:101]
	v_mfma_f32_16x16x32_bf16 v[90:93], v[130:133], v[190:193], 0
	v_mfma_f32_16x16x32_bf16 v[90:93], v[134:137], v[200:203], v[90:93]
	v_mfma_f32_16x16x32_bf16 v[82:85], v[138:141], v[190:193], 0
	v_mfma_f32_16x16x32_bf16 v[82:85], v[142:145], v[200:203], v[82:85]
	v_mfma_f32_16x16x32_bf16 v[74:77], v[130:133], v[208:211], 0
	v_mfma_f32_16x16x32_bf16 v[74:77], v[134:137], v[212:215], v[74:77]
	v_mfma_f32_16x16x32_bf16 v[66:69], v[138:141], v[208:211], 0
	v_mfma_f32_16x16x32_bf16 v[66:69], v[142:145], v[212:215], v[66:69]
	v_mfma_f32_16x16x32_bf16 v[126:129], v[146:149], v[174:177], 0
	v_mfma_f32_16x16x32_bf16 v[126:129], v[150:153], v[178:181], v[126:129]
	v_mfma_f32_16x16x32_bf16 v[118:121], v[154:157], v[174:177], 0
	v_mfma_f32_16x16x32_bf16 v[118:121], v[170:173], v[178:181], v[118:121]
	v_mfma_f32_16x16x32_bf16 v[110:113], v[146:149], v[182:185], 0
	v_mfma_f32_16x16x32_bf16 v[110:113], v[150:153], v[186:189], v[110:113]
	v_mfma_f32_16x16x32_bf16 v[102:105], v[154:157], v[182:185], 0
	v_mfma_f32_16x16x32_bf16 v[102:105], v[170:173], v[186:189], v[102:105]
	v_mfma_f32_16x16x32_bf16 v[94:97], v[146:149], v[190:193], 0
	v_mfma_f32_16x16x32_bf16 v[94:97], v[150:153], v[200:203], v[94:97]
	v_mfma_f32_16x16x32_bf16 v[86:89], v[154:157], v[190:193], 0
	v_mfma_f32_16x16x32_bf16 v[86:89], v[170:173], v[200:203], v[86:89]
	v_mfma_f32_16x16x32_bf16 v[78:81], v[146:149], v[208:211], 0
	v_mfma_f32_16x16x32_bf16 v[78:81], v[150:153], v[212:215], v[78:81]
	v_mfma_f32_16x16x32_bf16 v[70:73], v[154:157], v[208:211], 0
	v_mfma_f32_16x16x32_bf16 v[70:73], v[170:173], v[212:215], v[70:73]
	s_barrier
	s_add_i32 s64, s44, s35
	s_mov_b32 m0, s64
	ds_read_b128 v[174:177], v199 offset:16384
	ds_read_b128 v[178:181], v199 offset:17408
	ds_read_b128 v[182:185], v199 offset:18432
	ds_read_b128 v[186:189], v199 offset:19456
	ds_read_b128 v[190:193], v199 offset:20480
	ds_read_b128 v[200:203], v199 offset:21504
	ds_read_b128 v[208:211], v199 offset:22528
	ds_read_b128 v[212:215], v199 offset:23552
	global_load_lds_dwordx4 v160, s[2:3]
	s_add_i32 m0, s64, 0x2000
	s_add_u32 s80, s2, 0x80000
	s_addc_u32 s81, s3, 0
	s_add_i32 s64, s45, s35
	global_load_lds_dwordx4 v164, s[2:3]
	s_mov_b32 m0, s64
	v_lshl_add_u64 v[220:221], s[26:27], 0, v[162:163]
	global_load_lds_dwordx4 v160, s[80:81]
	s_add_i32 m0, s64, 0x2000
	s_nop 0
	global_load_lds_dwordx4 v164, s[80:81]
	v_lshl_add_u64 v[218:219], s[26:27], 0, v[158:159]
	s_mov_b32 m0, s13
	s_nop 0
	global_load_lds_dwordx4 v158, s[26:27]
	s_mov_b32 m0, s36
	s_nop 0
	global_load_lds_dwordx4 v162, s[26:27]
	s_waitcnt vmcnt(8)
	s_waitcnt lgkmcnt(0)
	s_barrier
	s_waitcnt lgkmcnt(0)
	v_mfma_f32_16x16x32_bf16 v[58:61], v[130:133], v[174:177], 0
	v_mfma_f32_16x16x32_bf16 v[58:61], v[134:137], v[178:181], v[58:61]
	v_mfma_f32_16x16x32_bf16 v[50:53], v[138:141], v[174:177], 0
	v_mfma_f32_16x16x32_bf16 v[50:53], v[142:145], v[178:181], v[50:53]
	v_mfma_f32_16x16x32_bf16 v[42:45], v[130:133], v[182:185], 0
	v_mfma_f32_16x16x32_bf16 v[42:45], v[134:137], v[186:189], v[42:45]
	v_mfma_f32_16x16x32_bf16 v[34:37], v[138:141], v[182:185], 0
	v_mfma_f32_16x16x32_bf16 v[34:37], v[142:145], v[186:189], v[34:37]
	v_mfma_f32_16x16x32_bf16 v[26:29], v[130:133], v[190:193], 0
	v_mfma_f32_16x16x32_bf16 v[26:29], v[134:137], v[200:203], v[26:29]
	v_mfma_f32_16x16x32_bf16 v[18:21], v[138:141], v[190:193], 0
	v_mfma_f32_16x16x32_bf16 v[18:21], v[142:145], v[200:203], v[18:21]
	v_mfma_f32_16x16x32_bf16 v[10:13], v[130:133], v[208:211], 0
	v_mfma_f32_16x16x32_bf16 v[10:13], v[134:137], v[212:215], v[10:13]
	v_mfma_f32_16x16x32_bf16 v[2:5], v[138:141], v[208:211], 0
	v_mfma_f32_16x16x32_bf16 v[2:5], v[142:145], v[212:215], v[2:5]
	v_mfma_f32_16x16x32_bf16 v[62:65], v[146:149], v[174:177], 0
	v_mfma_f32_16x16x32_bf16 v[62:65], v[150:153], v[178:181], v[62:65]
	v_mfma_f32_16x16x32_bf16 v[54:57], v[154:157], v[174:177], 0
	v_mfma_f32_16x16x32_bf16 v[54:57], v[170:173], v[178:181], v[54:57]
	v_mfma_f32_16x16x32_bf16 v[46:49], v[146:149], v[182:185], 0
	v_mfma_f32_16x16x32_bf16 v[46:49], v[150:153], v[186:189], v[46:49]
	v_mfma_f32_16x16x32_bf16 v[38:41], v[154:157], v[182:185], 0
	v_mfma_f32_16x16x32_bf16 v[38:41], v[170:173], v[186:189], v[38:41]
	v_mfma_f32_16x16x32_bf16 v[30:33], v[146:149], v[190:193], 0
	v_mfma_f32_16x16x32_bf16 v[30:33], v[150:153], v[200:203], v[30:33]
	v_mfma_f32_16x16x32_bf16 v[22:25], v[154:157], v[190:193], 0
	v_mfma_f32_16x16x32_bf16 v[22:25], v[170:173], v[200:203], v[22:25]
	v_mfma_f32_16x16x32_bf16 v[14:17], v[146:149], v[208:211], 0
	v_mfma_f32_16x16x32_bf16 v[14:17], v[150:153], v[212:215], v[14:17]
	v_mfma_f32_16x16x32_bf16 v[6:9], v[154:157], v[208:211], 0
	v_mfma_f32_16x16x32_bf16 v[6:9], v[170:173], v[212:215], v[6:9]
	s_barrier
	s_add_i32 s64, 0, 0x18000
	s_add_i32 s75, 0, 0x1c000
	v_add_u32_e32 v142, s64, v194
	v_add_u32_e32 v170, s75, v194
	ds_read_b128 v[130:133], v142
	ds_read_b128 v[134:137], v142 offset:1024
	ds_read_b128 v[138:141], v142 offset:2048
	ds_read_b128 v[142:145], v142 offset:3072
	ds_read_b128 v[146:149], v170
	ds_read_b128 v[150:153], v170 offset:1024
	ds_read_b128 v[154:157], v170 offset:2048
	ds_read_b128 v[170:173], v170 offset:3072
	s_add_u32 s26, s26, 0x80000
	s_addc_u32 s27, s27, 0
	s_mov_b32 m0, s37
	ds_read_b128 v[174:177], v199 offset:32768
	ds_read_b128 v[178:181], v199 offset:33792
	ds_read_b128 v[182:185], v199 offset:34816
	ds_read_b128 v[186:189], v199 offset:35840
	ds_read_b128 v[190:193], v199 offset:36864
	ds_read_b128 v[200:203], v199 offset:37888
	ds_read_b128 v[208:211], v199 offset:38912
	ds_read_b128 v[212:215], v199 offset:39936
	global_load_lds_dwordx4 v158, s[26:27]
	s_mov_b32 m0, s38
	s_nop 0
	global_load_lds_dwordx4 v162, s[26:27]
	s_waitcnt vmcnt(8)
	s_waitcnt lgkmcnt(0)
	s_barrier
	s_waitcnt lgkmcnt(0)
	v_mfma_f32_16x16x32_bf16 v[122:125], v[130:133], v[174:177], v[122:125]
	v_mfma_f32_16x16x32_bf16 v[122:125], v[134:137], v[178:181], v[122:125]
	v_mfma_f32_16x16x32_bf16 v[114:117], v[138:141], v[174:177], v[114:117]
	v_mfma_f32_16x16x32_bf16 v[114:117], v[142:145], v[178:181], v[114:117]
	v_mfma_f32_16x16x32_bf16 v[106:109], v[130:133], v[182:185], v[106:109]
	v_mfma_f32_16x16x32_bf16 v[106:109], v[134:137], v[186:189], v[106:109]
	v_mfma_f32_16x16x32_bf16 v[98:101], v[138:141], v[182:185], v[98:101]
	v_mfma_f32_16x16x32_bf16 v[98:101], v[142:145], v[186:189], v[98:101]
	v_mfma_f32_16x16x32_bf16 v[90:93], v[130:133], v[190:193], v[90:93]
	v_mfma_f32_16x16x32_bf16 v[90:93], v[134:137], v[200:203], v[90:93]
	v_mfma_f32_16x16x32_bf16 v[82:85], v[138:141], v[190:193], v[82:85]
	v_mfma_f32_16x16x32_bf16 v[82:85], v[142:145], v[200:203], v[82:85]
	v_mfma_f32_16x16x32_bf16 v[74:77], v[130:133], v[208:211], v[74:77]
	v_mfma_f32_16x16x32_bf16 v[74:77], v[134:137], v[212:215], v[74:77]
	v_mfma_f32_16x16x32_bf16 v[66:69], v[138:141], v[208:211], v[66:69]
	v_mfma_f32_16x16x32_bf16 v[66:69], v[142:145], v[212:215], v[66:69]
	v_mfma_f32_16x16x32_bf16 v[126:129], v[146:149], v[174:177], v[126:129]
	v_mfma_f32_16x16x32_bf16 v[126:129], v[150:153], v[178:181], v[126:129]
	v_mfma_f32_16x16x32_bf16 v[118:121], v[154:157], v[174:177], v[118:121]
	v_mfma_f32_16x16x32_bf16 v[118:121], v[170:173], v[178:181], v[118:121]
	v_mfma_f32_16x16x32_bf16 v[110:113], v[146:149], v[182:185], v[110:113]
	v_mfma_f32_16x16x32_bf16 v[110:113], v[150:153], v[186:189], v[110:113]
	v_mfma_f32_16x16x32_bf16 v[102:105], v[154:157], v[182:185], v[102:105]
	v_mfma_f32_16x16x32_bf16 v[102:105], v[170:173], v[186:189], v[102:105]
	v_mfma_f32_16x16x32_bf16 v[94:97], v[146:149], v[190:193], v[94:97]
	v_mfma_f32_16x16x32_bf16 v[94:97], v[150:153], v[200:203], v[94:97]
	v_mfma_f32_16x16x32_bf16 v[86:89], v[154:157], v[190:193], v[86:89]
	v_mfma_f32_16x16x32_bf16 v[86:89], v[170:173], v[200:203], v[86:89]
	v_mfma_f32_16x16x32_bf16 v[78:81], v[146:149], v[208:211], v[78:81]
	v_mfma_f32_16x16x32_bf16 v[78:81], v[150:153], v[212:215], v[78:81]
	v_mfma_f32_16x16x32_bf16 v[70:73], v[154:157], v[208:211], v[70:73]
	v_mfma_f32_16x16x32_bf16 v[70:73], v[170:173], v[212:215], v[70:73]
	s_barrier
	s_add_i32 s26, s64, s35
	s_add_u32 s98, s2, s68
	s_addc_u32 s99, s3, s69
	s_mov_b32 m0, s26
	ds_read_b128 v[174:177], v199 offset:49152
	ds_read_b128 v[178:181], v199 offset:50176
	ds_read_b128 v[182:185], v199 offset:51200
	ds_read_b128 v[186:189], v199 offset:52224
	ds_read_b128 v[190:193], v199 offset:53248
	ds_read_b128 v[200:203], v199 offset:54272
	ds_read_b128 v[208:211], v199 offset:55296
	ds_read_b128 v[212:215], v199 offset:56320
	global_load_lds_dwordx4 v160, s[98:99]
	s_add_i32 m0, s26, 0x2000
	s_add_u32 s2, s2, 0x80080
	s_addc_u32 s3, s3, 0
	s_add_i32 s26, s75, s35
	global_load_lds_dwordx4 v164, s[98:99]
	s_mov_b32 m0, s26
	s_nop 0
	global_load_lds_dwordx4 v160, s[2:3]
	s_add_i32 m0, s26, 0x2000
	s_nop 0
	global_load_lds_dwordx4 v164, s[2:3]
	v_lshl_add_u64 v[204:205], v[218:219], 0, s[68:69]
	s_mov_b32 m0, s40
	s_nop 0
	global_load_lds_dwordx4 v[204:205], off
	v_lshl_add_u64 v[204:205], v[220:221], 0, s[68:69]
	s_mov_b32 m0, s41
	s_nop 0
	global_load_lds_dwordx4 v[204:205], off
	s_waitcnt vmcnt(8)
	s_waitcnt lgkmcnt(0)
	s_barrier
	s_waitcnt lgkmcnt(0)
	v_mfma_f32_16x16x32_bf16 v[58:61], v[130:133], v[174:177], v[58:61]
	v_mfma_f32_16x16x32_bf16 v[58:61], v[134:137], v[178:181], v[58:61]
	v_mfma_f32_16x16x32_bf16 v[50:53], v[138:141], v[174:177], v[50:53]
	v_mfma_f32_16x16x32_bf16 v[50:53], v[142:145], v[178:181], v[50:53]
	v_mfma_f32_16x16x32_bf16 v[42:45], v[130:133], v[182:185], v[42:45]
	v_mfma_f32_16x16x32_bf16 v[42:45], v[134:137], v[186:189], v[42:45]
	v_mfma_f32_16x16x32_bf16 v[34:37], v[138:141], v[182:185], v[34:37]
	v_mfma_f32_16x16x32_bf16 v[34:37], v[142:145], v[186:189], v[34:37]
	v_mfma_f32_16x16x32_bf16 v[26:29], v[130:133], v[190:193], v[26:29]
	v_mfma_f32_16x16x32_bf16 v[26:29], v[134:137], v[200:203], v[26:29]
	v_mfma_f32_16x16x32_bf16 v[18:21], v[138:141], v[190:193], v[18:21]
	v_mfma_f32_16x16x32_bf16 v[18:21], v[142:145], v[200:203], v[18:21]
	v_mfma_f32_16x16x32_bf16 v[10:13], v[130:133], v[208:211], v[10:13]
	v_mfma_f32_16x16x32_bf16 v[10:13], v[134:137], v[212:215], v[10:13]
	v_mfma_f32_16x16x32_bf16 v[2:5], v[138:141], v[208:211], v[2:5]
	v_mfma_f32_16x16x32_bf16 v[2:5], v[142:145], v[212:215], v[2:5]
	v_mfma_f32_16x16x32_bf16 v[62:65], v[146:149], v[174:177], v[62:65]
	v_mfma_f32_16x16x32_bf16 v[62:65], v[150:153], v[178:181], v[62:65]
	v_mfma_f32_16x16x32_bf16 v[54:57], v[154:157], v[174:177], v[54:57]
	v_mfma_f32_16x16x32_bf16 v[54:57], v[170:173], v[178:181], v[54:57]
	v_mfma_f32_16x16x32_bf16 v[46:49], v[146:149], v[182:185], v[46:49]
	v_mfma_f32_16x16x32_bf16 v[46:49], v[150:153], v[186:189], v[46:49]
	v_mfma_f32_16x16x32_bf16 v[38:41], v[154:157], v[182:185], v[38:41]
	v_mfma_f32_16x16x32_bf16 v[38:41], v[170:173], v[186:189], v[38:41]
	v_mfma_f32_16x16x32_bf16 v[30:33], v[146:149], v[190:193], v[30:33]
	v_mfma_f32_16x16x32_bf16 v[30:33], v[150:153], v[200:203], v[30:33]
	v_mfma_f32_16x16x32_bf16 v[22:25], v[154:157], v[190:193], v[22:25]
	v_mfma_f32_16x16x32_bf16 v[22:25], v[170:173], v[200:203], v[22:25]
	v_mfma_f32_16x16x32_bf16 v[14:17], v[146:149], v[208:211], v[14:17]
	v_mfma_f32_16x16x32_bf16 v[14:17], v[150:153], v[212:215], v[14:17]
	v_mfma_f32_16x16x32_bf16 v[6:9], v[154:157], v[208:211], v[6:9]
	v_mfma_f32_16x16x32_bf16 v[6:9], v[170:173], v[212:215], v[6:9]
	s_barrier
	s_add_u32 s18, s18, 0x100
	s_addc_u32 s19, s19, 0
	s_add_u32 s51, s51, 0x100
	s_addc_u32 s52, s52, 0
	s_cmp_ge_i32 s53, s17
	s_mov_b32 s2, s53
	s_cbranch_scc1 .Lkpeel_exit_3
.LBB0_634:
	ds_read_b128 v[130:133], v197
	ds_read_b128 v[134:137], v197 offset:1024
	ds_read_b128 v[138:141], v197 offset:2048
	ds_read_b128 v[142:145], v197 offset:3072
	ds_read_b128 v[146:149], v198
	ds_read_b128 v[150:153], v198 offset:1024
	ds_read_b128 v[154:157], v198 offset:2048
	ds_read_b128 v[170:173], v198 offset:3072
	s_add_i32 s53, s2, 2
	s_add_u32 s3, s18, 0xfff80080
	s_addc_u32 s26, s19, -1
	s_cmp_eq_u32 s50, s2
	s_cselect_b32 s2, s47, s51
	s_cselect_b32 s27, s11, s26
	s_cselect_b32 s26, s16, s3
	s_cselect_b32 s3, s46, s52
	s_add_i32 m0, s13, 0xc000
	ds_read_b128 v[174:177], v199
	ds_read_b128 v[178:181], v199 offset:1024
	ds_read_b128 v[182:185], v199 offset:2048
	ds_read_b128 v[186:189], v199 offset:3072
	ds_read_b128 v[190:193], v199 offset:4096
	ds_read_b128 v[200:203], v199 offset:5120
	ds_read_b128 v[208:211], v199 offset:6144
	ds_read_b128 v[212:215], v199 offset:7168
	global_load_lds_dwordx4 v166, s[18:19]
	s_add_i32 m0, s13, 0xe000
	s_nop 0
	global_load_lds_dwordx4 v168, s[18:19]
	s_waitcnt vmcnt(8)
	s_waitcnt lgkmcnt(0)
	s_barrier
	s_waitcnt lgkmcnt(0)
	v_mfma_f32_16x16x32_bf16 v[122:125], v[130:133], v[174:177], v[122:125]
	v_mfma_f32_16x16x32_bf16 v[122:125], v[134:137], v[178:181], v[122:125]
	v_mfma_f32_16x16x32_bf16 v[114:117], v[138:141], v[174:177], v[114:117]
	v_mfma_f32_16x16x32_bf16 v[114:117], v[142:145], v[178:181], v[114:117]
	v_mfma_f32_16x16x32_bf16 v[106:109], v[130:133], v[182:185], v[106:109]
	v_mfma_f32_16x16x32_bf16 v[106:109], v[134:137], v[186:189], v[106:109]
	v_mfma_f32_16x16x32_bf16 v[98:101], v[138:141], v[182:185], v[98:101]
	v_mfma_f32_16x16x32_bf16 v[98:101], v[142:145], v[186:189], v[98:101]
	v_mfma_f32_16x16x32_bf16 v[90:93], v[130:133], v[190:193], v[90:93]
	v_mfma_f32_16x16x32_bf16 v[90:93], v[134:137], v[200:203], v[90:93]
	v_mfma_f32_16x16x32_bf16 v[82:85], v[138:141], v[190:193], v[82:85]
	v_mfma_f32_16x16x32_bf16 v[82:85], v[142:145], v[200:203], v[82:85]
	v_mfma_f32_16x16x32_bf16 v[74:77], v[130:133], v[208:211], v[74:77]
	v_mfma_f32_16x16x32_bf16 v[74:77], v[134:137], v[212:215], v[74:77]
	v_mfma_f32_16x16x32_bf16 v[66:69], v[138:141], v[208:211], v[66:69]
	v_mfma_f32_16x16x32_bf16 v[66:69], v[142:145], v[212:215], v[66:69]
	v_mfma_f32_16x16x32_bf16 v[126:129], v[146:149], v[174:177], v[126:129]
	v_mfma_f32_16x16x32_bf16 v[126:129], v[150:153], v[178:181], v[126:129]
	v_mfma_f32_16x16x32_bf16 v[118:121], v[154:157], v[174:177], v[118:121]
	v_mfma_f32_16x16x32_bf16 v[118:121], v[170:173], v[178:181], v[118:121]
	v_mfma_f32_16x16x32_bf16 v[110:113], v[146:149], v[182:185], v[110:113]
	v_mfma_f32_16x16x32_bf16 v[110:113], v[150:153], v[186:189], v[110:113]
	v_mfma_f32_16x16x32_bf16 v[102:105], v[154:157], v[182:185], v[102:105]
	v_mfma_f32_16x16x32_bf16 v[102:105], v[170:173], v[186:189], v[102:105]
	v_mfma_f32_16x16x32_bf16 v[94:97], v[146:149], v[190:193], v[94:97]
	v_mfma_f32_16x16x32_bf16 v[94:97], v[150:153], v[200:203], v[94:97]
	v_mfma_f32_16x16x32_bf16 v[86:89], v[154:157], v[190:193], v[86:89]
	v_mfma_f32_16x16x32_bf16 v[86:89], v[170:173], v[200:203], v[86:89]
	v_mfma_f32_16x16x32_bf16 v[78:81], v[146:149], v[208:211], v[78:81]
	v_mfma_f32_16x16x32_bf16 v[78:81], v[150:153], v[212:215], v[78:81]
	v_mfma_f32_16x16x32_bf16 v[70:73], v[154:157], v[208:211], v[70:73]
	v_mfma_f32_16x16x32_bf16 v[70:73], v[170:173], v[212:215], v[70:73]
	s_barrier
	s_add_i32 s64, s44, s35
	s_mov_b32 m0, s64
	ds_read_b128 v[174:177], v199 offset:16384
	ds_read_b128 v[178:181], v199 offset:17408
	ds_read_b128 v[182:185], v199 offset:18432
	ds_read_b128 v[186:189], v199 offset:19456
	ds_read_b128 v[190:193], v199 offset:20480
	ds_read_b128 v[200:203], v199 offset:21504
	ds_read_b128 v[208:211], v199 offset:22528
	ds_read_b128 v[212:215], v199 offset:23552
	global_load_lds_dwordx4 v160, s[2:3]
	s_add_i32 m0, s64, 0x2000
	s_add_u32 s80, s2, 0x80000
	s_addc_u32 s81, s3, 0
	s_add_i32 s64, s45, s35
	global_load_lds_dwordx4 v164, s[2:3]
	s_mov_b32 m0, s64
	v_lshl_add_u64 v[220:221], s[26:27], 0, v[162:163]
	global_load_lds_dwordx4 v160, s[80:81]
	s_add_i32 m0, s64, 0x2000
	s_nop 0
	global_load_lds_dwordx4 v164, s[80:81]
	v_lshl_add_u64 v[218:219], s[26:27], 0, v[158:159]
	s_mov_b32 m0, s13
	s_nop 0
	global_load_lds_dwordx4 v158, s[26:27]
	s_mov_b32 m0, s36
	s_nop 0
	global_load_lds_dwordx4 v162, s[26:27]
	s_waitcnt vmcnt(8)
	s_waitcnt lgkmcnt(0)
	s_barrier
	s_waitcnt lgkmcnt(0)
	v_mfma_f32_16x16x32_bf16 v[58:61], v[130:133], v[174:177], v[58:61]
	v_mfma_f32_16x16x32_bf16 v[58:61], v[134:137], v[178:181], v[58:61]
	v_mfma_f32_16x16x32_bf16 v[50:53], v[138:141], v[174:177], v[50:53]
	v_mfma_f32_16x16x32_bf16 v[50:53], v[142:145], v[178:181], v[50:53]
	v_mfma_f32_16x16x32_bf16 v[42:45], v[130:133], v[182:185], v[42:45]
	v_mfma_f32_16x16x32_bf16 v[42:45], v[134:137], v[186:189], v[42:45]
	v_mfma_f32_16x16x32_bf16 v[34:37], v[138:141], v[182:185], v[34:37]
	v_mfma_f32_16x16x32_bf16 v[34:37], v[142:145], v[186:189], v[34:37]
	v_mfma_f32_16x16x32_bf16 v[26:29], v[130:133], v[190:193], v[26:29]
	v_mfma_f32_16x16x32_bf16 v[26:29], v[134:137], v[200:203], v[26:29]
	v_mfma_f32_16x16x32_bf16 v[18:21], v[138:141], v[190:193], v[18:21]
	v_mfma_f32_16x16x32_bf16 v[18:21], v[142:145], v[200:203], v[18:21]
	v_mfma_f32_16x16x32_bf16 v[10:13], v[130:133], v[208:211], v[10:13]
	v_mfma_f32_16x16x32_bf16 v[10:13], v[134:137], v[212:215], v[10:13]
	v_mfma_f32_16x16x32_bf16 v[2:5], v[138:141], v[208:211], v[2:5]
	v_mfma_f32_16x16x32_bf16 v[2:5], v[142:145], v[212:215], v[2:5]
	v_mfma_f32_16x16x32_bf16 v[62:65], v[146:149], v[174:177], v[62:65]
	v_mfma_f32_16x16x32_bf16 v[62:65], v[150:153], v[178:181], v[62:65]
	v_mfma_f32_16x16x32_bf16 v[54:57], v[154:157], v[174:177], v[54:57]
	v_mfma_f32_16x16x32_bf16 v[54:57], v[170:173], v[178:181], v[54:57]
	v_mfma_f32_16x16x32_bf16 v[46:49], v[146:149], v[182:185], v[46:49]
	v_mfma_f32_16x16x32_bf16 v[46:49], v[150:153], v[186:189], v[46:49]
	v_mfma_f32_16x16x32_bf16 v[38:41], v[154:157], v[182:185], v[38:41]
	v_mfma_f32_16x16x32_bf16 v[38:41], v[170:173], v[186:189], v[38:41]
	v_mfma_f32_16x16x32_bf16 v[30:33], v[146:149], v[190:193], v[30:33]
	v_mfma_f32_16x16x32_bf16 v[30:33], v[150:153], v[200:203], v[30:33]
	v_mfma_f32_16x16x32_bf16 v[22:25], v[154:157], v[190:193], v[22:25]
	v_mfma_f32_16x16x32_bf16 v[22:25], v[170:173], v[200:203], v[22:25]
	v_mfma_f32_16x16x32_bf16 v[14:17], v[146:149], v[208:211], v[14:17]
	v_mfma_f32_16x16x32_bf16 v[14:17], v[150:153], v[212:215], v[14:17]
	v_mfma_f32_16x16x32_bf16 v[6:9], v[154:157], v[208:211], v[6:9]
	v_mfma_f32_16x16x32_bf16 v[6:9], v[170:173], v[212:215], v[6:9]
	s_barrier
	s_add_i32 s64, 0, 0x18000
	s_add_i32 s75, 0, 0x1c000
	v_add_u32_e32 v142, s64, v194
	v_add_u32_e32 v170, s75, v194
	ds_read_b128 v[130:133], v142
	ds_read_b128 v[134:137], v142 offset:1024
	ds_read_b128 v[138:141], v142 offset:2048
	ds_read_b128 v[142:145], v142 offset:3072
	ds_read_b128 v[146:149], v170
	ds_read_b128 v[150:153], v170 offset:1024
	ds_read_b128 v[154:157], v170 offset:2048
	ds_read_b128 v[170:173], v170 offset:3072
	s_add_u32 s26, s26, 0x80000
	s_addc_u32 s27, s27, 0
	s_mov_b32 m0, s37
	ds_read_b128 v[174:177], v199 offset:32768
	ds_read_b128 v[178:181], v199 offset:33792
	ds_read_b128 v[182:185], v199 offset:34816
	ds_read_b128 v[186:189], v199 offset:35840
	ds_read_b128 v[190:193], v199 offset:36864
	ds_read_b128 v[200:203], v199 offset:37888
	ds_read_b128 v[208:211], v199 offset:38912
	ds_read_b128 v[212:215], v199 offset:39936
	global_load_lds_dwordx4 v158, s[26:27]
	s_mov_b32 m0, s38
	s_nop 0
	global_load_lds_dwordx4 v162, s[26:27]
	s_waitcnt vmcnt(8)
	s_waitcnt lgkmcnt(0)
	s_barrier
	s_waitcnt lgkmcnt(0)
	v_mfma_f32_16x16x32_bf16 v[122:125], v[130:133], v[174:177], v[122:125]
	v_mfma_f32_16x16x32_bf16 v[122:125], v[134:137], v[178:181], v[122:125]
	v_mfma_f32_16x16x32_bf16 v[114:117], v[138:141], v[174:177], v[114:117]
	v_mfma_f32_16x16x32_bf16 v[114:117], v[142:145], v[178:181], v[114:117]
	v_mfma_f32_16x16x32_bf16 v[106:109], v[130:133], v[182:185], v[106:109]
	v_mfma_f32_16x16x32_bf16 v[106:109], v[134:137], v[186:189], v[106:109]
	v_mfma_f32_16x16x32_bf16 v[98:101], v[138:141], v[182:185], v[98:101]
	v_mfma_f32_16x16x32_bf16 v[98:101], v[142:145], v[186:189], v[98:101]
	v_mfma_f32_16x16x32_bf16 v[90:93], v[130:133], v[190:193], v[90:93]
	v_mfma_f32_16x16x32_bf16 v[90:93], v[134:137], v[200:203], v[90:93]
	v_mfma_f32_16x16x32_bf16 v[82:85], v[138:141], v[190:193], v[82:85]
	v_mfma_f32_16x16x32_bf16 v[82:85], v[142:145], v[200:203], v[82:85]
	v_mfma_f32_16x16x32_bf16 v[74:77], v[130:133], v[208:211], v[74:77]
	v_mfma_f32_16x16x32_bf16 v[74:77], v[134:137], v[212:215], v[74:77]
	v_mfma_f32_16x16x32_bf16 v[66:69], v[138:141], v[208:211], v[66:69]
	v_mfma_f32_16x16x32_bf16 v[66:69], v[142:145], v[212:215], v[66:69]
	v_mfma_f32_16x16x32_bf16 v[126:129], v[146:149], v[174:177], v[126:129]
	v_mfma_f32_16x16x32_bf16 v[126:129], v[150:153], v[178:181], v[126:129]
	v_mfma_f32_16x16x32_bf16 v[118:121], v[154:157], v[174:177], v[118:121]
	v_mfma_f32_16x16x32_bf16 v[118:121], v[170:173], v[178:181], v[118:121]
	v_mfma_f32_16x16x32_bf16 v[110:113], v[146:149], v[182:185], v[110:113]
	v_mfma_f32_16x16x32_bf16 v[110:113], v[150:153], v[186:189], v[110:113]
	v_mfma_f32_16x16x32_bf16 v[102:105], v[154:157], v[182:185], v[102:105]
	v_mfma_f32_16x16x32_bf16 v[102:105], v[170:173], v[186:189], v[102:105]
	v_mfma_f32_16x16x32_bf16 v[94:97], v[146:149], v[190:193], v[94:97]
	v_mfma_f32_16x16x32_bf16 v[94:97], v[150:153], v[200:203], v[94:97]
	v_mfma_f32_16x16x32_bf16 v[86:89], v[154:157], v[190:193], v[86:89]
	v_mfma_f32_16x16x32_bf16 v[86:89], v[170:173], v[200:203], v[86:89]
	v_mfma_f32_16x16x32_bf16 v[78:81], v[146:149], v[208:211], v[78:81]
	v_mfma_f32_16x16x32_bf16 v[78:81], v[150:153], v[212:215], v[78:81]
	v_mfma_f32_16x16x32_bf16 v[70:73], v[154:157], v[208:211], v[70:73]
	v_mfma_f32_16x16x32_bf16 v[70:73], v[170:173], v[212:215], v[70:73]
	s_barrier
	s_add_i32 s26, s64, s35
	s_add_u32 s98, s2, s68
	s_addc_u32 s99, s3, s69
	s_mov_b32 m0, s26
	ds_read_b128 v[174:177], v199 offset:49152
	ds_read_b128 v[178:181], v199 offset:50176
	ds_read_b128 v[182:185], v199 offset:51200
	ds_read_b128 v[186:189], v199 offset:52224
	ds_read_b128 v[190:193], v199 offset:53248
	ds_read_b128 v[200:203], v199 offset:54272
	ds_read_b128 v[208:211], v199 offset:55296
	ds_read_b128 v[212:215], v199 offset:56320
	global_load_lds_dwordx4 v160, s[98:99]
	s_add_i32 m0, s26, 0x2000
	s_add_u32 s2, s2, 0x80080
	s_addc_u32 s3, s3, 0
	s_add_i32 s26, s75, s35
	global_load_lds_dwordx4 v164, s[98:99]
	s_mov_b32 m0, s26
	s_nop 0
	global_load_lds_dwordx4 v160, s[2:3]
	s_add_i32 m0, s26, 0x2000
	s_nop 0
	global_load_lds_dwordx4 v164, s[2:3]
	v_lshl_add_u64 v[204:205], v[218:219], 0, s[68:69]
	s_mov_b32 m0, s40
	s_nop 0
	global_load_lds_dwordx4 v[204:205], off
	v_lshl_add_u64 v[204:205], v[220:221], 0, s[68:69]
	s_mov_b32 m0, s41
	s_nop 0
	global_load_lds_dwordx4 v[204:205], off
	s_waitcnt vmcnt(8)
	s_waitcnt lgkmcnt(0)
	s_barrier
	s_waitcnt lgkmcnt(0)
	v_mfma_f32_16x16x32_bf16 v[58:61], v[130:133], v[174:177], v[58:61]
	v_mfma_f32_16x16x32_bf16 v[58:61], v[134:137], v[178:181], v[58:61]
	v_mfma_f32_16x16x32_bf16 v[50:53], v[138:141], v[174:177], v[50:53]
	v_mfma_f32_16x16x32_bf16 v[50:53], v[142:145], v[178:181], v[50:53]
	v_mfma_f32_16x16x32_bf16 v[42:45], v[130:133], v[182:185], v[42:45]
	v_mfma_f32_16x16x32_bf16 v[42:45], v[134:137], v[186:189], v[42:45]
	v_mfma_f32_16x16x32_bf16 v[34:37], v[138:141], v[182:185], v[34:37]
	v_mfma_f32_16x16x32_bf16 v[34:37], v[142:145], v[186:189], v[34:37]
	v_mfma_f32_16x16x32_bf16 v[26:29], v[130:133], v[190:193], v[26:29]
	v_mfma_f32_16x16x32_bf16 v[26:29], v[134:137], v[200:203], v[26:29]
	v_mfma_f32_16x16x32_bf16 v[18:21], v[138:141], v[190:193], v[18:21]
	v_mfma_f32_16x16x32_bf16 v[18:21], v[142:145], v[200:203], v[18:21]
	v_mfma_f32_16x16x32_bf16 v[10:13], v[130:133], v[208:211], v[10:13]
	v_mfma_f32_16x16x32_bf16 v[10:13], v[134:137], v[212:215], v[10:13]
	v_mfma_f32_16x16x32_bf16 v[2:5], v[138:141], v[208:211], v[2:5]
	v_mfma_f32_16x16x32_bf16 v[2:5], v[142:145], v[212:215], v[2:5]
	v_mfma_f32_16x16x32_bf16 v[62:65], v[146:149], v[174:177], v[62:65]
	v_mfma_f32_16x16x32_bf16 v[62:65], v[150:153], v[178:181], v[62:65]
	v_mfma_f32_16x16x32_bf16 v[54:57], v[154:157], v[174:177], v[54:57]
	v_mfma_f32_16x16x32_bf16 v[54:57], v[170:173], v[178:181], v[54:57]
	v_mfma_f32_16x16x32_bf16 v[46:49], v[146:149], v[182:185], v[46:49]
	v_mfma_f32_16x16x32_bf16 v[46:49], v[150:153], v[186:189], v[46:49]
	v_mfma_f32_16x16x32_bf16 v[38:41], v[154:157], v[182:185], v[38:41]
	v_mfma_f32_16x16x32_bf16 v[38:41], v[170:173], v[186:189], v[38:41]
	v_mfma_f32_16x16x32_bf16 v[30:33], v[146:149], v[190:193], v[30:33]
	v_mfma_f32_16x16x32_bf16 v[30:33], v[150:153], v[200:203], v[30:33]
	v_mfma_f32_16x16x32_bf16 v[22:25], v[154:157], v[190:193], v[22:25]
	v_mfma_f32_16x16x32_bf16 v[22:25], v[170:173], v[200:203], v[22:25]
	v_mfma_f32_16x16x32_bf16 v[14:17], v[146:149], v[208:211], v[14:17]
	v_mfma_f32_16x16x32_bf16 v[14:17], v[150:153], v[212:215], v[14:17]
	v_mfma_f32_16x16x32_bf16 v[6:9], v[154:157], v[208:211], v[6:9]
	v_mfma_f32_16x16x32_bf16 v[6:9], v[170:173], v[212:215], v[6:9]
	s_barrier
	s_add_u32 s18, s18, 0x100
	s_addc_u32 s19, s19, 0
	s_add_u32 s51, s51, 0x100
	s_addc_u32 s52, s52, 0
	s_cmp_ge_i32 s53, s17
	s_mov_b32 s2, s53
	s_cbranch_scc0 .LBB0_634

.LBB0_798:
	s_lshl_b32 s0, s26, 21
	s_and_b32 s0, s0, 0x1fe00000
	v_readlane_b32 s22, v248, 22
	v_readlane_b32 s23, v248, 23
	s_add_u32 s0, s22, s0
	s_addc_u32 s23, s23, 0
	s_lshr_b32 s22, s26, 13
	s_and_b32 s24, s22, 0x7ff80
	s_add_u32 s22, s0, s24
	s_addc_u32 s23, s23, 0
	s_lshl_b32 s0, s26, 13
	s_and_b32 s0, s0, 0x1fe00000
	s_add_u32 s0, s82, s0
	s_addc_u32 s25, s83, 0
	s_add_u32 s24, s0, s24
	s_addc_u32 s25, s25, 0
	s_cmp_lt_i32 s35, 1
	v_cmp_gt_i64_e64 s[26:27], s[26:27], -1
	s_cbranch_scc1 .LBB0_820
	s_and_b64 s[38:39], s[26:27], exec
	s_cselect_b32 s0, s23, s37
	s_cselect_b32 s34, s22, s36
	s_cselect_b32 s56, s25, s3
	s_cselect_b32 s57, s24, s2
	s_add_i32 s58, s35, -2
	s_add_u32 s36, s36, 0x100080
	s_addc_u32 s37, s37, 0
	s_add_u32 s59, s2, 0x100
	s_addc_u32 s60, s3, 0
	s_mov_b32 s2, 0
	ds_read_b128 v[148:151], v144
	ds_read_b128 v[152:155], v144 offset:1024
	ds_read_b128 v[156:159], v144 offset:2048
	ds_read_b128 v[160:163], v144 offset:3072
	ds_read_b128 v[164:167], v145
	ds_read_b128 v[168:171], v145 offset:1024
	ds_read_b128 v[172:175], v145 offset:2048
	ds_read_b128 v[176:179], v145 offset:3072
	s_add_i32 s61, s2, 2
	s_add_u32 s3, s36, 0xfff00080
	s_addc_u32 s38, s37, -1
	s_cmp_eq_u32 s58, s2
	s_cselect_b32 s2, s57, s59
	s_cselect_b32 s39, s0, s38
	s_cselect_b32 s38, s34, s3
	s_cselect_b32 s3, s56, s60
	s_add_i32 m0, s29, 0xc000
	ds_read_b128 v[180:183], v146
	ds_read_b128 v[184:187], v146 offset:1024
	ds_read_b128 v[188:191], v146 offset:2048
	ds_read_b128 v[192:195], v146 offset:3072
	ds_read_b128 v[196:199], v146 offset:4096
	ds_read_b128 v[200:203], v146 offset:5120
	ds_read_b128 v[208:211], v146 offset:6144
	ds_read_b128 v[212:215], v146 offset:7168
	global_load_lds_dwordx4 v138, s[36:37]
	s_add_i32 m0, s29, 0xe000
	s_nop 0
	global_load_lds_dwordx4 v140, s[36:37]
	s_waitcnt vmcnt(8)
	s_waitcnt lgkmcnt(0)
	s_barrier
	s_waitcnt lgkmcnt(0)
	v_mfma_f32_16x16x32_bf16 v[126:129], v[148:151], v[180:183], 0
	v_mfma_f32_16x16x32_bf16 v[126:129], v[152:155], v[184:187], v[126:129]
	v_mfma_f32_16x16x32_bf16 v[122:125], v[156:159], v[180:183], 0
	v_mfma_f32_16x16x32_bf16 v[122:125], v[160:163], v[184:187], v[122:125]
	v_mfma_f32_16x16x32_bf16 v[110:113], v[148:151], v[188:191], 0
	v_mfma_f32_16x16x32_bf16 v[110:113], v[152:155], v[192:195], v[110:113]
	v_mfma_f32_16x16x32_bf16 v[102:105], v[156:159], v[188:191], 0
	v_mfma_f32_16x16x32_bf16 v[102:105], v[160:163], v[192:195], v[102:105]
	v_mfma_f32_16x16x32_bf16 v[94:97], v[148:151], v[196:199], 0
	v_mfma_f32_16x16x32_bf16 v[94:97], v[152:155], v[200:203], v[94:97]
	v_mfma_f32_16x16x32_bf16 v[86:89], v[156:159], v[196:199], 0
	v_mfma_f32_16x16x32_bf16 v[86:89], v[160:163], v[200:203], v[86:89]
	v_mfma_f32_16x16x32_bf16 v[78:81], v[148:151], v[208:211], 0
	v_mfma_f32_16x16x32_bf16 v[78:81], v[152:155], v[212:215], v[78:81]
	v_mfma_f32_16x16x32_bf16 v[70:73], v[156:159], v[208:211], 0
	v_mfma_f32_16x16x32_bf16 v[70:73], v[160:163], v[212:215], v[70:73]
	v_mfma_f32_16x16x32_bf16 v[118:121], v[164:167], v[180:183], 0
	v_mfma_f32_16x16x32_bf16 v[118:121], v[168:171], v[184:187], v[118:121]
	v_mfma_f32_16x16x32_bf16 v[114:117], v[172:175], v[180:183], 0
	v_mfma_f32_16x16x32_bf16 v[114:117], v[176:179], v[184:187], v[114:117]
	v_mfma_f32_16x16x32_bf16 v[106:109], v[164:167], v[188:191], 0
	v_mfma_f32_16x16x32_bf16 v[106:109], v[168:171], v[192:195], v[106:109]
	v_mfma_f32_16x16x32_bf16 v[98:101], v[172:175], v[188:191], 0
	v_mfma_f32_16x16x32_bf16 v[98:101], v[176:179], v[192:195], v[98:101]
	v_mfma_f32_16x16x32_bf16 v[90:93], v[164:167], v[196:199], 0
	v_mfma_f32_16x16x32_bf16 v[90:93], v[168:171], v[200:203], v[90:93]
	v_mfma_f32_16x16x32_bf16 v[82:85], v[172:175], v[196:199], 0
	v_mfma_f32_16x16x32_bf16 v[82:85], v[176:179], v[200:203], v[82:85]
	v_mfma_f32_16x16x32_bf16 v[74:77], v[164:167], v[208:211], 0
	v_mfma_f32_16x16x32_bf16 v[74:77], v[168:171], v[212:215], v[74:77]
	v_mfma_f32_16x16x32_bf16 v[66:69], v[172:175], v[208:211], 0
	v_mfma_f32_16x16x32_bf16 v[66:69], v[176:179], v[212:215], v[66:69]
	s_barrier
	s_add_i32 s64, s50, s33
	s_mov_b32 m0, s64
	ds_read_b128 v[180:183], v146 offset:16384
	ds_read_b128 v[184:187], v146 offset:17408
	ds_read_b128 v[188:191], v146 offset:18432
	ds_read_b128 v[192:195], v146 offset:19456
	ds_read_b128 v[196:199], v146 offset:20480
	ds_read_b128 v[200:203], v146 offset:21504
	ds_read_b128 v[208:211], v146 offset:22528
	ds_read_b128 v[212:215], v146 offset:23552
	global_load_lds_dwordx4 v132, s[2:3]
	s_add_i32 m0, s64, 0x2000
	s_add_u32 s64, s2, 0x100000
	s_addc_u32 s65, s3, 0
	s_add_i32 s66, s51, s33
	global_load_lds_dwordx4 v136, s[2:3]
	s_mov_b32 m0, s66
	v_lshl_add_u64 v[220:221], s[38:39], 0, v[134:135]
	global_load_lds_dwordx4 v132, s[64:65]
	s_add_i32 m0, s66, 0x2000
	s_nop 0
	global_load_lds_dwordx4 v136, s[64:65]
	v_lshl_add_u64 v[218:219], s[38:39], 0, v[130:131]
	s_mov_b32 m0, s29
	s_nop 0
	global_load_lds_dwordx4 v130, s[38:39]
	s_mov_b32 m0, s31
	s_nop 0
	global_load_lds_dwordx4 v134, s[38:39]
	s_waitcnt vmcnt(8)
	s_waitcnt lgkmcnt(0)
	s_barrier
	s_waitcnt lgkmcnt(0)
	v_mfma_f32_16x16x32_bf16 v[62:65], v[148:151], v[180:183], 0
	v_mfma_f32_16x16x32_bf16 v[62:65], v[152:155], v[184:187], v[62:65]
	v_mfma_f32_16x16x32_bf16 v[54:57], v[156:159], v[180:183], 0
	v_mfma_f32_16x16x32_bf16 v[54:57], v[160:163], v[184:187], v[54:57]
	v_mfma_f32_16x16x32_bf16 v[46:49], v[148:151], v[188:191], 0
	v_mfma_f32_16x16x32_bf16 v[46:49], v[152:155], v[192:195], v[46:49]
	v_mfma_f32_16x16x32_bf16 v[38:41], v[156:159], v[188:191], 0
	v_mfma_f32_16x16x32_bf16 v[38:41], v[160:163], v[192:195], v[38:41]
	v_mfma_f32_16x16x32_bf16 v[30:33], v[148:151], v[196:199], 0
	v_mfma_f32_16x16x32_bf16 v[30:33], v[152:155], v[200:203], v[30:33]
	v_mfma_f32_16x16x32_bf16 v[22:25], v[156:159], v[196:199], 0
	v_mfma_f32_16x16x32_bf16 v[22:25], v[160:163], v[200:203], v[22:25]
	v_mfma_f32_16x16x32_bf16 v[14:17], v[148:151], v[208:211], 0
	v_mfma_f32_16x16x32_bf16 v[14:17], v[152:155], v[212:215], v[14:17]
	v_mfma_f32_16x16x32_bf16 v[6:9], v[156:159], v[208:211], 0
	v_mfma_f32_16x16x32_bf16 v[6:9], v[160:163], v[212:215], v[6:9]
	v_mfma_f32_16x16x32_bf16 v[58:61], v[164:167], v[180:183], 0
	v_mfma_f32_16x16x32_bf16 v[58:61], v[168:171], v[184:187], v[58:61]
	v_mfma_f32_16x16x32_bf16 v[50:53], v[172:175], v[180:183], 0
	v_mfma_f32_16x16x32_bf16 v[50:53], v[176:179], v[184:187], v[50:53]
	v_mfma_f32_16x16x32_bf16 v[42:45], v[164:167], v[188:191], 0
	v_mfma_f32_16x16x32_bf16 v[42:45], v[168:171], v[192:195], v[42:45]
	v_mfma_f32_16x16x32_bf16 v[34:37], v[172:175], v[188:191], 0
	v_mfma_f32_16x16x32_bf16 v[34:37], v[176:179], v[192:195], v[34:37]
	v_mfma_f32_16x16x32_bf16 v[26:29], v[164:167], v[196:199], 0
	v_mfma_f32_16x16x32_bf16 v[26:29], v[168:171], v[200:203], v[26:29]
	v_mfma_f32_16x16x32_bf16 v[18:21], v[172:175], v[196:199], 0
	v_mfma_f32_16x16x32_bf16 v[18:21], v[176:179], v[200:203], v[18:21]
	v_mfma_f32_16x16x32_bf16 v[10:13], v[164:167], v[208:211], 0
	v_mfma_f32_16x16x32_bf16 v[10:13], v[168:171], v[212:215], v[10:13]
	v_mfma_f32_16x16x32_bf16 v[2:5], v[172:175], v[208:211], 0
	v_mfma_f32_16x16x32_bf16 v[2:5], v[176:179], v[212:215], v[2:5]
	s_barrier
	s_add_i32 s64, 0, 0x18000
	v_add_u32_e32 v147, s64, v142
	s_add_i32 s65, 0, 0x1c000
	ds_read_b128 v[148:151], v147
	ds_read_b128 v[152:155], v147 offset:1024
	ds_read_b128 v[156:159], v147 offset:2048
	ds_read_b128 v[160:163], v147 offset:3072
	v_add_u32_e32 v147, s65, v142
	ds_read_b128 v[164:167], v147
	ds_read_b128 v[168:171], v147 offset:1024
	ds_read_b128 v[172:175], v147 offset:2048
	ds_read_b128 v[176:179], v147 offset:3072
	s_add_u32 s38, s38, 0x100000
	s_addc_u32 s39, s39, 0
	s_mov_b32 m0, s41
	ds_read_b128 v[180:183], v146 offset:32768
	ds_read_b128 v[184:187], v146 offset:33792
	ds_read_b128 v[188:191], v146 offset:34816
	ds_read_b128 v[192:195], v146 offset:35840
	ds_read_b128 v[196:199], v146 offset:36864
	ds_read_b128 v[200:203], v146 offset:37888
	ds_read_b128 v[208:211], v146 offset:38912
	ds_read_b128 v[212:215], v146 offset:39936
	global_load_lds_dwordx4 v130, s[38:39]
	s_mov_b32 m0, s42
	s_nop 0
	global_load_lds_dwordx4 v134, s[38:39]
	s_waitcnt vmcnt(8)
	s_waitcnt lgkmcnt(0)
	s_barrier
	s_waitcnt lgkmcnt(0)
	v_mfma_f32_16x16x32_bf16 v[126:129], v[148:151], v[180:183], v[126:129]
	v_mfma_f32_16x16x32_bf16 v[126:129], v[152:155], v[184:187], v[126:129]
	v_mfma_f32_16x16x32_bf16 v[122:125], v[156:159], v[180:183], v[122:125]
	v_mfma_f32_16x16x32_bf16 v[122:125], v[160:163], v[184:187], v[122:125]
	v_mfma_f32_16x16x32_bf16 v[110:113], v[148:151], v[188:191], v[110:113]
	v_mfma_f32_16x16x32_bf16 v[110:113], v[152:155], v[192:195], v[110:113]
	v_mfma_f32_16x16x32_bf16 v[102:105], v[156:159], v[188:191], v[102:105]
	v_mfma_f32_16x16x32_bf16 v[102:105], v[160:163], v[192:195], v[102:105]
	v_mfma_f32_16x16x32_bf16 v[94:97], v[148:151], v[196:199], v[94:97]
	v_mfma_f32_16x16x32_bf16 v[94:97], v[152:155], v[200:203], v[94:97]
	v_mfma_f32_16x16x32_bf16 v[86:89], v[156:159], v[196:199], v[86:89]
	v_mfma_f32_16x16x32_bf16 v[86:89], v[160:163], v[200:203], v[86:89]
	v_mfma_f32_16x16x32_bf16 v[78:81], v[148:151], v[208:211], v[78:81]
	v_mfma_f32_16x16x32_bf16 v[78:81], v[152:155], v[212:215], v[78:81]
	v_mfma_f32_16x16x32_bf16 v[70:73], v[156:159], v[208:211], v[70:73]
	v_mfma_f32_16x16x32_bf16 v[70:73], v[160:163], v[212:215], v[70:73]
	v_mfma_f32_16x16x32_bf16 v[118:121], v[164:167], v[180:183], v[118:121]
	v_mfma_f32_16x16x32_bf16 v[118:121], v[168:171], v[184:187], v[118:121]
	v_mfma_f32_16x16x32_bf16 v[114:117], v[172:175], v[180:183], v[114:117]
	v_mfma_f32_16x16x32_bf16 v[114:117], v[176:179], v[184:187], v[114:117]
	v_mfma_f32_16x16x32_bf16 v[106:109], v[164:167], v[188:191], v[106:109]
	v_mfma_f32_16x16x32_bf16 v[106:109], v[168:171], v[192:195], v[106:109]
	v_mfma_f32_16x16x32_bf16 v[98:101], v[172:175], v[188:191], v[98:101]
	v_mfma_f32_16x16x32_bf16 v[98:101], v[176:179], v[192:195], v[98:101]
	v_mfma_f32_16x16x32_bf16 v[90:93], v[164:167], v[196:199], v[90:93]
	v_mfma_f32_16x16x32_bf16 v[90:93], v[168:171], v[200:203], v[90:93]
	v_mfma_f32_16x16x32_bf16 v[82:85], v[172:175], v[196:199], v[82:85]
	v_mfma_f32_16x16x32_bf16 v[82:85], v[176:179], v[200:203], v[82:85]
	v_mfma_f32_16x16x32_bf16 v[74:77], v[164:167], v[208:211], v[74:77]
	v_mfma_f32_16x16x32_bf16 v[74:77], v[168:171], v[212:215], v[74:77]
	v_mfma_f32_16x16x32_bf16 v[66:69], v[172:175], v[208:211], v[66:69]
	v_mfma_f32_16x16x32_bf16 v[66:69], v[176:179], v[212:215], v[66:69]
	s_barrier
	s_add_i32 s38, s64, s33
	s_add_u32 s98, s2, s16
	s_addc_u32 s99, s3, s17
	s_mov_b32 m0, s38
	ds_read_b128 v[180:183], v146 offset:49152
	ds_read_b128 v[184:187], v146 offset:50176
	ds_read_b128 v[188:191], v146 offset:51200
	ds_read_b128 v[192:195], v146 offset:52224
	ds_read_b128 v[196:199], v146 offset:53248
	ds_read_b128 v[200:203], v146 offset:54272
	ds_read_b128 v[208:211], v146 offset:55296
	ds_read_b128 v[212:215], v146 offset:56320
	global_load_lds_dwordx4 v132, s[98:99]
	s_add_i32 m0, s38, 0x2000
	s_add_u32 s2, s2, 0x100080
	s_addc_u32 s3, s3, 0
	s_add_i32 s38, s65, s33
	global_load_lds_dwordx4 v136, s[98:99]
	s_mov_b32 m0, s38
	s_nop 0
	global_load_lds_dwordx4 v132, s[2:3]
	s_add_i32 m0, s38, 0x2000
	s_nop 0
	global_load_lds_dwordx4 v136, s[2:3]
	v_lshl_add_u64 v[204:205], v[218:219], 0, s[16:17]
	s_mov_b32 m0, s44
	s_nop 0
	global_load_lds_dwordx4 v[204:205], off
	v_lshl_add_u64 v[204:205], v[220:221], 0, s[16:17]
	s_mov_b32 m0, s45
	s_nop 0
	global_load_lds_dwordx4 v[204:205], off
	s_waitcnt vmcnt(8)
	s_waitcnt lgkmcnt(0)
	s_barrier
	s_waitcnt lgkmcnt(0)
	v_mfma_f32_16x16x32_bf16 v[62:65], v[148:151], v[180:183], v[62:65]
	v_mfma_f32_16x16x32_bf16 v[62:65], v[152:155], v[184:187], v[62:65]
	v_mfma_f32_16x16x32_bf16 v[54:57], v[156:159], v[180:183], v[54:57]
	v_mfma_f32_16x16x32_bf16 v[54:57], v[160:163], v[184:187], v[54:57]
	v_mfma_f32_16x16x32_bf16 v[46:49], v[148:151], v[188:191], v[46:49]
	v_mfma_f32_16x16x32_bf16 v[46:49], v[152:155], v[192:195], v[46:49]
	v_mfma_f32_16x16x32_bf16 v[38:41], v[156:159], v[188:191], v[38:41]
	v_mfma_f32_16x16x32_bf16 v[38:41], v[160:163], v[192:195], v[38:41]
	v_mfma_f32_16x16x32_bf16 v[30:33], v[148:151], v[196:199], v[30:33]
	v_mfma_f32_16x16x32_bf16 v[30:33], v[152:155], v[200:203], v[30:33]
	v_mfma_f32_16x16x32_bf16 v[22:25], v[156:159], v[196:199], v[22:25]
	v_mfma_f32_16x16x32_bf16 v[22:25], v[160:163], v[200:203], v[22:25]
	v_mfma_f32_16x16x32_bf16 v[14:17], v[148:151], v[208:211], v[14:17]
	v_mfma_f32_16x16x32_bf16 v[14:17], v[152:155], v[212:215], v[14:17]
	v_mfma_f32_16x16x32_bf16 v[6:9], v[156:159], v[208:211], v[6:9]
	v_mfma_f32_16x16x32_bf16 v[6:9], v[160:163], v[212:215], v[6:9]
	v_mfma_f32_16x16x32_bf16 v[58:61], v[164:167], v[180:183], v[58:61]
	v_mfma_f32_16x16x32_bf16 v[58:61], v[168:171], v[184:187], v[58:61]
	v_mfma_f32_16x16x32_bf16 v[50:53], v[172:175], v[180:183], v[50:53]
	v_mfma_f32_16x16x32_bf16 v[50:53], v[176:179], v[184:187], v[50:53]
	v_mfma_f32_16x16x32_bf16 v[42:45], v[164:167], v[188:191], v[42:45]
	v_mfma_f32_16x16x32_bf16 v[42:45], v[168:171], v[192:195], v[42:45]
	v_mfma_f32_16x16x32_bf16 v[34:37], v[172:175], v[188:191], v[34:37]
	v_mfma_f32_16x16x32_bf16 v[34:37], v[176:179], v[192:195], v[34:37]
	v_mfma_f32_16x16x32_bf16 v[26:29], v[164:167], v[196:199], v[26:29]
	v_mfma_f32_16x16x32_bf16 v[26:29], v[168:171], v[200:203], v[26:29]
	v_mfma_f32_16x16x32_bf16 v[18:21], v[172:175], v[196:199], v[18:21]
	v_mfma_f32_16x16x32_bf16 v[18:21], v[176:179], v[200:203], v[18:21]
	v_mfma_f32_16x16x32_bf16 v[10:13], v[164:167], v[208:211], v[10:13]
	v_mfma_f32_16x16x32_bf16 v[10:13], v[168:171], v[212:215], v[10:13]
	v_mfma_f32_16x16x32_bf16 v[2:5], v[172:175], v[208:211], v[2:5]
	v_mfma_f32_16x16x32_bf16 v[2:5], v[176:179], v[212:215], v[2:5]
	s_barrier
	s_add_u32 s36, s36, 0x100
	s_addc_u32 s37, s37, 0
	s_add_u32 s59, s59, 0x100
	s_addc_u32 s60, s60, 0
	s_cmp_ge_i32 s61, s35
	s_mov_b32 s2, s61
	s_cbranch_scc1 .Lkpeel_exit_4
.LBB0_800:
	ds_read_b128 v[148:151], v144
	ds_read_b128 v[152:155], v144 offset:1024
	ds_read_b128 v[156:159], v144 offset:2048
	ds_read_b128 v[160:163], v144 offset:3072
	ds_read_b128 v[164:167], v145
	ds_read_b128 v[168:171], v145 offset:1024
	ds_read_b128 v[172:175], v145 offset:2048
	ds_read_b128 v[176:179], v145 offset:3072
	s_add_i32 s61, s2, 2
	s_add_u32 s3, s36, 0xfff00080
	s_addc_u32 s38, s37, -1
	s_cmp_eq_u32 s58, s2
	s_cselect_b32 s2, s57, s59
	s_cselect_b32 s39, s0, s38
	s_cselect_b32 s38, s34, s3
	s_cselect_b32 s3, s56, s60
	s_add_i32 m0, s29, 0xc000
	ds_read_b128 v[180:183], v146
	ds_read_b128 v[184:187], v146 offset:1024
	ds_read_b128 v[188:191], v146 offset:2048
	ds_read_b128 v[192:195], v146 offset:3072
	ds_read_b128 v[196:199], v146 offset:4096
	ds_read_b128 v[200:203], v146 offset:5120
	ds_read_b128 v[208:211], v146 offset:6144
	ds_read_b128 v[212:215], v146 offset:7168
	global_load_lds_dwordx4 v138, s[36:37]
	s_add_i32 m0, s29, 0xe000
	s_nop 0
	global_load_lds_dwordx4 v140, s[36:37]
	s_waitcnt vmcnt(8)
	s_waitcnt lgkmcnt(0)
	s_barrier
	s_waitcnt lgkmcnt(0)
	v_mfma_f32_16x16x32_bf16 v[126:129], v[148:151], v[180:183], v[126:129]
	v_mfma_f32_16x16x32_bf16 v[126:129], v[152:155], v[184:187], v[126:129]
	v_mfma_f32_16x16x32_bf16 v[122:125], v[156:159], v[180:183], v[122:125]
	v_mfma_f32_16x16x32_bf16 v[122:125], v[160:163], v[184:187], v[122:125]
	v_mfma_f32_16x16x32_bf16 v[110:113], v[148:151], v[188:191], v[110:113]
	v_mfma_f32_16x16x32_bf16 v[110:113], v[152:155], v[192:195], v[110:113]
	v_mfma_f32_16x16x32_bf16 v[102:105], v[156:159], v[188:191], v[102:105]
	v_mfma_f32_16x16x32_bf16 v[102:105], v[160:163], v[192:195], v[102:105]
	v_mfma_f32_16x16x32_bf16 v[94:97], v[148:151], v[196:199], v[94:97]
	v_mfma_f32_16x16x32_bf16 v[94:97], v[152:155], v[200:203], v[94:97]
	v_mfma_f32_16x16x32_bf16 v[86:89], v[156:159], v[196:199], v[86:89]
	v_mfma_f32_16x16x32_bf16 v[86:89], v[160:163], v[200:203], v[86:89]
	v_mfma_f32_16x16x32_bf16 v[78:81], v[148:151], v[208:211], v[78:81]
	v_mfma_f32_16x16x32_bf16 v[78:81], v[152:155], v[212:215], v[78:81]
	v_mfma_f32_16x16x32_bf16 v[70:73], v[156:159], v[208:211], v[70:73]
	v_mfma_f32_16x16x32_bf16 v[70:73], v[160:163], v[212:215], v[70:73]
	v_mfma_f32_16x16x32_bf16 v[118:121], v[164:167], v[180:183], v[118:121]
	v_mfma_f32_16x16x32_bf16 v[118:121], v[168:171], v[184:187], v[118:121]
	v_mfma_f32_16x16x32_bf16 v[114:117], v[172:175], v[180:183], v[114:117]
	v_mfma_f32_16x16x32_bf16 v[114:117], v[176:179], v[184:187], v[114:117]
	v_mfma_f32_16x16x32_bf16 v[106:109], v[164:167], v[188:191], v[106:109]
	v_mfma_f32_16x16x32_bf16 v[106:109], v[168:171], v[192:195], v[106:109]
	v_mfma_f32_16x16x32_bf16 v[98:101], v[172:175], v[188:191], v[98:101]
	v_mfma_f32_16x16x32_bf16 v[98:101], v[176:179], v[192:195], v[98:101]
	v_mfma_f32_16x16x32_bf16 v[90:93], v[164:167], v[196:199], v[90:93]
	v_mfma_f32_16x16x32_bf16 v[90:93], v[168:171], v[200:203], v[90:93]
	v_mfma_f32_16x16x32_bf16 v[82:85], v[172:175], v[196:199], v[82:85]
	v_mfma_f32_16x16x32_bf16 v[82:85], v[176:179], v[200:203], v[82:85]
	v_mfma_f32_16x16x32_bf16 v[74:77], v[164:167], v[208:211], v[74:77]
	v_mfma_f32_16x16x32_bf16 v[74:77], v[168:171], v[212:215], v[74:77]
	v_mfma_f32_16x16x32_bf16 v[66:69], v[172:175], v[208:211], v[66:69]
	v_mfma_f32_16x16x32_bf16 v[66:69], v[176:179], v[212:215], v[66:69]
	s_barrier
	s_add_i32 s64, s50, s33
	s_mov_b32 m0, s64
	ds_read_b128 v[180:183], v146 offset:16384
	ds_read_b128 v[184:187], v146 offset:17408
	ds_read_b128 v[188:191], v146 offset:18432
	ds_read_b128 v[192:195], v146 offset:19456
	ds_read_b128 v[196:199], v146 offset:20480
	ds_read_b128 v[200:203], v146 offset:21504
	ds_read_b128 v[208:211], v146 offset:22528
	ds_read_b128 v[212:215], v146 offset:23552
	global_load_lds_dwordx4 v132, s[2:3]
	s_add_i32 m0, s64, 0x2000
	s_add_u32 s64, s2, 0x100000
	s_addc_u32 s65, s3, 0
	s_add_i32 s66, s51, s33
	global_load_lds_dwordx4 v136, s[2:3]
	s_mov_b32 m0, s66
	v_lshl_add_u64 v[220:221], s[38:39], 0, v[134:135]
	global_load_lds_dwordx4 v132, s[64:65]
	s_add_i32 m0, s66, 0x2000
	s_nop 0
	global_load_lds_dwordx4 v136, s[64:65]
	v_lshl_add_u64 v[218:219], s[38:39], 0, v[130:131]
	s_mov_b32 m0, s29
	s_nop 0
	global_load_lds_dwordx4 v130, s[38:39]
	s_mov_b32 m0, s31
	s_nop 0
	global_load_lds_dwordx4 v134, s[38:39]
	s_waitcnt vmcnt(8)
	s_waitcnt lgkmcnt(0)
	s_barrier
	s_waitcnt lgkmcnt(0)
	v_mfma_f32_16x16x32_bf16 v[62:65], v[148:151], v[180:183], v[62:65]
	v_mfma_f32_16x16x32_bf16 v[62:65], v[152:155], v[184:187], v[62:65]
	v_mfma_f32_16x16x32_bf16 v[54:57], v[156:159], v[180:183], v[54:57]
	v_mfma_f32_16x16x32_bf16 v[54:57], v[160:163], v[184:187], v[54:57]
	v_mfma_f32_16x16x32_bf16 v[46:49], v[148:151], v[188:191], v[46:49]
	v_mfma_f32_16x16x32_bf16 v[46:49], v[152:155], v[192:195], v[46:49]
	v_mfma_f32_16x16x32_bf16 v[38:41], v[156:159], v[188:191], v[38:41]
	v_mfma_f32_16x16x32_bf16 v[38:41], v[160:163], v[192:195], v[38:41]
	v_mfma_f32_16x16x32_bf16 v[30:33], v[148:151], v[196:199], v[30:33]
	v_mfma_f32_16x16x32_bf16 v[30:33], v[152:155], v[200:203], v[30:33]
	v_mfma_f32_16x16x32_bf16 v[22:25], v[156:159], v[196:199], v[22:25]
	v_mfma_f32_16x16x32_bf16 v[22:25], v[160:163], v[200:203], v[22:25]
	v_mfma_f32_16x16x32_bf16 v[14:17], v[148:151], v[208:211], v[14:17]
	v_mfma_f32_16x16x32_bf16 v[14:17], v[152:155], v[212:215], v[14:17]
	v_mfma_f32_16x16x32_bf16 v[6:9], v[156:159], v[208:211], v[6:9]
	v_mfma_f32_16x16x32_bf16 v[6:9], v[160:163], v[212:215], v[6:9]
	v_mfma_f32_16x16x32_bf16 v[58:61], v[164:167], v[180:183], v[58:61]
	v_mfma_f32_16x16x32_bf16 v[58:61], v[168:171], v[184:187], v[58:61]
	v_mfma_f32_16x16x32_bf16 v[50:53], v[172:175], v[180:183], v[50:53]
	v_mfma_f32_16x16x32_bf16 v[50:53], v[176:179], v[184:187], v[50:53]
	v_mfma_f32_16x16x32_bf16 v[42:45], v[164:167], v[188:191], v[42:45]
	v_mfma_f32_16x16x32_bf16 v[42:45], v[168:171], v[192:195], v[42:45]
	v_mfma_f32_16x16x32_bf16 v[34:37], v[172:175], v[188:191], v[34:37]
	v_mfma_f32_16x16x32_bf16 v[34:37], v[176:179], v[192:195], v[34:37]
	v_mfma_f32_16x16x32_bf16 v[26:29], v[164:167], v[196:199], v[26:29]
	v_mfma_f32_16x16x32_bf16 v[26:29], v[168:171], v[200:203], v[26:29]
	v_mfma_f32_16x16x32_bf16 v[18:21], v[172:175], v[196:199], v[18:21]
	v_mfma_f32_16x16x32_bf16 v[18:21], v[176:179], v[200:203], v[18:21]
	v_mfma_f32_16x16x32_bf16 v[10:13], v[164:167], v[208:211], v[10:13]
	v_mfma_f32_16x16x32_bf16 v[10:13], v[168:171], v[212:215], v[10:13]
	v_mfma_f32_16x16x32_bf16 v[2:5], v[172:175], v[208:211], v[2:5]
	v_mfma_f32_16x16x32_bf16 v[2:5], v[176:179], v[212:215], v[2:5]
	s_barrier
	s_add_i32 s64, 0, 0x18000
	v_add_u32_e32 v147, s64, v142
	s_add_i32 s65, 0, 0x1c000
	ds_read_b128 v[148:151], v147
	ds_read_b128 v[152:155], v147 offset:1024
	ds_read_b128 v[156:159], v147 offset:2048
	ds_read_b128 v[160:163], v147 offset:3072
	v_add_u32_e32 v147, s65, v142
	ds_read_b128 v[164:167], v147
	ds_read_b128 v[168:171], v147 offset:1024
	ds_read_b128 v[172:175], v147 offset:2048
	ds_read_b128 v[176:179], v147 offset:3072
	s_add_u32 s38, s38, 0x100000
	s_addc_u32 s39, s39, 0
	s_mov_b32 m0, s41
	ds_read_b128 v[180:183], v146 offset:32768
	ds_read_b128 v[184:187], v146 offset:33792
	ds_read_b128 v[188:191], v146 offset:34816
	ds_read_b128 v[192:195], v146 offset:35840
	ds_read_b128 v[196:199], v146 offset:36864
	ds_read_b128 v[200:203], v146 offset:37888
	ds_read_b128 v[208:211], v146 offset:38912
	ds_read_b128 v[212:215], v146 offset:39936
	global_load_lds_dwordx4 v130, s[38:39]
	s_mov_b32 m0, s42
	s_nop 0
	global_load_lds_dwordx4 v134, s[38:39]
	s_waitcnt vmcnt(8)
	s_waitcnt lgkmcnt(0)
	s_barrier
	s_waitcnt lgkmcnt(0)
	v_mfma_f32_16x16x32_bf16 v[126:129], v[148:151], v[180:183], v[126:129]
	v_mfma_f32_16x16x32_bf16 v[126:129], v[152:155], v[184:187], v[126:129]
	v_mfma_f32_16x16x32_bf16 v[122:125], v[156:159], v[180:183], v[122:125]
	v_mfma_f32_16x16x32_bf16 v[122:125], v[160:163], v[184:187], v[122:125]
	v_mfma_f32_16x16x32_bf16 v[110:113], v[148:151], v[188:191], v[110:113]
	v_mfma_f32_16x16x32_bf16 v[110:113], v[152:155], v[192:195], v[110:113]
	v_mfma_f32_16x16x32_bf16 v[102:105], v[156:159], v[188:191], v[102:105]
	v_mfma_f32_16x16x32_bf16 v[102:105], v[160:163], v[192:195], v[102:105]
	v_mfma_f32_16x16x32_bf16 v[94:97], v[148:151], v[196:199], v[94:97]
	v_mfma_f32_16x16x32_bf16 v[94:97], v[152:155], v[200:203], v[94:97]
	v_mfma_f32_16x16x32_bf16 v[86:89], v[156:159], v[196:199], v[86:89]
	v_mfma_f32_16x16x32_bf16 v[86:89], v[160:163], v[200:203], v[86:89]
	v_mfma_f32_16x16x32_bf16 v[78:81], v[148:151], v[208:211], v[78:81]
	v_mfma_f32_16x16x32_bf16 v[78:81], v[152:155], v[212:215], v[78:81]
	v_mfma_f32_16x16x32_bf16 v[70:73], v[156:159], v[208:211], v[70:73]
	v_mfma_f32_16x16x32_bf16 v[70:73], v[160:163], v[212:215], v[70:73]
	v_mfma_f32_16x16x32_bf16 v[118:121], v[164:167], v[180:183], v[118:121]
	v_mfma_f32_16x16x32_bf16 v[118:121], v[168:171], v[184:187], v[118:121]
	v_mfma_f32_16x16x32_bf16 v[114:117], v[172:175], v[180:183], v[114:117]
	v_mfma_f32_16x16x32_bf16 v[114:117], v[176:179], v[184:187], v[114:117]
	v_mfma_f32_16x16x32_bf16 v[106:109], v[164:167], v[188:191], v[106:109]
	v_mfma_f32_16x16x32_bf16 v[106:109], v[168:171], v[192:195], v[106:109]
	v_mfma_f32_16x16x32_bf16 v[98:101], v[172:175], v[188:191], v[98:101]
	v_mfma_f32_16x16x32_bf16 v[98:101], v[176:179], v[192:195], v[98:101]
	v_mfma_f32_16x16x32_bf16 v[90:93], v[164:167], v[196:199], v[90:93]
	v_mfma_f32_16x16x32_bf16 v[90:93], v[168:171], v[200:203], v[90:93]
	v_mfma_f32_16x16x32_bf16 v[82:85], v[172:175], v[196:199], v[82:85]
	v_mfma_f32_16x16x32_bf16 v[82:85], v[176:179], v[200:203], v[82:85]
	v_mfma_f32_16x16x32_bf16 v[74:77], v[164:167], v[208:211], v[74:77]
	v_mfma_f32_16x16x32_bf16 v[74:77], v[168:171], v[212:215], v[74:77]
	v_mfma_f32_16x16x32_bf16 v[66:69], v[172:175], v[208:211], v[66:69]
	v_mfma_f32_16x16x32_bf16 v[66:69], v[176:179], v[212:215], v[66:69]
	s_barrier
	s_add_i32 s38, s64, s33
	s_add_u32 s98, s2, s16
	s_addc_u32 s99, s3, s17
	s_mov_b32 m0, s38
	ds_read_b128 v[180:183], v146 offset:49152
	ds_read_b128 v[184:187], v146 offset:50176
	ds_read_b128 v[188:191], v146 offset:51200
	ds_read_b128 v[192:195], v146 offset:52224
	ds_read_b128 v[196:199], v146 offset:53248
	ds_read_b128 v[200:203], v146 offset:54272
	ds_read_b128 v[208:211], v146 offset:55296
	ds_read_b128 v[212:215], v146 offset:56320
	global_load_lds_dwordx4 v132, s[98:99]
	s_add_i32 m0, s38, 0x2000
	s_add_u32 s2, s2, 0x100080
	s_addc_u32 s3, s3, 0
	s_add_i32 s38, s65, s33
	global_load_lds_dwordx4 v136, s[98:99]
	s_mov_b32 m0, s38
	s_nop 0
	global_load_lds_dwordx4 v132, s[2:3]
	s_add_i32 m0, s38, 0x2000
	s_nop 0
	global_load_lds_dwordx4 v136, s[2:3]
	v_lshl_add_u64 v[204:205], v[218:219], 0, s[16:17]
	s_mov_b32 m0, s44
	s_nop 0
	global_load_lds_dwordx4 v[204:205], off
	v_lshl_add_u64 v[204:205], v[220:221], 0, s[16:17]
	s_mov_b32 m0, s45
	s_nop 0
	global_load_lds_dwordx4 v[204:205], off
	s_waitcnt vmcnt(8)
	s_waitcnt lgkmcnt(0)
	s_barrier
	s_waitcnt lgkmcnt(0)
	v_mfma_f32_16x16x32_bf16 v[62:65], v[148:151], v[180:183], v[62:65]
	v_mfma_f32_16x16x32_bf16 v[62:65], v[152:155], v[184:187], v[62:65]
	v_mfma_f32_16x16x32_bf16 v[54:57], v[156:159], v[180:183], v[54:57]
	v_mfma_f32_16x16x32_bf16 v[54:57], v[160:163], v[184:187], v[54:57]
	v_mfma_f32_16x16x32_bf16 v[46:49], v[148:151], v[188:191], v[46:49]
	v_mfma_f32_16x16x32_bf16 v[46:49], v[152:155], v[192:195], v[46:49]
	v_mfma_f32_16x16x32_bf16 v[38:41], v[156:159], v[188:191], v[38:41]
	v_mfma_f32_16x16x32_bf16 v[38:41], v[160:163], v[192:195], v[38:41]
	v_mfma_f32_16x16x32_bf16 v[30:33], v[148:151], v[196:199], v[30:33]
	v_mfma_f32_16x16x32_bf16 v[30:33], v[152:155], v[200:203], v[30:33]
	v_mfma_f32_16x16x32_bf16 v[22:25], v[156:159], v[196:199], v[22:25]
	v_mfma_f32_16x16x32_bf16 v[22:25], v[160:163], v[200:203], v[22:25]
	v_mfma_f32_16x16x32_bf16 v[14:17], v[148:151], v[208:211], v[14:17]
	v_mfma_f32_16x16x32_bf16 v[14:17], v[152:155], v[212:215], v[14:17]
	v_mfma_f32_16x16x32_bf16 v[6:9], v[156:159], v[208:211], v[6:9]
	v_mfma_f32_16x16x32_bf16 v[6:9], v[160:163], v[212:215], v[6:9]
	v_mfma_f32_16x16x32_bf16 v[58:61], v[164:167], v[180:183], v[58:61]
	v_mfma_f32_16x16x32_bf16 v[58:61], v[168:171], v[184:187], v[58:61]
	v_mfma_f32_16x16x32_bf16 v[50:53], v[172:175], v[180:183], v[50:53]
	v_mfma_f32_16x16x32_bf16 v[50:53], v[176:179], v[184:187], v[50:53]
	v_mfma_f32_16x16x32_bf16 v[42:45], v[164:167], v[188:191], v[42:45]
	v_mfma_f32_16x16x32_bf16 v[42:45], v[168:171], v[192:195], v[42:45]
	v_mfma_f32_16x16x32_bf16 v[34:37], v[172:175], v[188:191], v[34:37]
	v_mfma_f32_16x16x32_bf16 v[34:37], v[176:179], v[192:195], v[34:37]
	v_mfma_f32_16x16x32_bf16 v[26:29], v[164:167], v[196:199], v[26:29]
	v_mfma_f32_16x16x32_bf16 v[26:29], v[168:171], v[200:203], v[26:29]
	v_mfma_f32_16x16x32_bf16 v[18:21], v[172:175], v[196:199], v[18:21]
	v_mfma_f32_16x16x32_bf16 v[18:21], v[176:179], v[200:203], v[18:21]
	v_mfma_f32_16x16x32_bf16 v[10:13], v[164:167], v[208:211], v[10:13]
	v_mfma_f32_16x16x32_bf16 v[10:13], v[168:171], v[212:215], v[10:13]
	v_mfma_f32_16x16x32_bf16 v[2:5], v[172:175], v[208:211], v[2:5]
	v_mfma_f32_16x16x32_bf16 v[2:5], v[176:179], v[212:215], v[2:5]
	s_barrier
	s_add_u32 s36, s36, 0x100
	s_addc_u32 s37, s37, 0
	s_add_u32 s59, s59, 0x100
	s_addc_u32 s60, s60, 0
	s_cmp_ge_i32 s61, s35
	s_mov_b32 s2, s61
	s_cbranch_scc0 .LBB0_800

.LBB0_959:
	s_lshl_b32 s0, s16, 20
	s_and_b32 s0, s0, 0xff00000
	v_readlane_b32 s12, v248, 20
	v_readlane_b32 s13, v248, 21
	s_add_u32 s0, s12, s0
	s_addc_u32 s1, s13, 0
	s_lshr_b32 s12, s16, 13
	s_and_b32 s12, s12, 0x7ff80
	s_add_u32 s0, s0, s12
	s_addc_u32 s1, s1, 0
	s_lshl_b32 s13, s16, 12
	s_and_b32 s13, s13, 0xff00000
	v_readlane_b32 s24, v248, 51
	s_add_u32 s13, s24, s13
	v_readlane_b32 s24, v248, 53
	s_addc_u32 s24, s24, 0
	s_add_u32 s12, s13, s12
	s_addc_u32 s13, s24, 0
	s_cmp_lt_i32 s19, 1
	v_cmp_gt_i64_e64 s[16:17], s[16:17], -1
	s_cbranch_scc1 .LBB0_976
	s_and_b64 s[36:37], s[16:17], exec
	s_cselect_b32 s24, s1, s35
	s_cselect_b32 s53, s0, s34
	s_cselect_b32 s56, s13, s3
	s_cselect_b32 s57, s12, s2
	s_add_i32 s58, s19, -2
	s_add_u32 s34, s34, 0x80080
	s_addc_u32 s35, s35, 0
	s_add_u32 s59, s2, 0x100
	s_addc_u32 s60, s3, 0
	s_mov_b32 s2, 0
	s_add_i32 s61, s2, 2
	s_add_u32 s3, s34, 0xfff80080
	s_addc_u32 s36, s35, -1
	s_add_i32 s64, 0, 0x10000
	s_cmp_eq_u32 s58, s2
	s_cselect_b32 s37, s24, s36
	s_cselect_b32 s36, s53, s3
	v_add_u32_e32 v142, s64, v131
	s_cselect_b32 s3, s56, s60
	s_cselect_b32 s2, s57, s59
	s_add_i32 s66, 0, 0x14000
	ds_read_b128 v[148:151], v142
	ds_read_b128 v[152:155], v142 offset:1024
	ds_read_b128 v[156:159], v142 offset:2048
	ds_read_b128 v[160:163], v142 offset:3072
	v_add_u32_e32 v142, s66, v131
	ds_read_b128 v[188:191], v142
	ds_read_b128 v[192:195], v142 offset:1024
	ds_read_b128 v[196:199], v142 offset:2048
	ds_read_b128 v[200:203], v142 offset:3072
	s_add_i32 m0, s40, 0xc000
	ds_read_b128 v[204:207], v186
	ds_read_b128 v[208:211], v186 offset:1024
	ds_read_b128 v[212:215], v186 offset:2048
	ds_read_b128 v[216:219], v186 offset:3072
	ds_read_b128 v[220:223], v186 offset:4096
	ds_read_b128 v[224:227], v186 offset:5120
	ds_read_b128 v[228:231], v186 offset:6144
	ds_read_b128 v[232:235], v186 offset:7168
	global_load_lds_dwordx4 v144, s[34:35]
	s_add_i32 m0, s40, 0xe000
	s_nop 0
	global_load_lds_dwordx4 v146, s[34:35]
	s_waitcnt vmcnt(8)
	s_waitcnt lgkmcnt(0)
	s_barrier
	s_waitcnt lgkmcnt(0)
	v_mfma_i32_16x16x64_i8 v[126:129], v[148:151], v[204:207], 0
	v_mfma_i32_16x16x64_i8 v[126:129], v[152:155], v[208:211], v[126:129]
	v_mfma_i32_16x16x64_i8 v[122:125], v[156:159], v[204:207], 0
	v_mfma_i32_16x16x64_i8 v[122:125], v[160:163], v[208:211], v[122:125]
	v_mfma_i32_16x16x64_i8 v[118:121], v[148:151], v[212:215], 0
	v_mfma_i32_16x16x64_i8 v[118:121], v[152:155], v[216:219], v[118:121]
	v_mfma_i32_16x16x64_i8 v[114:117], v[156:159], v[212:215], 0
	v_mfma_i32_16x16x64_i8 v[114:117], v[160:163], v[216:219], v[114:117]
	v_mfma_i32_16x16x64_i8 v[110:113], v[148:151], v[220:223], 0
	v_mfma_i32_16x16x64_i8 v[110:113], v[152:155], v[224:227], v[110:113]
	v_mfma_i32_16x16x64_i8 v[106:109], v[156:159], v[220:223], 0
	v_mfma_i32_16x16x64_i8 v[106:109], v[160:163], v[224:227], v[106:109]
	v_mfma_i32_16x16x64_i8 v[102:105], v[148:151], v[228:231], 0
	v_mfma_i32_16x16x64_i8 v[102:105], v[152:155], v[232:235], v[102:105]
	v_mfma_i32_16x16x64_i8 v[98:101], v[156:159], v[228:231], 0
	v_mfma_i32_16x16x64_i8 v[98:101], v[160:163], v[232:235], v[98:101]
	v_mfma_i32_16x16x64_i8 v[94:97], v[188:191], v[204:207], 0
	v_mfma_i32_16x16x64_i8 v[94:97], v[192:195], v[208:211], v[94:97]
	v_mfma_i32_16x16x64_i8 v[90:93], v[196:199], v[204:207], 0
	v_mfma_i32_16x16x64_i8 v[90:93], v[200:203], v[208:211], v[90:93]
	v_mfma_i32_16x16x64_i8 v[86:89], v[188:191], v[212:215], 0
	v_mfma_i32_16x16x64_i8 v[86:89], v[192:195], v[216:219], v[86:89]
	v_mfma_i32_16x16x64_i8 v[82:85], v[196:199], v[212:215], 0
	v_mfma_i32_16x16x64_i8 v[82:85], v[200:203], v[216:219], v[82:85]
	v_mfma_i32_16x16x64_i8 v[78:81], v[188:191], v[220:223], 0
	v_mfma_i32_16x16x64_i8 v[78:81], v[192:195], v[224:227], v[78:81]
	v_mfma_i32_16x16x64_i8 v[74:77], v[196:199], v[220:223], 0
	v_mfma_i32_16x16x64_i8 v[74:77], v[200:203], v[224:227], v[74:77]
	v_mfma_i32_16x16x64_i8 v[70:73], v[188:191], v[228:231], 0
	v_mfma_i32_16x16x64_i8 v[70:73], v[192:195], v[232:235], v[70:73]
	v_mfma_i32_16x16x64_i8 v[66:69], v[196:199], v[228:231], 0
	v_mfma_i32_16x16x64_i8 v[66:69], v[200:203], v[232:235], v[66:69]
	s_barrier
	s_add_i32 s64, s64, s39
	s_mov_b32 m0, s64
	ds_read_b128 v[204:207], v186 offset:16384
	ds_read_b128 v[208:211], v186 offset:17408
	ds_read_b128 v[212:215], v186 offset:18432
	ds_read_b128 v[216:219], v186 offset:19456
	ds_read_b128 v[220:223], v186 offset:20480
	ds_read_b128 v[224:227], v186 offset:21504
	ds_read_b128 v[228:231], v186 offset:22528
	ds_read_b128 v[232:235], v186 offset:23552
	global_load_lds_dwordx4 v136, s[2:3]
	s_add_i32 m0, s64, 0x2000
	s_add_u32 s64, s2, 0x80000
	s_addc_u32 s65, s3, 0
	s_add_i32 s66, s66, s39
	global_load_lds_dwordx4 v140, s[2:3]
	s_mov_b32 m0, s66
	v_lshl_add_u64 v[242:243], s[36:37], 0, v[138:139]
	global_load_lds_dwordx4 v136, s[64:65]
	s_add_i32 m0, s66, 0x2000
	s_nop 0
	global_load_lds_dwordx4 v140, s[64:65]
	v_lshl_add_u64 v[240:241], s[36:37], 0, v[134:135]
	s_mov_b32 m0, s40
	s_nop 0
	global_load_lds_dwordx4 v134, s[36:37]
	s_mov_b32 m0, s41
	s_nop 0
	global_load_lds_dwordx4 v138, s[36:37]
	s_waitcnt vmcnt(8)
	s_waitcnt lgkmcnt(0)
	s_barrier
	s_waitcnt lgkmcnt(0)
	v_mfma_i32_16x16x64_i8 v[62:65], v[148:151], v[204:207], 0
	v_mfma_i32_16x16x64_i8 v[62:65], v[152:155], v[208:211], v[62:65]
	v_mfma_i32_16x16x64_i8 v[58:61], v[156:159], v[204:207], 0
	v_mfma_i32_16x16x64_i8 v[58:61], v[160:163], v[208:211], v[58:61]
	v_mfma_i32_16x16x64_i8 v[54:57], v[148:151], v[212:215], 0
	v_mfma_i32_16x16x64_i8 v[54:57], v[152:155], v[216:219], v[54:57]
	v_mfma_i32_16x16x64_i8 v[50:53], v[156:159], v[212:215], 0
	v_mfma_i32_16x16x64_i8 v[50:53], v[160:163], v[216:219], v[50:53]
	v_mfma_i32_16x16x64_i8 v[46:49], v[148:151], v[220:223], 0
	v_mfma_i32_16x16x64_i8 v[46:49], v[152:155], v[224:227], v[46:49]
	v_mfma_i32_16x16x64_i8 v[42:45], v[156:159], v[220:223], 0
	v_mfma_i32_16x16x64_i8 v[42:45], v[160:163], v[224:227], v[42:45]
	v_mfma_i32_16x16x64_i8 v[38:41], v[148:151], v[228:231], 0
	v_mfma_i32_16x16x64_i8 v[38:41], v[152:155], v[232:235], v[38:41]
	v_mfma_i32_16x16x64_i8 v[34:37], v[156:159], v[228:231], 0
	v_mfma_i32_16x16x64_i8 v[34:37], v[160:163], v[232:235], v[34:37]
	v_mfma_i32_16x16x64_i8 v[30:33], v[188:191], v[204:207], 0
	v_mfma_i32_16x16x64_i8 v[30:33], v[192:195], v[208:211], v[30:33]
	v_mfma_i32_16x16x64_i8 v[26:29], v[196:199], v[204:207], 0
	v_mfma_i32_16x16x64_i8 v[26:29], v[200:203], v[208:211], v[26:29]
	v_mfma_i32_16x16x64_i8 v[22:25], v[188:191], v[212:215], 0
	v_mfma_i32_16x16x64_i8 v[22:25], v[192:195], v[216:219], v[22:25]
	v_mfma_i32_16x16x64_i8 v[18:21], v[196:199], v[212:215], 0
	v_mfma_i32_16x16x64_i8 v[18:21], v[200:203], v[216:219], v[18:21]
	v_mfma_i32_16x16x64_i8 v[14:17], v[188:191], v[220:223], 0
	v_mfma_i32_16x16x64_i8 v[14:17], v[192:195], v[224:227], v[14:17]
	v_mfma_i32_16x16x64_i8 v[10:13], v[196:199], v[220:223], 0
	v_mfma_i32_16x16x64_i8 v[10:13], v[200:203], v[224:227], v[10:13]
	v_mfma_i32_16x16x64_i8 v[6:9], v[188:191], v[228:231], 0
	v_mfma_i32_16x16x64_i8 v[6:9], v[192:195], v[232:235], v[6:9]
	v_mfma_i32_16x16x64_i8 v[2:5], v[196:199], v[228:231], 0
	v_mfma_i32_16x16x64_i8 v[2:5], v[200:203], v[232:235], v[2:5]
	s_barrier
	s_add_i32 s64, 0, 0x18000
	v_add_u32_e32 v142, s64, v131
	s_add_i32 s65, 0, 0x1c000
	ds_read_b128 v[148:151], v142
	ds_read_b128 v[152:155], v142 offset:1024
	ds_read_b128 v[156:159], v142 offset:2048
	ds_read_b128 v[160:163], v142 offset:3072
	v_add_u32_e32 v142, s65, v131
	ds_read_b128 v[188:191], v142
	ds_read_b128 v[192:195], v142 offset:1024
	ds_read_b128 v[196:199], v142 offset:2048
	ds_read_b128 v[200:203], v142 offset:3072
	s_add_u32 s36, s36, 0x80000
	s_addc_u32 s37, s37, 0
	s_mov_b32 m0, s42
	ds_read_b128 v[204:207], v186 offset:32768
	ds_read_b128 v[208:211], v186 offset:33792
	ds_read_b128 v[212:215], v186 offset:34816
	ds_read_b128 v[216:219], v186 offset:35840
	ds_read_b128 v[220:223], v186 offset:36864
	ds_read_b128 v[224:227], v186 offset:37888
	ds_read_b128 v[228:231], v186 offset:38912
	ds_read_b128 v[232:235], v186 offset:39936
	global_load_lds_dwordx4 v134, s[36:37]
	s_mov_b32 m0, s43
	s_nop 0
	global_load_lds_dwordx4 v138, s[36:37]
	s_waitcnt vmcnt(8)
	s_waitcnt lgkmcnt(0)
	s_barrier
	s_waitcnt lgkmcnt(0)
	v_mfma_i32_16x16x64_i8 v[126:129], v[148:151], v[204:207], v[126:129]
	v_mfma_i32_16x16x64_i8 v[126:129], v[152:155], v[208:211], v[126:129]
	v_mfma_i32_16x16x64_i8 v[122:125], v[156:159], v[204:207], v[122:125]
	v_mfma_i32_16x16x64_i8 v[122:125], v[160:163], v[208:211], v[122:125]
	v_mfma_i32_16x16x64_i8 v[118:121], v[148:151], v[212:215], v[118:121]
	v_mfma_i32_16x16x64_i8 v[118:121], v[152:155], v[216:219], v[118:121]
	v_mfma_i32_16x16x64_i8 v[114:117], v[156:159], v[212:215], v[114:117]
	v_mfma_i32_16x16x64_i8 v[114:117], v[160:163], v[216:219], v[114:117]
	v_mfma_i32_16x16x64_i8 v[110:113], v[148:151], v[220:223], v[110:113]
	v_mfma_i32_16x16x64_i8 v[110:113], v[152:155], v[224:227], v[110:113]
	v_mfma_i32_16x16x64_i8 v[106:109], v[156:159], v[220:223], v[106:109]
	v_mfma_i32_16x16x64_i8 v[106:109], v[160:163], v[224:227], v[106:109]
	v_mfma_i32_16x16x64_i8 v[102:105], v[148:151], v[228:231], v[102:105]
	v_mfma_i32_16x16x64_i8 v[102:105], v[152:155], v[232:235], v[102:105]
	v_mfma_i32_16x16x64_i8 v[98:101], v[156:159], v[228:231], v[98:101]
	v_mfma_i32_16x16x64_i8 v[98:101], v[160:163], v[232:235], v[98:101]
	v_mfma_i32_16x16x64_i8 v[94:97], v[188:191], v[204:207], v[94:97]
	v_mfma_i32_16x16x64_i8 v[94:97], v[192:195], v[208:211], v[94:97]
	v_mfma_i32_16x16x64_i8 v[90:93], v[196:199], v[204:207], v[90:93]
	v_mfma_i32_16x16x64_i8 v[90:93], v[200:203], v[208:211], v[90:93]
	v_mfma_i32_16x16x64_i8 v[86:89], v[188:191], v[212:215], v[86:89]
	v_mfma_i32_16x16x64_i8 v[86:89], v[192:195], v[216:219], v[86:89]
	v_mfma_i32_16x16x64_i8 v[82:85], v[196:199], v[212:215], v[82:85]
	v_mfma_i32_16x16x64_i8 v[82:85], v[200:203], v[216:219], v[82:85]
	v_mfma_i32_16x16x64_i8 v[78:81], v[188:191], v[220:223], v[78:81]
	v_mfma_i32_16x16x64_i8 v[78:81], v[192:195], v[224:227], v[78:81]
	v_mfma_i32_16x16x64_i8 v[74:77], v[196:199], v[220:223], v[74:77]
	v_mfma_i32_16x16x64_i8 v[74:77], v[200:203], v[224:227], v[74:77]
	v_mfma_i32_16x16x64_i8 v[70:73], v[188:191], v[228:231], v[70:73]
	v_mfma_i32_16x16x64_i8 v[70:73], v[192:195], v[232:235], v[70:73]
	v_mfma_i32_16x16x64_i8 v[66:69], v[196:199], v[228:231], v[66:69]
	v_mfma_i32_16x16x64_i8 v[66:69], v[200:203], v[232:235], v[66:69]
	s_barrier
	s_add_i32 s36, s64, s39
	s_add_u32 s98, s2, s28
	s_addc_u32 s99, s3, s29
	s_mov_b32 m0, s36
	ds_read_b128 v[204:207], v186 offset:49152
	ds_read_b128 v[208:211], v186 offset:50176
	ds_read_b128 v[212:215], v186 offset:51200
	ds_read_b128 v[216:219], v186 offset:52224
	ds_read_b128 v[220:223], v186 offset:53248
	ds_read_b128 v[224:227], v186 offset:54272
	ds_read_b128 v[228:231], v186 offset:55296
	ds_read_b128 v[232:235], v186 offset:56320
	global_load_lds_dwordx4 v136, s[98:99]
	s_add_i32 m0, s36, 0x2000
	s_add_u32 s2, s2, 0x80080
	s_addc_u32 s3, s3, 0
	s_add_i32 s36, s65, s39
	global_load_lds_dwordx4 v140, s[98:99]
	s_mov_b32 m0, s36
	s_nop 0
	global_load_lds_dwordx4 v136, s[2:3]
	s_add_i32 m0, s36, 0x2000
	s_nop 0
	global_load_lds_dwordx4 v140, s[2:3]
	v_lshl_add_u64 v[236:237], v[240:241], 0, s[28:29]
	s_mov_b32 m0, s45
	s_nop 0
	global_load_lds_dwordx4 v[236:237], off
	v_lshl_add_u64 v[236:237], v[242:243], 0, s[28:29]
	s_mov_b32 m0, s52
	s_nop 0
	global_load_lds_dwordx4 v[236:237], off
	s_waitcnt vmcnt(8)
	s_waitcnt lgkmcnt(0)
	s_barrier
	s_waitcnt lgkmcnt(0)
	v_mfma_i32_16x16x64_i8 v[62:65], v[148:151], v[204:207], v[62:65]
	v_mfma_i32_16x16x64_i8 v[62:65], v[152:155], v[208:211], v[62:65]
	v_mfma_i32_16x16x64_i8 v[58:61], v[156:159], v[204:207], v[58:61]
	v_mfma_i32_16x16x64_i8 v[58:61], v[160:163], v[208:211], v[58:61]
	v_mfma_i32_16x16x64_i8 v[54:57], v[148:151], v[212:215], v[54:57]
	v_mfma_i32_16x16x64_i8 v[54:57], v[152:155], v[216:219], v[54:57]
	v_mfma_i32_16x16x64_i8 v[50:53], v[156:159], v[212:215], v[50:53]
	v_mfma_i32_16x16x64_i8 v[50:53], v[160:163], v[216:219], v[50:53]
	v_mfma_i32_16x16x64_i8 v[46:49], v[148:151], v[220:223], v[46:49]
	v_mfma_i32_16x16x64_i8 v[46:49], v[152:155], v[224:227], v[46:49]
	v_mfma_i32_16x16x64_i8 v[42:45], v[156:159], v[220:223], v[42:45]
	v_mfma_i32_16x16x64_i8 v[42:45], v[160:163], v[224:227], v[42:45]
	v_mfma_i32_16x16x64_i8 v[38:41], v[148:151], v[228:231], v[38:41]
	v_mfma_i32_16x16x64_i8 v[38:41], v[152:155], v[232:235], v[38:41]
	v_mfma_i32_16x16x64_i8 v[34:37], v[156:159], v[228:231], v[34:37]
	v_mfma_i32_16x16x64_i8 v[34:37], v[160:163], v[232:235], v[34:37]
	v_mfma_i32_16x16x64_i8 v[30:33], v[188:191], v[204:207], v[30:33]
	v_mfma_i32_16x16x64_i8 v[30:33], v[192:195], v[208:211], v[30:33]
	v_mfma_i32_16x16x64_i8 v[26:29], v[196:199], v[204:207], v[26:29]
	v_mfma_i32_16x16x64_i8 v[26:29], v[200:203], v[208:211], v[26:29]
	v_mfma_i32_16x16x64_i8 v[22:25], v[188:191], v[212:215], v[22:25]
	v_mfma_i32_16x16x64_i8 v[22:25], v[192:195], v[216:219], v[22:25]
	v_mfma_i32_16x16x64_i8 v[18:21], v[196:199], v[212:215], v[18:21]
	v_mfma_i32_16x16x64_i8 v[18:21], v[200:203], v[216:219], v[18:21]
	v_mfma_i32_16x16x64_i8 v[14:17], v[188:191], v[220:223], v[14:17]
	v_mfma_i32_16x16x64_i8 v[14:17], v[192:195], v[224:227], v[14:17]
	v_mfma_i32_16x16x64_i8 v[10:13], v[196:199], v[220:223], v[10:13]
	v_mfma_i32_16x16x64_i8 v[10:13], v[200:203], v[224:227], v[10:13]
	v_mfma_i32_16x16x64_i8 v[6:9], v[188:191], v[228:231], v[6:9]
	v_mfma_i32_16x16x64_i8 v[6:9], v[192:195], v[232:235], v[6:9]
	v_mfma_i32_16x16x64_i8 v[2:5], v[196:199], v[228:231], v[2:5]
	v_mfma_i32_16x16x64_i8 v[2:5], v[200:203], v[232:235], v[2:5]
	s_barrier
	s_add_u32 s34, s34, 0x100
	s_addc_u32 s35, s35, 0
	s_add_u32 s59, s59, 0x100
	s_addc_u32 s60, s60, 0
	s_cmp_ge_i32 s61, s19
	s_mov_b32 s2, s61
	s_cbranch_scc1 .Lkpeel_exit_5
.LBB0_961:
	s_add_i32 s61, s2, 2
	s_add_u32 s3, s34, 0xfff80080
	s_addc_u32 s36, s35, -1
	s_add_i32 s64, 0, 0x10000
	s_cmp_eq_u32 s58, s2
	s_cselect_b32 s37, s24, s36
	s_cselect_b32 s36, s53, s3
	v_add_u32_e32 v142, s64, v131
	s_cselect_b32 s3, s56, s60
	s_cselect_b32 s2, s57, s59
	s_add_i32 s66, 0, 0x14000
	ds_read_b128 v[148:151], v142
	ds_read_b128 v[152:155], v142 offset:1024
	ds_read_b128 v[156:159], v142 offset:2048
	ds_read_b128 v[160:163], v142 offset:3072
	v_add_u32_e32 v142, s66, v131
	ds_read_b128 v[188:191], v142
	ds_read_b128 v[192:195], v142 offset:1024
	ds_read_b128 v[196:199], v142 offset:2048
	ds_read_b128 v[200:203], v142 offset:3072
	s_add_i32 m0, s40, 0xc000
	ds_read_b128 v[204:207], v186
	ds_read_b128 v[208:211], v186 offset:1024
	ds_read_b128 v[212:215], v186 offset:2048
	ds_read_b128 v[216:219], v186 offset:3072
	ds_read_b128 v[220:223], v186 offset:4096
	ds_read_b128 v[224:227], v186 offset:5120
	ds_read_b128 v[228:231], v186 offset:6144
	ds_read_b128 v[232:235], v186 offset:7168
	global_load_lds_dwordx4 v144, s[34:35]
	s_add_i32 m0, s40, 0xe000
	s_nop 0
	global_load_lds_dwordx4 v146, s[34:35]
	s_waitcnt vmcnt(8)
	s_waitcnt lgkmcnt(0)
	s_barrier
	s_waitcnt lgkmcnt(0)
	v_mfma_i32_16x16x64_i8 v[126:129], v[148:151], v[204:207], v[126:129]
	v_mfma_i32_16x16x64_i8 v[126:129], v[152:155], v[208:211], v[126:129]
	v_mfma_i32_16x16x64_i8 v[122:125], v[156:159], v[204:207], v[122:125]
	v_mfma_i32_16x16x64_i8 v[122:125], v[160:163], v[208:211], v[122:125]
	v_mfma_i32_16x16x64_i8 v[118:121], v[148:151], v[212:215], v[118:121]
	v_mfma_i32_16x16x64_i8 v[118:121], v[152:155], v[216:219], v[118:121]
	v_mfma_i32_16x16x64_i8 v[114:117], v[156:159], v[212:215], v[114:117]
	v_mfma_i32_16x16x64_i8 v[114:117], v[160:163], v[216:219], v[114:117]
	v_mfma_i32_16x16x64_i8 v[110:113], v[148:151], v[220:223], v[110:113]
	v_mfma_i32_16x16x64_i8 v[110:113], v[152:155], v[224:227], v[110:113]
	v_mfma_i32_16x16x64_i8 v[106:109], v[156:159], v[220:223], v[106:109]
	v_mfma_i32_16x16x64_i8 v[106:109], v[160:163], v[224:227], v[106:109]
	v_mfma_i32_16x16x64_i8 v[102:105], v[148:151], v[228:231], v[102:105]
	v_mfma_i32_16x16x64_i8 v[102:105], v[152:155], v[232:235], v[102:105]
	v_mfma_i32_16x16x64_i8 v[98:101], v[156:159], v[228:231], v[98:101]
	v_mfma_i32_16x16x64_i8 v[98:101], v[160:163], v[232:235], v[98:101]
	v_mfma_i32_16x16x64_i8 v[94:97], v[188:191], v[204:207], v[94:97]
	v_mfma_i32_16x16x64_i8 v[94:97], v[192:195], v[208:211], v[94:97]
	v_mfma_i32_16x16x64_i8 v[90:93], v[196:199], v[204:207], v[90:93]
	v_mfma_i32_16x16x64_i8 v[90:93], v[200:203], v[208:211], v[90:93]
	v_mfma_i32_16x16x64_i8 v[86:89], v[188:191], v[212:215], v[86:89]
	v_mfma_i32_16x16x64_i8 v[86:89], v[192:195], v[216:219], v[86:89]
	v_mfma_i32_16x16x64_i8 v[82:85], v[196:199], v[212:215], v[82:85]
	v_mfma_i32_16x16x64_i8 v[82:85], v[200:203], v[216:219], v[82:85]
	v_mfma_i32_16x16x64_i8 v[78:81], v[188:191], v[220:223], v[78:81]
	v_mfma_i32_16x16x64_i8 v[78:81], v[192:195], v[224:227], v[78:81]
	v_mfma_i32_16x16x64_i8 v[74:77], v[196:199], v[220:223], v[74:77]
	v_mfma_i32_16x16x64_i8 v[74:77], v[200:203], v[224:227], v[74:77]
	v_mfma_i32_16x16x64_i8 v[70:73], v[188:191], v[228:231], v[70:73]
	v_mfma_i32_16x16x64_i8 v[70:73], v[192:195], v[232:235], v[70:73]
	v_mfma_i32_16x16x64_i8 v[66:69], v[196:199], v[228:231], v[66:69]
	v_mfma_i32_16x16x64_i8 v[66:69], v[200:203], v[232:235], v[66:69]
	s_barrier
	s_add_i32 s64, s64, s39
	s_mov_b32 m0, s64
	ds_read_b128 v[204:207], v186 offset:16384
	ds_read_b128 v[208:211], v186 offset:17408
	ds_read_b128 v[212:215], v186 offset:18432
	ds_read_b128 v[216:219], v186 offset:19456
	ds_read_b128 v[220:223], v186 offset:20480
	ds_read_b128 v[224:227], v186 offset:21504
	ds_read_b128 v[228:231], v186 offset:22528
	ds_read_b128 v[232:235], v186 offset:23552
	global_load_lds_dwordx4 v136, s[2:3]
	s_add_i32 m0, s64, 0x2000
	s_add_u32 s64, s2, 0x80000
	s_addc_u32 s65, s3, 0
	s_add_i32 s66, s66, s39
	global_load_lds_dwordx4 v140, s[2:3]
	s_mov_b32 m0, s66
	v_lshl_add_u64 v[242:243], s[36:37], 0, v[138:139]
	global_load_lds_dwordx4 v136, s[64:65]
	s_add_i32 m0, s66, 0x2000
	s_nop 0
	global_load_lds_dwordx4 v140, s[64:65]
	v_lshl_add_u64 v[240:241], s[36:37], 0, v[134:135]
	s_mov_b32 m0, s40
	s_nop 0
	global_load_lds_dwordx4 v134, s[36:37]
	s_mov_b32 m0, s41
	s_nop 0
	global_load_lds_dwordx4 v138, s[36:37]
	s_waitcnt vmcnt(8)
	s_waitcnt lgkmcnt(0)
	s_barrier
	s_waitcnt lgkmcnt(0)
	v_mfma_i32_16x16x64_i8 v[62:65], v[148:151], v[204:207], v[62:65]
	v_mfma_i32_16x16x64_i8 v[62:65], v[152:155], v[208:211], v[62:65]
	v_mfma_i32_16x16x64_i8 v[58:61], v[156:159], v[204:207], v[58:61]
	v_mfma_i32_16x16x64_i8 v[58:61], v[160:163], v[208:211], v[58:61]
	v_mfma_i32_16x16x64_i8 v[54:57], v[148:151], v[212:215], v[54:57]
	v_mfma_i32_16x16x64_i8 v[54:57], v[152:155], v[216:219], v[54:57]
	v_mfma_i32_16x16x64_i8 v[50:53], v[156:159], v[212:215], v[50:53]
	v_mfma_i32_16x16x64_i8 v[50:53], v[160:163], v[216:219], v[50:53]
	v_mfma_i32_16x16x64_i8 v[46:49], v[148:151], v[220:223], v[46:49]
	v_mfma_i32_16x16x64_i8 v[46:49], v[152:155], v[224:227], v[46:49]
	v_mfma_i32_16x16x64_i8 v[42:45], v[156:159], v[220:223], v[42:45]
	v_mfma_i32_16x16x64_i8 v[42:45], v[160:163], v[224:227], v[42:45]
	v_mfma_i32_16x16x64_i8 v[38:41], v[148:151], v[228:231], v[38:41]
	v_mfma_i32_16x16x64_i8 v[38:41], v[152:155], v[232:235], v[38:41]
	v_mfma_i32_16x16x64_i8 v[34:37], v[156:159], v[228:231], v[34:37]
	v_mfma_i32_16x16x64_i8 v[34:37], v[160:163], v[232:235], v[34:37]
	v_mfma_i32_16x16x64_i8 v[30:33], v[188:191], v[204:207], v[30:33]
	v_mfma_i32_16x16x64_i8 v[30:33], v[192:195], v[208:211], v[30:33]
	v_mfma_i32_16x16x64_i8 v[26:29], v[196:199], v[204:207], v[26:29]
	v_mfma_i32_16x16x64_i8 v[26:29], v[200:203], v[208:211], v[26:29]
	v_mfma_i32_16x16x64_i8 v[22:25], v[188:191], v[212:215], v[22:25]
	v_mfma_i32_16x16x64_i8 v[22:25], v[192:195], v[216:219], v[22:25]
	v_mfma_i32_16x16x64_i8 v[18:21], v[196:199], v[212:215], v[18:21]
	v_mfma_i32_16x16x64_i8 v[18:21], v[200:203], v[216:219], v[18:21]
	v_mfma_i32_16x16x64_i8 v[14:17], v[188:191], v[220:223], v[14:17]
	v_mfma_i32_16x16x64_i8 v[14:17], v[192:195], v[224:227], v[14:17]
	v_mfma_i32_16x16x64_i8 v[10:13], v[196:199], v[220:223], v[10:13]
	v_mfma_i32_16x16x64_i8 v[10:13], v[200:203], v[224:227], v[10:13]
	v_mfma_i32_16x16x64_i8 v[6:9], v[188:191], v[228:231], v[6:9]
	v_mfma_i32_16x16x64_i8 v[6:9], v[192:195], v[232:235], v[6:9]
	v_mfma_i32_16x16x64_i8 v[2:5], v[196:199], v[228:231], v[2:5]
	v_mfma_i32_16x16x64_i8 v[2:5], v[200:203], v[232:235], v[2:5]
	s_barrier
	s_add_i32 s64, 0, 0x18000
	v_add_u32_e32 v142, s64, v131
	s_add_i32 s65, 0, 0x1c000
	ds_read_b128 v[148:151], v142
	ds_read_b128 v[152:155], v142 offset:1024
	ds_read_b128 v[156:159], v142 offset:2048
	ds_read_b128 v[160:163], v142 offset:3072
	v_add_u32_e32 v142, s65, v131
	ds_read_b128 v[188:191], v142
	ds_read_b128 v[192:195], v142 offset:1024
	ds_read_b128 v[196:199], v142 offset:2048
	ds_read_b128 v[200:203], v142 offset:3072
	s_add_u32 s36, s36, 0x80000
	s_addc_u32 s37, s37, 0
	s_mov_b32 m0, s42
	ds_read_b128 v[204:207], v186 offset:32768
	ds_read_b128 v[208:211], v186 offset:33792
	ds_read_b128 v[212:215], v186 offset:34816
	ds_read_b128 v[216:219], v186 offset:35840
	ds_read_b128 v[220:223], v186 offset:36864
	ds_read_b128 v[224:227], v186 offset:37888
	ds_read_b128 v[228:231], v186 offset:38912
	ds_read_b128 v[232:235], v186 offset:39936
	global_load_lds_dwordx4 v134, s[36:37]
	s_mov_b32 m0, s43
	s_nop 0
	global_load_lds_dwordx4 v138, s[36:37]
	s_waitcnt vmcnt(8)
	s_waitcnt lgkmcnt(0)
	s_barrier
	s_waitcnt lgkmcnt(0)
	v_mfma_i32_16x16x64_i8 v[126:129], v[148:151], v[204:207], v[126:129]
	v_mfma_i32_16x16x64_i8 v[126:129], v[152:155], v[208:211], v[126:129]
	v_mfma_i32_16x16x64_i8 v[122:125], v[156:159], v[204:207], v[122:125]
	v_mfma_i32_16x16x64_i8 v[122:125], v[160:163], v[208:211], v[122:125]
	v_mfma_i32_16x16x64_i8 v[118:121], v[148:151], v[212:215], v[118:121]
	v_mfma_i32_16x16x64_i8 v[118:121], v[152:155], v[216:219], v[118:121]
	v_mfma_i32_16x16x64_i8 v[114:117], v[156:159], v[212:215], v[114:117]
	v_mfma_i32_16x16x64_i8 v[114:117], v[160:163], v[216:219], v[114:117]
	v_mfma_i32_16x16x64_i8 v[110:113], v[148:151], v[220:223], v[110:113]
	v_mfma_i32_16x16x64_i8 v[110:113], v[152:155], v[224:227], v[110:113]
	v_mfma_i32_16x16x64_i8 v[106:109], v[156:159], v[220:223], v[106:109]
	v_mfma_i32_16x16x64_i8 v[106:109], v[160:163], v[224:227], v[106:109]
	v_mfma_i32_16x16x64_i8 v[102:105], v[148:151], v[228:231], v[102:105]
	v_mfma_i32_16x16x64_i8 v[102:105], v[152:155], v[232:235], v[102:105]
	v_mfma_i32_16x16x64_i8 v[98:101], v[156:159], v[228:231], v[98:101]
	v_mfma_i32_16x16x64_i8 v[98:101], v[160:163], v[232:235], v[98:101]
	v_mfma_i32_16x16x64_i8 v[94:97], v[188:191], v[204:207], v[94:97]
	v_mfma_i32_16x16x64_i8 v[94:97], v[192:195], v[208:211], v[94:97]
	v_mfma_i32_16x16x64_i8 v[90:93], v[196:199], v[204:207], v[90:93]
	v_mfma_i32_16x16x64_i8 v[90:93], v[200:203], v[208:211], v[90:93]
	v_mfma_i32_16x16x64_i8 v[86:89], v[188:191], v[212:215], v[86:89]
	v_mfma_i32_16x16x64_i8 v[86:89], v[192:195], v[216:219], v[86:89]
	v_mfma_i32_16x16x64_i8 v[82:85], v[196:199], v[212:215], v[82:85]
	v_mfma_i32_16x16x64_i8 v[82:85], v[200:203], v[216:219], v[82:85]
	v_mfma_i32_16x16x64_i8 v[78:81], v[188:191], v[220:223], v[78:81]
	v_mfma_i32_16x16x64_i8 v[78:81], v[192:195], v[224:227], v[78:81]
	v_mfma_i32_16x16x64_i8 v[74:77], v[196:199], v[220:223], v[74:77]
	v_mfma_i32_16x16x64_i8 v[74:77], v[200:203], v[224:227], v[74:77]
	v_mfma_i32_16x16x64_i8 v[70:73], v[188:191], v[228:231], v[70:73]
	v_mfma_i32_16x16x64_i8 v[70:73], v[192:195], v[232:235], v[70:73]
	v_mfma_i32_16x16x64_i8 v[66:69], v[196:199], v[228:231], v[66:69]
	v_mfma_i32_16x16x64_i8 v[66:69], v[200:203], v[232:235], v[66:69]
	s_barrier
	s_add_i32 s36, s64, s39
	s_add_u32 s98, s2, s28
	s_addc_u32 s99, s3, s29
	s_mov_b32 m0, s36
	ds_read_b128 v[204:207], v186 offset:49152
	ds_read_b128 v[208:211], v186 offset:50176
	ds_read_b128 v[212:215], v186 offset:51200
	ds_read_b128 v[216:219], v186 offset:52224
	ds_read_b128 v[220:223], v186 offset:53248
	ds_read_b128 v[224:227], v186 offset:54272
	ds_read_b128 v[228:231], v186 offset:55296
	ds_read_b128 v[232:235], v186 offset:56320
	global_load_lds_dwordx4 v136, s[98:99]
	s_add_i32 m0, s36, 0x2000
	s_add_u32 s2, s2, 0x80080
	s_addc_u32 s3, s3, 0
	s_add_i32 s36, s65, s39
	global_load_lds_dwordx4 v140, s[98:99]
	s_mov_b32 m0, s36
	s_nop 0
	global_load_lds_dwordx4 v136, s[2:3]
	s_add_i32 m0, s36, 0x2000
	s_nop 0
	global_load_lds_dwordx4 v140, s[2:3]
	v_lshl_add_u64 v[236:237], v[240:241], 0, s[28:29]
	s_mov_b32 m0, s45
	s_nop 0
	global_load_lds_dwordx4 v[236:237], off
	v_lshl_add_u64 v[236:237], v[242:243], 0, s[28:29]
	s_mov_b32 m0, s52
	s_nop 0
	global_load_lds_dwordx4 v[236:237], off
	s_waitcnt vmcnt(8)
	s_waitcnt lgkmcnt(0)
	s_barrier
	s_waitcnt lgkmcnt(0)
	v_mfma_i32_16x16x64_i8 v[62:65], v[148:151], v[204:207], v[62:65]
	v_mfma_i32_16x16x64_i8 v[62:65], v[152:155], v[208:211], v[62:65]
	v_mfma_i32_16x16x64_i8 v[58:61], v[156:159], v[204:207], v[58:61]
	v_mfma_i32_16x16x64_i8 v[58:61], v[160:163], v[208:211], v[58:61]
	v_mfma_i32_16x16x64_i8 v[54:57], v[148:151], v[212:215], v[54:57]
	v_mfma_i32_16x16x64_i8 v[54:57], v[152:155], v[216:219], v[54:57]
	v_mfma_i32_16x16x64_i8 v[50:53], v[156:159], v[212:215], v[50:53]
	v_mfma_i32_16x16x64_i8 v[50:53], v[160:163], v[216:219], v[50:53]
	v_mfma_i32_16x16x64_i8 v[46:49], v[148:151], v[220:223], v[46:49]
	v_mfma_i32_16x16x64_i8 v[46:49], v[152:155], v[224:227], v[46:49]
	v_mfma_i32_16x16x64_i8 v[42:45], v[156:159], v[220:223], v[42:45]
	v_mfma_i32_16x16x64_i8 v[42:45], v[160:163], v[224:227], v[42:45]
	v_mfma_i32_16x16x64_i8 v[38:41], v[148:151], v[228:231], v[38:41]
	v_mfma_i32_16x16x64_i8 v[38:41], v[152:155], v[232:235], v[38:41]
	v_mfma_i32_16x16x64_i8 v[34:37], v[156:159], v[228:231], v[34:37]
	v_mfma_i32_16x16x64_i8 v[34:37], v[160:163], v[232:235], v[34:37]
	v_mfma_i32_16x16x64_i8 v[30:33], v[188:191], v[204:207], v[30:33]
	v_mfma_i32_16x16x64_i8 v[30:33], v[192:195], v[208:211], v[30:33]
	v_mfma_i32_16x16x64_i8 v[26:29], v[196:199], v[204:207], v[26:29]
	v_mfma_i32_16x16x64_i8 v[26:29], v[200:203], v[208:211], v[26:29]
	v_mfma_i32_16x16x64_i8 v[22:25], v[188:191], v[212:215], v[22:25]
	v_mfma_i32_16x16x64_i8 v[22:25], v[192:195], v[216:219], v[22:25]
	v_mfma_i32_16x16x64_i8 v[18:21], v[196:199], v[212:215], v[18:21]
	v_mfma_i32_16x16x64_i8 v[18:21], v[200:203], v[216:219], v[18:21]
	v_mfma_i32_16x16x64_i8 v[14:17], v[188:191], v[220:223], v[14:17]
	v_mfma_i32_16x16x64_i8 v[14:17], v[192:195], v[224:227], v[14:17]
	v_mfma_i32_16x16x64_i8 v[10:13], v[196:199], v[220:223], v[10:13]
	v_mfma_i32_16x16x64_i8 v[10:13], v[200:203], v[224:227], v[10:13]
	v_mfma_i32_16x16x64_i8 v[6:9], v[188:191], v[228:231], v[6:9]
	v_mfma_i32_16x16x64_i8 v[6:9], v[192:195], v[232:235], v[6:9]
	v_mfma_i32_16x16x64_i8 v[2:5], v[196:199], v[228:231], v[2:5]
	v_mfma_i32_16x16x64_i8 v[2:5], v[200:203], v[232:235], v[2:5]
	s_barrier
	s_add_u32 s34, s34, 0x100
	s_addc_u32 s35, s35, 0
	s_add_u32 s59, s59, 0x100
	s_addc_u32 s60, s60, 0
	s_cmp_ge_i32 s61, s19
	s_mov_b32 s2, s61
	s_cbranch_scc0 .LBB0_961

.LBB0_1126:
	s_cmp_lt_i32 s29, 1
	s_cbranch_scc1 .LBB0_1148
	s_add_i32 s18, s29, -2
	s_add_u32 s30, s30, 0x2b0080
	s_addc_u32 s31, s31, 0
	s_add_u32 s28, s2, 0x100
	s_addc_u32 s52, s3, 0
	s_mov_b32 s2, 0
	ds_read_b128 v[148:151], v145
	ds_read_b128 v[152:155], v145 offset:1024
	ds_read_b128 v[156:159], v145 offset:2048
	ds_read_b128 v[160:163], v145 offset:3072
	ds_read_b128 v[164:167], v146
	ds_read_b128 v[170:173], v146 offset:1024
	ds_read_b128 v[174:177], v146 offset:2048
	ds_read_b128 v[178:181], v146 offset:3072
	s_add_i32 s53, s2, 2
	s_add_u32 s3, s30, 0xffd50080
	s_addc_u32 s34, s31, -1
	s_cmp_eq_u32 s18, s2
	s_cselect_b32 s2, s26, s28
	s_cselect_b32 s35, s25, s34
	s_cselect_b32 s34, s24, s3
	s_cselect_b32 s3, s27, s52
	s_add_i32 m0, s37, 0xc000
	ds_read_b128 v[182:185], v147
	ds_read_b128 v[186:189], v147 offset:1024
	ds_read_b128 v[190:193], v147 offset:2048
	ds_read_b128 v[194:197], v147 offset:3072
	ds_read_b128 v[198:201], v147 offset:4096
	ds_read_b128 v[202:205], v147 offset:5120
	ds_read_b128 v[206:209], v147 offset:6144
	ds_read_b128 v[210:213], v147 offset:7168
	global_load_lds_dwordx4 v140, s[30:31]
	s_add_i32 m0, s37, 0xe000
	s_nop 0
	global_load_lds_dwordx4 v142, s[30:31]
	s_waitcnt vmcnt(8)
	s_waitcnt lgkmcnt(0)
	s_barrier
	s_waitcnt lgkmcnt(0)
	v_mfma_f32_16x16x32_bf16 v[124:127], v[148:151], v[182:185], 0
	v_mfma_f32_16x16x32_bf16 v[124:127], v[152:155], v[186:189], v[124:127]
	v_mfma_f32_16x16x32_bf16 v[120:123], v[156:159], v[182:185], 0
	v_mfma_f32_16x16x32_bf16 v[120:123], v[160:163], v[186:189], v[120:123]
	v_mfma_f32_16x16x32_bf16 v[108:111], v[148:151], v[190:193], 0
	v_mfma_f32_16x16x32_bf16 v[108:111], v[152:155], v[194:197], v[108:111]
	v_mfma_f32_16x16x32_bf16 v[100:103], v[156:159], v[190:193], 0
	v_mfma_f32_16x16x32_bf16 v[100:103], v[160:163], v[194:197], v[100:103]
	v_mfma_f32_16x16x32_bf16 v[92:95], v[148:151], v[198:201], 0
	v_mfma_f32_16x16x32_bf16 v[92:95], v[152:155], v[202:205], v[92:95]
	v_mfma_f32_16x16x32_bf16 v[84:87], v[156:159], v[198:201], 0
	v_mfma_f32_16x16x32_bf16 v[84:87], v[160:163], v[202:205], v[84:87]
	v_mfma_f32_16x16x32_bf16 v[76:79], v[148:151], v[206:209], 0
	v_mfma_f32_16x16x32_bf16 v[76:79], v[152:155], v[210:213], v[76:79]
	v_mfma_f32_16x16x32_bf16 v[68:71], v[156:159], v[206:209], 0
	v_mfma_f32_16x16x32_bf16 v[68:71], v[160:163], v[210:213], v[68:71]
	v_mfma_f32_16x16x32_bf16 v[116:119], v[164:167], v[182:185], 0
	v_mfma_f32_16x16x32_bf16 v[116:119], v[170:173], v[186:189], v[116:119]
	v_mfma_f32_16x16x32_bf16 v[112:115], v[174:177], v[182:185], 0
	v_mfma_f32_16x16x32_bf16 v[112:115], v[178:181], v[186:189], v[112:115]
	v_mfma_f32_16x16x32_bf16 v[104:107], v[164:167], v[190:193], 0
	v_mfma_f32_16x16x32_bf16 v[104:107], v[170:173], v[194:197], v[104:107]
	v_mfma_f32_16x16x32_bf16 v[96:99], v[174:177], v[190:193], 0
	v_mfma_f32_16x16x32_bf16 v[96:99], v[178:181], v[194:197], v[96:99]
	v_mfma_f32_16x16x32_bf16 v[88:91], v[164:167], v[198:201], 0
	v_mfma_f32_16x16x32_bf16 v[88:91], v[170:173], v[202:205], v[88:91]
	v_mfma_f32_16x16x32_bf16 v[80:83], v[174:177], v[198:201], 0
	v_mfma_f32_16x16x32_bf16 v[80:83], v[178:181], v[202:205], v[80:83]
	v_mfma_f32_16x16x32_bf16 v[72:75], v[164:167], v[206:209], 0
	v_mfma_f32_16x16x32_bf16 v[72:75], v[170:173], v[210:213], v[72:75]
	v_mfma_f32_16x16x32_bf16 v[64:67], v[174:177], v[206:209], 0
	v_mfma_f32_16x16x32_bf16 v[64:67], v[178:181], v[210:213], v[64:67]
	s_barrier
	s_add_i32 s56, s46, s33
	s_mov_b32 m0, s56
	ds_read_b128 v[182:185], v147 offset:16384
	ds_read_b128 v[186:189], v147 offset:17408
	ds_read_b128 v[190:193], v147 offset:18432
	ds_read_b128 v[194:197], v147 offset:19456
	ds_read_b128 v[198:201], v147 offset:20480
	ds_read_b128 v[202:205], v147 offset:21504
	ds_read_b128 v[206:209], v147 offset:22528
	ds_read_b128 v[210:213], v147 offset:23552
	global_load_lds_dwordx4 v134, s[2:3]
	s_add_i32 m0, s56, 0x2000
	s_add_u32 s56, s2, 0x2b0000
	s_addc_u32 s57, s3, 0
	s_add_i32 s58, s47, s33
	global_load_lds_dwordx4 v138, s[2:3]
	s_mov_b32 m0, s58
	v_lshl_add_u64 v[220:221], s[34:35], 0, v[136:137]
	global_load_lds_dwordx4 v134, s[56:57]
	s_add_i32 m0, s58, 0x2000
	s_nop 0
	global_load_lds_dwordx4 v138, s[56:57]
	v_lshl_add_u64 v[218:219], s[34:35], 0, v[128:129]
	s_mov_b32 m0, s37
	s_nop 0
	global_load_lds_dwordx4 v128, s[34:35]
	s_mov_b32 m0, s38
	s_nop 0
	global_load_lds_dwordx4 v136, s[34:35]
	s_waitcnt vmcnt(8)
	s_waitcnt lgkmcnt(0)
	s_barrier
	s_waitcnt lgkmcnt(0)
	v_mfma_f32_16x16x32_bf16 v[60:63], v[148:151], v[182:185], 0
	v_mfma_f32_16x16x32_bf16 v[60:63], v[152:155], v[186:189], v[60:63]
	v_mfma_f32_16x16x32_bf16 v[52:55], v[156:159], v[182:185], 0
	v_mfma_f32_16x16x32_bf16 v[52:55], v[160:163], v[186:189], v[52:55]
	v_mfma_f32_16x16x32_bf16 v[44:47], v[148:151], v[190:193], 0
	v_mfma_f32_16x16x32_bf16 v[44:47], v[152:155], v[194:197], v[44:47]
	v_mfma_f32_16x16x32_bf16 v[36:39], v[156:159], v[190:193], 0
	v_mfma_f32_16x16x32_bf16 v[36:39], v[160:163], v[194:197], v[36:39]
	v_mfma_f32_16x16x32_bf16 v[28:31], v[148:151], v[198:201], 0
	v_mfma_f32_16x16x32_bf16 v[28:31], v[152:155], v[202:205], v[28:31]
	v_mfma_f32_16x16x32_bf16 v[20:23], v[156:159], v[198:201], 0
	v_mfma_f32_16x16x32_bf16 v[20:23], v[160:163], v[202:205], v[20:23]
	v_mfma_f32_16x16x32_bf16 v[12:15], v[148:151], v[206:209], 0
	v_mfma_f32_16x16x32_bf16 v[12:15], v[152:155], v[210:213], v[12:15]
	v_mfma_f32_16x16x32_bf16 v[4:7], v[156:159], v[206:209], 0
	v_mfma_f32_16x16x32_bf16 v[4:7], v[160:163], v[210:213], v[4:7]
	v_mfma_f32_16x16x32_bf16 v[56:59], v[164:167], v[182:185], 0
	v_mfma_f32_16x16x32_bf16 v[56:59], v[170:173], v[186:189], v[56:59]
	v_mfma_f32_16x16x32_bf16 v[48:51], v[174:177], v[182:185], 0
	v_mfma_f32_16x16x32_bf16 v[48:51], v[178:181], v[186:189], v[48:51]
	v_mfma_f32_16x16x32_bf16 v[40:43], v[164:167], v[190:193], 0
	v_mfma_f32_16x16x32_bf16 v[40:43], v[170:173], v[194:197], v[40:43]
	v_mfma_f32_16x16x32_bf16 v[32:35], v[174:177], v[190:193], 0
	v_mfma_f32_16x16x32_bf16 v[32:35], v[178:181], v[194:197], v[32:35]
	v_mfma_f32_16x16x32_bf16 v[24:27], v[164:167], v[198:201], 0
	v_mfma_f32_16x16x32_bf16 v[24:27], v[170:173], v[202:205], v[24:27]
	v_mfma_f32_16x16x32_bf16 v[16:19], v[174:177], v[198:201], 0
	v_mfma_f32_16x16x32_bf16 v[16:19], v[178:181], v[202:205], v[16:19]
	v_mfma_f32_16x16x32_bf16 v[8:11], v[164:167], v[206:209], 0
	v_mfma_f32_16x16x32_bf16 v[8:11], v[170:173], v[210:213], v[8:11]
	v_mfma_f32_16x16x32_bf16 v[0:3], v[174:177], v[206:209], 0
	v_mfma_f32_16x16x32_bf16 v[0:3], v[178:181], v[210:213], v[0:3]
	s_barrier
	s_add_i32 s56, 0, 0x18000
	s_add_i32 s57, 0, 0x1c000
	v_add_u32_e32 v160, s56, v133
	v_add_u32_e32 v168, s57, v133
	ds_read_b128 v[148:151], v160
	ds_read_b128 v[152:155], v160 offset:1024
	ds_read_b128 v[156:159], v160 offset:2048
	ds_read_b128 v[160:163], v160 offset:3072
	ds_read_b128 v[164:167], v168
	ds_read_b128 v[170:173], v168 offset:1024
	ds_read_b128 v[174:177], v168 offset:2048
	ds_read_b128 v[178:181], v168 offset:3072
	s_add_u32 s34, s34, 0x2b0000
	s_addc_u32 s35, s35, 0
	s_mov_b32 m0, s39
	ds_read_b128 v[182:185], v147 offset:32768
	ds_read_b128 v[186:189], v147 offset:33792
	ds_read_b128 v[190:193], v147 offset:34816
	ds_read_b128 v[194:197], v147 offset:35840
	ds_read_b128 v[198:201], v147 offset:36864
	ds_read_b128 v[202:205], v147 offset:37888
	ds_read_b128 v[206:209], v147 offset:38912
	ds_read_b128 v[210:213], v147 offset:39936
	global_load_lds_dwordx4 v128, s[34:35]
	s_mov_b32 m0, s40
	s_nop 0
	global_load_lds_dwordx4 v136, s[34:35]
	s_waitcnt vmcnt(8)
	s_waitcnt lgkmcnt(0)
	s_barrier
	s_waitcnt lgkmcnt(0)
	v_mfma_f32_16x16x32_bf16 v[124:127], v[148:151], v[182:185], v[124:127]
	v_mfma_f32_16x16x32_bf16 v[124:127], v[152:155], v[186:189], v[124:127]
	v_mfma_f32_16x16x32_bf16 v[120:123], v[156:159], v[182:185], v[120:123]
	v_mfma_f32_16x16x32_bf16 v[120:123], v[160:163], v[186:189], v[120:123]
	v_mfma_f32_16x16x32_bf16 v[108:111], v[148:151], v[190:193], v[108:111]
	v_mfma_f32_16x16x32_bf16 v[108:111], v[152:155], v[194:197], v[108:111]
	v_mfma_f32_16x16x32_bf16 v[100:103], v[156:159], v[190:193], v[100:103]
	v_mfma_f32_16x16x32_bf16 v[100:103], v[160:163], v[194:197], v[100:103]
	v_mfma_f32_16x16x32_bf16 v[92:95], v[148:151], v[198:201], v[92:95]
	v_mfma_f32_16x16x32_bf16 v[92:95], v[152:155], v[202:205], v[92:95]
	v_mfma_f32_16x16x32_bf16 v[84:87], v[156:159], v[198:201], v[84:87]
	v_mfma_f32_16x16x32_bf16 v[84:87], v[160:163], v[202:205], v[84:87]
	v_mfma_f32_16x16x32_bf16 v[76:79], v[148:151], v[206:209], v[76:79]
	v_mfma_f32_16x16x32_bf16 v[76:79], v[152:155], v[210:213], v[76:79]
	v_mfma_f32_16x16x32_bf16 v[68:71], v[156:159], v[206:209], v[68:71]
	v_mfma_f32_16x16x32_bf16 v[68:71], v[160:163], v[210:213], v[68:71]
	v_mfma_f32_16x16x32_bf16 v[116:119], v[164:167], v[182:185], v[116:119]
	v_mfma_f32_16x16x32_bf16 v[116:119], v[170:173], v[186:189], v[116:119]
	v_mfma_f32_16x16x32_bf16 v[112:115], v[174:177], v[182:185], v[112:115]
	v_mfma_f32_16x16x32_bf16 v[112:115], v[178:181], v[186:189], v[112:115]
	v_mfma_f32_16x16x32_bf16 v[104:107], v[164:167], v[190:193], v[104:107]
	v_mfma_f32_16x16x32_bf16 v[104:107], v[170:173], v[194:197], v[104:107]
	v_mfma_f32_16x16x32_bf16 v[96:99], v[174:177], v[190:193], v[96:99]
	v_mfma_f32_16x16x32_bf16 v[96:99], v[178:181], v[194:197], v[96:99]
	v_mfma_f32_16x16x32_bf16 v[88:91], v[164:167], v[198:201], v[88:91]
	v_mfma_f32_16x16x32_bf16 v[88:91], v[170:173], v[202:205], v[88:91]
	v_mfma_f32_16x16x32_bf16 v[80:83], v[174:177], v[198:201], v[80:83]
	v_mfma_f32_16x16x32_bf16 v[80:83], v[178:181], v[202:205], v[80:83]
	v_mfma_f32_16x16x32_bf16 v[72:75], v[164:167], v[206:209], v[72:75]
	v_mfma_f32_16x16x32_bf16 v[72:75], v[170:173], v[210:213], v[72:75]
	v_mfma_f32_16x16x32_bf16 v[64:67], v[174:177], v[206:209], v[64:67]
	v_mfma_f32_16x16x32_bf16 v[64:67], v[178:181], v[210:213], v[64:67]
	s_barrier
	s_add_i32 s34, s56, s33
	s_add_u32 s98, s2, s6
	s_addc_u32 s99, s3, s7
	s_mov_b32 m0, s34
	ds_read_b128 v[182:185], v147 offset:49152
	ds_read_b128 v[186:189], v147 offset:50176
	ds_read_b128 v[190:193], v147 offset:51200
	ds_read_b128 v[194:197], v147 offset:52224
	ds_read_b128 v[198:201], v147 offset:53248
	ds_read_b128 v[202:205], v147 offset:54272
	ds_read_b128 v[206:209], v147 offset:55296
	ds_read_b128 v[210:213], v147 offset:56320
	global_load_lds_dwordx4 v134, s[98:99]
	s_add_i32 m0, s34, 0x2000
	s_add_u32 s2, s2, 0x2b0080
	s_addc_u32 s3, s3, 0
	s_add_i32 s34, s57, s33
	global_load_lds_dwordx4 v138, s[98:99]
	s_mov_b32 m0, s34
	s_nop 0
	global_load_lds_dwordx4 v134, s[2:3]
	s_add_i32 m0, s34, 0x2000
	s_nop 0
	global_load_lds_dwordx4 v138, s[2:3]
	v_lshl_add_u64 v[214:215], v[218:219], 0, s[6:7]
	s_mov_b32 m0, s42
	s_nop 0
	global_load_lds_dwordx4 v[214:215], off
	v_lshl_add_u64 v[214:215], v[220:221], 0, s[6:7]
	s_mov_b32 m0, s43
	s_nop 0
	global_load_lds_dwordx4 v[214:215], off
	s_waitcnt vmcnt(8)
	s_waitcnt lgkmcnt(0)
	s_barrier
	s_waitcnt lgkmcnt(0)
	v_mfma_f32_16x16x32_bf16 v[60:63], v[148:151], v[182:185], v[60:63]
	v_mfma_f32_16x16x32_bf16 v[60:63], v[152:155], v[186:189], v[60:63]
	v_mfma_f32_16x16x32_bf16 v[52:55], v[156:159], v[182:185], v[52:55]
	v_mfma_f32_16x16x32_bf16 v[52:55], v[160:163], v[186:189], v[52:55]
	v_mfma_f32_16x16x32_bf16 v[44:47], v[148:151], v[190:193], v[44:47]
	v_mfma_f32_16x16x32_bf16 v[44:47], v[152:155], v[194:197], v[44:47]
	v_mfma_f32_16x16x32_bf16 v[36:39], v[156:159], v[190:193], v[36:39]
	v_mfma_f32_16x16x32_bf16 v[36:39], v[160:163], v[194:197], v[36:39]
	v_mfma_f32_16x16x32_bf16 v[28:31], v[148:151], v[198:201], v[28:31]
	v_mfma_f32_16x16x32_bf16 v[28:31], v[152:155], v[202:205], v[28:31]
	v_mfma_f32_16x16x32_bf16 v[20:23], v[156:159], v[198:201], v[20:23]
	v_mfma_f32_16x16x32_bf16 v[20:23], v[160:163], v[202:205], v[20:23]
	v_mfma_f32_16x16x32_bf16 v[12:15], v[148:151], v[206:209], v[12:15]
	v_mfma_f32_16x16x32_bf16 v[12:15], v[152:155], v[210:213], v[12:15]
	v_mfma_f32_16x16x32_bf16 v[4:7], v[156:159], v[206:209], v[4:7]
	v_mfma_f32_16x16x32_bf16 v[4:7], v[160:163], v[210:213], v[4:7]
	v_mfma_f32_16x16x32_bf16 v[56:59], v[164:167], v[182:185], v[56:59]
	v_mfma_f32_16x16x32_bf16 v[56:59], v[170:173], v[186:189], v[56:59]
	v_mfma_f32_16x16x32_bf16 v[48:51], v[174:177], v[182:185], v[48:51]
	v_mfma_f32_16x16x32_bf16 v[48:51], v[178:181], v[186:189], v[48:51]
	v_mfma_f32_16x16x32_bf16 v[40:43], v[164:167], v[190:193], v[40:43]
	v_mfma_f32_16x16x32_bf16 v[40:43], v[170:173], v[194:197], v[40:43]
	v_mfma_f32_16x16x32_bf16 v[32:35], v[174:177], v[190:193], v[32:35]
	v_mfma_f32_16x16x32_bf16 v[32:35], v[178:181], v[194:197], v[32:35]
	v_mfma_f32_16x16x32_bf16 v[24:27], v[164:167], v[198:201], v[24:27]
	v_mfma_f32_16x16x32_bf16 v[24:27], v[170:173], v[202:205], v[24:27]
	v_mfma_f32_16x16x32_bf16 v[16:19], v[174:177], v[198:201], v[16:19]
	v_mfma_f32_16x16x32_bf16 v[16:19], v[178:181], v[202:205], v[16:19]
	v_mfma_f32_16x16x32_bf16 v[8:11], v[164:167], v[206:209], v[8:11]
	v_mfma_f32_16x16x32_bf16 v[8:11], v[170:173], v[210:213], v[8:11]
	v_mfma_f32_16x16x32_bf16 v[0:3], v[174:177], v[206:209], v[0:3]
	v_mfma_f32_16x16x32_bf16 v[0:3], v[178:181], v[210:213], v[0:3]
	s_barrier
	s_add_u32 s30, s30, 0x100
	s_addc_u32 s31, s31, 0
	s_add_u32 s28, s28, 0x100
	s_addc_u32 s52, s52, 0
	s_cmp_ge_i32 s53, s29
	s_mov_b32 s2, s53
	s_cbranch_scc1 .Lkpeel_exit_6
.LBB0_1128:
	ds_read_b128 v[148:151], v145
	ds_read_b128 v[152:155], v145 offset:1024
	ds_read_b128 v[156:159], v145 offset:2048
	ds_read_b128 v[160:163], v145 offset:3072
	ds_read_b128 v[164:167], v146
	ds_read_b128 v[170:173], v146 offset:1024
	ds_read_b128 v[174:177], v146 offset:2048
	ds_read_b128 v[178:181], v146 offset:3072
	s_add_i32 s53, s2, 2
	s_add_u32 s3, s30, 0xffd50080
	s_addc_u32 s34, s31, -1
	s_cmp_eq_u32 s18, s2
	s_cselect_b32 s2, s26, s28
	s_cselect_b32 s35, s25, s34
	s_cselect_b32 s34, s24, s3
	s_cselect_b32 s3, s27, s52
	s_add_i32 m0, s37, 0xc000
	ds_read_b128 v[182:185], v147
	ds_read_b128 v[186:189], v147 offset:1024
	ds_read_b128 v[190:193], v147 offset:2048
	ds_read_b128 v[194:197], v147 offset:3072
	ds_read_b128 v[198:201], v147 offset:4096
	ds_read_b128 v[202:205], v147 offset:5120
	ds_read_b128 v[206:209], v147 offset:6144
	ds_read_b128 v[210:213], v147 offset:7168
	global_load_lds_dwordx4 v140, s[30:31]
	s_add_i32 m0, s37, 0xe000
	s_nop 0
	global_load_lds_dwordx4 v142, s[30:31]
	s_waitcnt vmcnt(8)
	s_waitcnt lgkmcnt(0)
	s_barrier
	s_waitcnt lgkmcnt(0)
	v_mfma_f32_16x16x32_bf16 v[124:127], v[148:151], v[182:185], v[124:127]
	v_mfma_f32_16x16x32_bf16 v[124:127], v[152:155], v[186:189], v[124:127]
	v_mfma_f32_16x16x32_bf16 v[120:123], v[156:159], v[182:185], v[120:123]
	v_mfma_f32_16x16x32_bf16 v[120:123], v[160:163], v[186:189], v[120:123]
	v_mfma_f32_16x16x32_bf16 v[108:111], v[148:151], v[190:193], v[108:111]
	v_mfma_f32_16x16x32_bf16 v[108:111], v[152:155], v[194:197], v[108:111]
	v_mfma_f32_16x16x32_bf16 v[100:103], v[156:159], v[190:193], v[100:103]
	v_mfma_f32_16x16x32_bf16 v[100:103], v[160:163], v[194:197], v[100:103]
	v_mfma_f32_16x16x32_bf16 v[92:95], v[148:151], v[198:201], v[92:95]
	v_mfma_f32_16x16x32_bf16 v[92:95], v[152:155], v[202:205], v[92:95]
	v_mfma_f32_16x16x32_bf16 v[84:87], v[156:159], v[198:201], v[84:87]
	v_mfma_f32_16x16x32_bf16 v[84:87], v[160:163], v[202:205], v[84:87]
	v_mfma_f32_16x16x32_bf16 v[76:79], v[148:151], v[206:209], v[76:79]
	v_mfma_f32_16x16x32_bf16 v[76:79], v[152:155], v[210:213], v[76:79]
	v_mfma_f32_16x16x32_bf16 v[68:71], v[156:159], v[206:209], v[68:71]
	v_mfma_f32_16x16x32_bf16 v[68:71], v[160:163], v[210:213], v[68:71]
	v_mfma_f32_16x16x32_bf16 v[116:119], v[164:167], v[182:185], v[116:119]
	v_mfma_f32_16x16x32_bf16 v[116:119], v[170:173], v[186:189], v[116:119]
	v_mfma_f32_16x16x32_bf16 v[112:115], v[174:177], v[182:185], v[112:115]
	v_mfma_f32_16x16x32_bf16 v[112:115], v[178:181], v[186:189], v[112:115]
	v_mfma_f32_16x16x32_bf16 v[104:107], v[164:167], v[190:193], v[104:107]
	v_mfma_f32_16x16x32_bf16 v[104:107], v[170:173], v[194:197], v[104:107]
	v_mfma_f32_16x16x32_bf16 v[96:99], v[174:177], v[190:193], v[96:99]
	v_mfma_f32_16x16x32_bf16 v[96:99], v[178:181], v[194:197], v[96:99]
	v_mfma_f32_16x16x32_bf16 v[88:91], v[164:167], v[198:201], v[88:91]
	v_mfma_f32_16x16x32_bf16 v[88:91], v[170:173], v[202:205], v[88:91]
	v_mfma_f32_16x16x32_bf16 v[80:83], v[174:177], v[198:201], v[80:83]
	v_mfma_f32_16x16x32_bf16 v[80:83], v[178:181], v[202:205], v[80:83]
	v_mfma_f32_16x16x32_bf16 v[72:75], v[164:167], v[206:209], v[72:75]
	v_mfma_f32_16x16x32_bf16 v[72:75], v[170:173], v[210:213], v[72:75]
	v_mfma_f32_16x16x32_bf16 v[64:67], v[174:177], v[206:209], v[64:67]
	v_mfma_f32_16x16x32_bf16 v[64:67], v[178:181], v[210:213], v[64:67]
	s_barrier
	s_add_i32 s56, s46, s33
	s_mov_b32 m0, s56
	ds_read_b128 v[182:185], v147 offset:16384
	ds_read_b128 v[186:189], v147 offset:17408
	ds_read_b128 v[190:193], v147 offset:18432
	ds_read_b128 v[194:197], v147 offset:19456
	ds_read_b128 v[198:201], v147 offset:20480
	ds_read_b128 v[202:205], v147 offset:21504
	ds_read_b128 v[206:209], v147 offset:22528
	ds_read_b128 v[210:213], v147 offset:23552
	global_load_lds_dwordx4 v134, s[2:3]
	s_add_i32 m0, s56, 0x2000
	s_add_u32 s56, s2, 0x2b0000
	s_addc_u32 s57, s3, 0
	s_add_i32 s58, s47, s33
	global_load_lds_dwordx4 v138, s[2:3]
	s_mov_b32 m0, s58
	v_lshl_add_u64 v[220:221], s[34:35], 0, v[136:137]
	global_load_lds_dwordx4 v134, s[56:57]
	s_add_i32 m0, s58, 0x2000
	s_nop 0
	global_load_lds_dwordx4 v138, s[56:57]
	v_lshl_add_u64 v[218:219], s[34:35], 0, v[128:129]
	s_mov_b32 m0, s37
	s_nop 0
	global_load_lds_dwordx4 v128, s[34:35]
	s_mov_b32 m0, s38
	s_nop 0
	global_load_lds_dwordx4 v136, s[34:35]
	s_waitcnt vmcnt(8)
	s_waitcnt lgkmcnt(0)
	s_barrier
	s_waitcnt lgkmcnt(0)
	v_mfma_f32_16x16x32_bf16 v[60:63], v[148:151], v[182:185], v[60:63]
	v_mfma_f32_16x16x32_bf16 v[60:63], v[152:155], v[186:189], v[60:63]
	v_mfma_f32_16x16x32_bf16 v[52:55], v[156:159], v[182:185], v[52:55]
	v_mfma_f32_16x16x32_bf16 v[52:55], v[160:163], v[186:189], v[52:55]
	v_mfma_f32_16x16x32_bf16 v[44:47], v[148:151], v[190:193], v[44:47]
	v_mfma_f32_16x16x32_bf16 v[44:47], v[152:155], v[194:197], v[44:47]
	v_mfma_f32_16x16x32_bf16 v[36:39], v[156:159], v[190:193], v[36:39]
	v_mfma_f32_16x16x32_bf16 v[36:39], v[160:163], v[194:197], v[36:39]
	v_mfma_f32_16x16x32_bf16 v[28:31], v[148:151], v[198:201], v[28:31]
	v_mfma_f32_16x16x32_bf16 v[28:31], v[152:155], v[202:205], v[28:31]
	v_mfma_f32_16x16x32_bf16 v[20:23], v[156:159], v[198:201], v[20:23]
	v_mfma_f32_16x16x32_bf16 v[20:23], v[160:163], v[202:205], v[20:23]
	v_mfma_f32_16x16x32_bf16 v[12:15], v[148:151], v[206:209], v[12:15]
	v_mfma_f32_16x16x32_bf16 v[12:15], v[152:155], v[210:213], v[12:15]
	v_mfma_f32_16x16x32_bf16 v[4:7], v[156:159], v[206:209], v[4:7]
	v_mfma_f32_16x16x32_bf16 v[4:7], v[160:163], v[210:213], v[4:7]
	v_mfma_f32_16x16x32_bf16 v[56:59], v[164:167], v[182:185], v[56:59]
	v_mfma_f32_16x16x32_bf16 v[56:59], v[170:173], v[186:189], v[56:59]
	v_mfma_f32_16x16x32_bf16 v[48:51], v[174:177], v[182:185], v[48:51]
	v_mfma_f32_16x16x32_bf16 v[48:51], v[178:181], v[186:189], v[48:51]
	v_mfma_f32_16x16x32_bf16 v[40:43], v[164:167], v[190:193], v[40:43]
	v_mfma_f32_16x16x32_bf16 v[40:43], v[170:173], v[194:197], v[40:43]
	v_mfma_f32_16x16x32_bf16 v[32:35], v[174:177], v[190:193], v[32:35]
	v_mfma_f32_16x16x32_bf16 v[32:35], v[178:181], v[194:197], v[32:35]
	v_mfma_f32_16x16x32_bf16 v[24:27], v[164:167], v[198:201], v[24:27]
	v_mfma_f32_16x16x32_bf16 v[24:27], v[170:173], v[202:205], v[24:27]
	v_mfma_f32_16x16x32_bf16 v[16:19], v[174:177], v[198:201], v[16:19]
	v_mfma_f32_16x16x32_bf16 v[16:19], v[178:181], v[202:205], v[16:19]
	v_mfma_f32_16x16x32_bf16 v[8:11], v[164:167], v[206:209], v[8:11]
	v_mfma_f32_16x16x32_bf16 v[8:11], v[170:173], v[210:213], v[8:11]
	v_mfma_f32_16x16x32_bf16 v[0:3], v[174:177], v[206:209], v[0:3]
	v_mfma_f32_16x16x32_bf16 v[0:3], v[178:181], v[210:213], v[0:3]
	s_barrier
	s_add_i32 s56, 0, 0x18000
	s_add_i32 s57, 0, 0x1c000
	v_add_u32_e32 v160, s56, v133
	v_add_u32_e32 v168, s57, v133
	ds_read_b128 v[148:151], v160
	ds_read_b128 v[152:155], v160 offset:1024
	ds_read_b128 v[156:159], v160 offset:2048
	ds_read_b128 v[160:163], v160 offset:3072
	ds_read_b128 v[164:167], v168
	ds_read_b128 v[170:173], v168 offset:1024
	ds_read_b128 v[174:177], v168 offset:2048
	ds_read_b128 v[178:181], v168 offset:3072
	s_add_u32 s34, s34, 0x2b0000
	s_addc_u32 s35, s35, 0
	s_mov_b32 m0, s39
	ds_read_b128 v[182:185], v147 offset:32768
	ds_read_b128 v[186:189], v147 offset:33792
	ds_read_b128 v[190:193], v147 offset:34816
	ds_read_b128 v[194:197], v147 offset:35840
	ds_read_b128 v[198:201], v147 offset:36864
	ds_read_b128 v[202:205], v147 offset:37888
	ds_read_b128 v[206:209], v147 offset:38912
	ds_read_b128 v[210:213], v147 offset:39936
	global_load_lds_dwordx4 v128, s[34:35]
	s_mov_b32 m0, s40
	s_nop 0
	global_load_lds_dwordx4 v136, s[34:35]
	s_waitcnt vmcnt(8)
	s_waitcnt lgkmcnt(0)
	s_barrier
	s_waitcnt lgkmcnt(0)
	v_mfma_f32_16x16x32_bf16 v[124:127], v[148:151], v[182:185], v[124:127]
	v_mfma_f32_16x16x32_bf16 v[124:127], v[152:155], v[186:189], v[124:127]
	v_mfma_f32_16x16x32_bf16 v[120:123], v[156:159], v[182:185], v[120:123]
	v_mfma_f32_16x16x32_bf16 v[120:123], v[160:163], v[186:189], v[120:123]
	v_mfma_f32_16x16x32_bf16 v[108:111], v[148:151], v[190:193], v[108:111]
	v_mfma_f32_16x16x32_bf16 v[108:111], v[152:155], v[194:197], v[108:111]
	v_mfma_f32_16x16x32_bf16 v[100:103], v[156:159], v[190:193], v[100:103]
	v_mfma_f32_16x16x32_bf16 v[100:103], v[160:163], v[194:197], v[100:103]
	v_mfma_f32_16x16x32_bf16 v[92:95], v[148:151], v[198:201], v[92:95]
	v_mfma_f32_16x16x32_bf16 v[92:95], v[152:155], v[202:205], v[92:95]
	v_mfma_f32_16x16x32_bf16 v[84:87], v[156:159], v[198:201], v[84:87]
	v_mfma_f32_16x16x32_bf16 v[84:87], v[160:163], v[202:205], v[84:87]
	v_mfma_f32_16x16x32_bf16 v[76:79], v[148:151], v[206:209], v[76:79]
	v_mfma_f32_16x16x32_bf16 v[76:79], v[152:155], v[210:213], v[76:79]
	v_mfma_f32_16x16x32_bf16 v[68:71], v[156:159], v[206:209], v[68:71]
	v_mfma_f32_16x16x32_bf16 v[68:71], v[160:163], v[210:213], v[68:71]
	v_mfma_f32_16x16x32_bf16 v[116:119], v[164:167], v[182:185], v[116:119]
	v_mfma_f32_16x16x32_bf16 v[116:119], v[170:173], v[186:189], v[116:119]
	v_mfma_f32_16x16x32_bf16 v[112:115], v[174:177], v[182:185], v[112:115]
	v_mfma_f32_16x16x32_bf16 v[112:115], v[178:181], v[186:189], v[112:115]
	v_mfma_f32_16x16x32_bf16 v[104:107], v[164:167], v[190:193], v[104:107]
	v_mfma_f32_16x16x32_bf16 v[104:107], v[170:173], v[194:197], v[104:107]
	v_mfma_f32_16x16x32_bf16 v[96:99], v[174:177], v[190:193], v[96:99]
	v_mfma_f32_16x16x32_bf16 v[96:99], v[178:181], v[194:197], v[96:99]
	v_mfma_f32_16x16x32_bf16 v[88:91], v[164:167], v[198:201], v[88:91]
	v_mfma_f32_16x16x32_bf16 v[88:91], v[170:173], v[202:205], v[88:91]
	v_mfma_f32_16x16x32_bf16 v[80:83], v[174:177], v[198:201], v[80:83]
	v_mfma_f32_16x16x32_bf16 v[80:83], v[178:181], v[202:205], v[80:83]
	v_mfma_f32_16x16x32_bf16 v[72:75], v[164:167], v[206:209], v[72:75]
	v_mfma_f32_16x16x32_bf16 v[72:75], v[170:173], v[210:213], v[72:75]
	v_mfma_f32_16x16x32_bf16 v[64:67], v[174:177], v[206:209], v[64:67]
	v_mfma_f32_16x16x32_bf16 v[64:67], v[178:181], v[210:213], v[64:67]
	s_barrier
	s_add_i32 s34, s56, s33
	s_add_u32 s98, s2, s6
	s_addc_u32 s99, s3, s7
	s_mov_b32 m0, s34
	ds_read_b128 v[182:185], v147 offset:49152
	ds_read_b128 v[186:189], v147 offset:50176
	ds_read_b128 v[190:193], v147 offset:51200
	ds_read_b128 v[194:197], v147 offset:52224
	ds_read_b128 v[198:201], v147 offset:53248
	ds_read_b128 v[202:205], v147 offset:54272
	ds_read_b128 v[206:209], v147 offset:55296
	ds_read_b128 v[210:213], v147 offset:56320
	global_load_lds_dwordx4 v134, s[98:99]
	s_add_i32 m0, s34, 0x2000
	s_add_u32 s2, s2, 0x2b0080
	s_addc_u32 s3, s3, 0
	s_add_i32 s34, s57, s33
	global_load_lds_dwordx4 v138, s[98:99]
	s_mov_b32 m0, s34
	s_nop 0
	global_load_lds_dwordx4 v134, s[2:3]
	s_add_i32 m0, s34, 0x2000
	s_nop 0
	global_load_lds_dwordx4 v138, s[2:3]
	v_lshl_add_u64 v[214:215], v[218:219], 0, s[6:7]
	s_mov_b32 m0, s42
	s_nop 0
	global_load_lds_dwordx4 v[214:215], off
	v_lshl_add_u64 v[214:215], v[220:221], 0, s[6:7]
	s_mov_b32 m0, s43
	s_nop 0
	global_load_lds_dwordx4 v[214:215], off
	s_waitcnt vmcnt(8)
	s_waitcnt lgkmcnt(0)
	s_barrier
	s_waitcnt lgkmcnt(0)
	v_mfma_f32_16x16x32_bf16 v[60:63], v[148:151], v[182:185], v[60:63]
	v_mfma_f32_16x16x32_bf16 v[60:63], v[152:155], v[186:189], v[60:63]
	v_mfma_f32_16x16x32_bf16 v[52:55], v[156:159], v[182:185], v[52:55]
	v_mfma_f32_16x16x32_bf16 v[52:55], v[160:163], v[186:189], v[52:55]
	v_mfma_f32_16x16x32_bf16 v[44:47], v[148:151], v[190:193], v[44:47]
	v_mfma_f32_16x16x32_bf16 v[44:47], v[152:155], v[194:197], v[44:47]
	v_mfma_f32_16x16x32_bf16 v[36:39], v[156:159], v[190:193], v[36:39]
	v_mfma_f32_16x16x32_bf16 v[36:39], v[160:163], v[194:197], v[36:39]
	v_mfma_f32_16x16x32_bf16 v[28:31], v[148:151], v[198:201], v[28:31]
	v_mfma_f32_16x16x32_bf16 v[28:31], v[152:155], v[202:205], v[28:31]
	v_mfma_f32_16x16x32_bf16 v[20:23], v[156:159], v[198:201], v[20:23]
	v_mfma_f32_16x16x32_bf16 v[20:23], v[160:163], v[202:205], v[20:23]
	v_mfma_f32_16x16x32_bf16 v[12:15], v[148:151], v[206:209], v[12:15]
	v_mfma_f32_16x16x32_bf16 v[12:15], v[152:155], v[210:213], v[12:15]
	v_mfma_f32_16x16x32_bf16 v[4:7], v[156:159], v[206:209], v[4:7]
	v_mfma_f32_16x16x32_bf16 v[4:7], v[160:163], v[210:213], v[4:7]
	v_mfma_f32_16x16x32_bf16 v[56:59], v[164:167], v[182:185], v[56:59]
	v_mfma_f32_16x16x32_bf16 v[56:59], v[170:173], v[186:189], v[56:59]
	v_mfma_f32_16x16x32_bf16 v[48:51], v[174:177], v[182:185], v[48:51]
	v_mfma_f32_16x16x32_bf16 v[48:51], v[178:181], v[186:189], v[48:51]
	v_mfma_f32_16x16x32_bf16 v[40:43], v[164:167], v[190:193], v[40:43]
	v_mfma_f32_16x16x32_bf16 v[40:43], v[170:173], v[194:197], v[40:43]
	v_mfma_f32_16x16x32_bf16 v[32:35], v[174:177], v[190:193], v[32:35]
	v_mfma_f32_16x16x32_bf16 v[32:35], v[178:181], v[194:197], v[32:35]
	v_mfma_f32_16x16x32_bf16 v[24:27], v[164:167], v[198:201], v[24:27]
	v_mfma_f32_16x16x32_bf16 v[24:27], v[170:173], v[202:205], v[24:27]
	v_mfma_f32_16x16x32_bf16 v[16:19], v[174:177], v[198:201], v[16:19]
	v_mfma_f32_16x16x32_bf16 v[16:19], v[178:181], v[202:205], v[16:19]
	v_mfma_f32_16x16x32_bf16 v[8:11], v[164:167], v[206:209], v[8:11]
	v_mfma_f32_16x16x32_bf16 v[8:11], v[170:173], v[210:213], v[8:11]
	v_mfma_f32_16x16x32_bf16 v[0:3], v[174:177], v[206:209], v[0:3]
	v_mfma_f32_16x16x32_bf16 v[0:3], v[178:181], v[210:213], v[0:3]
	s_barrier
	s_add_u32 s30, s30, 0x100
	s_addc_u32 s31, s31, 0
	s_add_u32 s28, s28, 0x100
	s_addc_u32 s52, s52, 0
	s_cmp_ge_i32 s53, s29
	s_mov_b32 s2, s53
	s_cbranch_scc0 .LBB0_1128
